# snake MFMA order; inverted flips: load phase at prio 1, MFMA block at prio 0
# baseline (speedup 1.0000x reference)
.LBB0_142:
	ds_read_b128 v[168:171], v165
	ds_read_b128 v[172:175], v165 offset:1024
	ds_read_b128 v[176:179], v165 offset:2048
	ds_read_b128 v[180:183], v165 offset:3072
	ds_read_b128 v[184:187], v166
	ds_read_b128 v[188:191], v166 offset:1024
	ds_read_b128 v[192:195], v166 offset:2048
	ds_read_b128 v[196:199], v166 offset:3072
	s_add_i32 s54, s22, 2
	s_add_u32 s55, s20, 0x80
	s_addc_u32 s23, s21, 0
	s_cmp_eq_u32 s42, s22
	s_cselect_b32 s22, s4, s55
	s_cselect_b32 s23, s5, s23
	s_cselect_b32 s61, s19, s53
	s_cselect_b32 s60, s18, s52
	v_lshl_add_u64 v[234:235], s[20:21], 0, v[154:155]
	s_add_i32 m0, s31, 0xc000
	ds_read_b128 v[200:203], v167
	ds_read_b128 v[204:207], v167 offset:1024
	ds_read_b128 v[208:211], v167 offset:2048
	ds_read_b128 v[212:215], v167 offset:3072
	ds_read_b128 v[216:219], v167 offset:4096
	ds_read_b128 v[222:225], v167 offset:5120
	ds_read_b128 v[226:229], v167 offset:6144
	ds_read_b128 v[230:233], v167 offset:7168
	global_load_lds_dwordx4 v[234:235], off
	v_lshl_add_u64 v[234:235], s[20:21], 0, v[156:157]
	s_add_i32 m0, s31, 0xe000
	s_nop 0
	global_load_lds_dwordx4 v[234:235], off
	s_waitcnt vmcnt(8)
	s_waitcnt lgkmcnt(0)
	s_barrier
	s_waitcnt lgkmcnt(0)
	s_setprio 0
	v_mfma_f32_16x16x32_bf16 v[120:123], v[168:171], v[200:203], v[120:123]
	v_mfma_f32_16x16x32_bf16 v[120:123], v[172:175], v[204:207], v[120:123]
	v_mfma_f32_16x16x32_bf16 v[116:119], v[180:183], v[204:207], v[116:119]
	v_mfma_f32_16x16x32_bf16 v[116:119], v[176:179], v[200:203], v[116:119]
	v_mfma_f32_16x16x32_bf16 v[124:127], v[184:187], v[200:203], v[124:127]
	v_mfma_f32_16x16x32_bf16 v[124:127], v[188:191], v[204:207], v[124:127]
	v_mfma_f32_16x16x32_bf16 v[112:115], v[196:199], v[204:207], v[112:115]
	v_mfma_f32_16x16x32_bf16 v[112:115], v[192:195], v[200:203], v[112:115]
	v_mfma_f32_16x16x32_bf16 v[96:99], v[192:195], v[208:211], v[96:99]
	v_mfma_f32_16x16x32_bf16 v[96:99], v[196:199], v[212:215], v[96:99]
	v_mfma_f32_16x16x32_bf16 v[104:107], v[188:191], v[212:215], v[104:107]
	v_mfma_f32_16x16x32_bf16 v[104:107], v[184:187], v[208:211], v[104:107]
	v_mfma_f32_16x16x32_bf16 v[100:103], v[176:179], v[208:211], v[100:103]
	v_mfma_f32_16x16x32_bf16 v[100:103], v[180:183], v[212:215], v[100:103]
	v_mfma_f32_16x16x32_bf16 v[108:111], v[172:175], v[212:215], v[108:111]
	v_mfma_f32_16x16x32_bf16 v[108:111], v[168:171], v[208:211], v[108:111]
	v_mfma_f32_16x16x32_bf16 v[92:95], v[168:171], v[216:219], v[92:95]
	v_mfma_f32_16x16x32_bf16 v[92:95], v[172:175], v[222:225], v[92:95]
	v_mfma_f32_16x16x32_bf16 v[84:87], v[180:183], v[222:225], v[84:87]
	v_mfma_f32_16x16x32_bf16 v[84:87], v[176:179], v[216:219], v[84:87]
	v_mfma_f32_16x16x32_bf16 v[88:91], v[184:187], v[216:219], v[88:91]
	v_mfma_f32_16x16x32_bf16 v[88:91], v[188:191], v[222:225], v[88:91]
	v_mfma_f32_16x16x32_bf16 v[80:83], v[196:199], v[222:225], v[80:83]
	v_mfma_f32_16x16x32_bf16 v[80:83], v[192:195], v[216:219], v[80:83]
	v_mfma_f32_16x16x32_bf16 v[64:67], v[192:195], v[226:229], v[64:67]
	v_mfma_f32_16x16x32_bf16 v[64:67], v[196:199], v[230:233], v[64:67]
	v_mfma_f32_16x16x32_bf16 v[72:75], v[188:191], v[230:233], v[72:75]
	v_mfma_f32_16x16x32_bf16 v[72:75], v[184:187], v[226:229], v[72:75]
	v_mfma_f32_16x16x32_bf16 v[68:71], v[176:179], v[226:229], v[68:71]
	v_mfma_f32_16x16x32_bf16 v[68:71], v[180:183], v[230:233], v[68:71]
	v_mfma_f32_16x16x32_bf16 v[76:79], v[172:175], v[230:233], v[76:79]
	v_mfma_f32_16x16x32_bf16 v[76:79], v[168:171], v[226:229], v[76:79]
	s_setprio 1
	s_barrier
	s_add_i32 s55, s46, s28
	v_lshl_add_u64 v[234:235], s[60:61], 0, v[132:133]
	s_mov_b32 m0, s55
	ds_read_b128 v[200:203], v167 offset:16384
	ds_read_b128 v[204:207], v167 offset:17408
	ds_read_b128 v[208:211], v167 offset:18432
	ds_read_b128 v[212:215], v167 offset:19456
	ds_read_b128 v[216:219], v167 offset:20480
	ds_read_b128 v[222:225], v167 offset:21504
	ds_read_b128 v[226:229], v167 offset:22528
	ds_read_b128 v[230:233], v167 offset:23552
	global_load_lds_dwordx4 v[234:235], off
	s_add_i32 m0, s55, 0x2000
	v_lshl_add_u64 v[236:237], s[60:61], 0, v[128:129]
	s_add_u32 s60, s60, s10
	s_addc_u32 s61, s61, s11
	s_add_i32 s55, s47, s28
	global_load_lds_dwordx4 v[236:237], off
	v_lshl_add_u64 v[238:239], s[60:61], 0, v[132:133]
	s_mov_b32 m0, s55
	v_lshl_add_u64 v[240:241], s[60:61], 0, v[128:129]
	global_load_lds_dwordx4 v[238:239], off
	s_add_i32 m0, s55, 0x2000
	v_lshl_add_u64 v[242:243], s[22:23], 0, v[134:135]
	global_load_lds_dwordx4 v[240:241], off
	s_mov_b32 m0, s31
	v_lshl_add_u64 v[244:245], s[22:23], 0, v[130:131]
	global_load_lds_dwordx4 v[242:243], off
	s_mov_b32 m0, s33
	s_nop 0
	global_load_lds_dwordx4 v[244:245], off
	s_waitcnt vmcnt(8)
	s_waitcnt lgkmcnt(0)
	s_barrier
	s_waitcnt lgkmcnt(0)
	s_setprio 0
	v_mfma_f32_16x16x32_bf16 v[60:63], v[168:171], v[200:203], v[60:63]
	v_mfma_f32_16x16x32_bf16 v[60:63], v[172:175], v[204:207], v[60:63]
	v_mfma_f32_16x16x32_bf16 v[52:55], v[180:183], v[204:207], v[52:55]
	v_mfma_f32_16x16x32_bf16 v[52:55], v[176:179], v[200:203], v[52:55]
	v_mfma_f32_16x16x32_bf16 v[56:59], v[184:187], v[200:203], v[56:59]
	v_mfma_f32_16x16x32_bf16 v[56:59], v[188:191], v[204:207], v[56:59]
	v_mfma_f32_16x16x32_bf16 v[48:51], v[196:199], v[204:207], v[48:51]
	v_mfma_f32_16x16x32_bf16 v[48:51], v[192:195], v[200:203], v[48:51]
	v_mfma_f32_16x16x32_bf16 v[32:35], v[192:195], v[208:211], v[32:35]
	v_mfma_f32_16x16x32_bf16 v[32:35], v[196:199], v[212:215], v[32:35]
	v_mfma_f32_16x16x32_bf16 v[40:43], v[188:191], v[212:215], v[40:43]
	v_mfma_f32_16x16x32_bf16 v[40:43], v[184:187], v[208:211], v[40:43]
	v_mfma_f32_16x16x32_bf16 v[36:39], v[176:179], v[208:211], v[36:39]
	v_mfma_f32_16x16x32_bf16 v[36:39], v[180:183], v[212:215], v[36:39]
	v_mfma_f32_16x16x32_bf16 v[44:47], v[172:175], v[212:215], v[44:47]
	v_mfma_f32_16x16x32_bf16 v[44:47], v[168:171], v[208:211], v[44:47]
	v_mfma_f32_16x16x32_bf16 v[28:31], v[168:171], v[216:219], v[28:31]
	v_mfma_f32_16x16x32_bf16 v[28:31], v[172:175], v[222:225], v[28:31]
	v_mfma_f32_16x16x32_bf16 v[20:23], v[180:183], v[222:225], v[20:23]
	v_mfma_f32_16x16x32_bf16 v[20:23], v[176:179], v[216:219], v[20:23]
	v_mfma_f32_16x16x32_bf16 v[24:27], v[184:187], v[216:219], v[24:27]
	v_mfma_f32_16x16x32_bf16 v[24:27], v[188:191], v[222:225], v[24:27]
	v_mfma_f32_16x16x32_bf16 v[16:19], v[196:199], v[222:225], v[16:19]
	v_mfma_f32_16x16x32_bf16 v[16:19], v[192:195], v[216:219], v[16:19]
	v_mfma_f32_16x16x32_bf16 v[0:3], v[192:195], v[226:229], v[0:3]
	v_mfma_f32_16x16x32_bf16 v[0:3], v[196:199], v[230:233], v[0:3]
	v_mfma_f32_16x16x32_bf16 v[8:11], v[188:191], v[230:233], v[8:11]
	v_mfma_f32_16x16x32_bf16 v[8:11], v[184:187], v[226:229], v[8:11]
	v_mfma_f32_16x16x32_bf16 v[4:7], v[176:179], v[226:229], v[4:7]
	v_mfma_f32_16x16x32_bf16 v[4:7], v[180:183], v[230:233], v[4:7]
	v_mfma_f32_16x16x32_bf16 v[12:15], v[172:175], v[230:233], v[12:15]
	v_mfma_f32_16x16x32_bf16 v[12:15], v[168:171], v[226:229], v[12:15]
	s_setprio 1
	s_barrier
	s_add_i32 s55, 0, 0x18000
	s_add_i32 s60, 0, 0x1c000
	v_add_u32_e32 v180, s55, v164
	v_add_u32_e32 v196, s60, v164
	ds_read_b128 v[168:171], v180
	ds_read_b128 v[172:175], v180 offset:1024
	ds_read_b128 v[176:179], v180 offset:2048
	ds_read_b128 v[180:183], v180 offset:3072
	ds_read_b128 v[184:187], v196
	ds_read_b128 v[188:191], v196 offset:1024
	ds_read_b128 v[192:195], v196 offset:2048
	ds_read_b128 v[196:199], v196 offset:3072
	s_add_u32 s22, s22, s10
	s_addc_u32 s23, s23, s11
	s_mov_b32 m0, s34
	v_lshl_add_u64 v[246:247], s[22:23], 0, v[134:135]
	ds_read_b128 v[200:203], v167 offset:32768
	ds_read_b128 v[204:207], v167 offset:33792
	ds_read_b128 v[208:211], v167 offset:34816
	ds_read_b128 v[212:215], v167 offset:35840
	ds_read_b128 v[216:219], v167 offset:36864
	ds_read_b128 v[222:225], v167 offset:37888
	ds_read_b128 v[226:229], v167 offset:38912
	ds_read_b128 v[230:233], v167 offset:39936
	global_load_lds_dwordx4 v[246:247], off
	v_lshl_add_u64 v[246:247], s[22:23], 0, v[130:131]
	s_mov_b32 m0, s35
	s_nop 0
	global_load_lds_dwordx4 v[246:247], off
	s_waitcnt vmcnt(8)
	s_waitcnt lgkmcnt(0)
	s_barrier
	s_waitcnt lgkmcnt(0)
	s_setprio 0
	v_mfma_f32_16x16x32_bf16 v[120:123], v[168:171], v[200:203], v[120:123]
	v_mfma_f32_16x16x32_bf16 v[120:123], v[172:175], v[204:207], v[120:123]
	v_mfma_f32_16x16x32_bf16 v[116:119], v[180:183], v[204:207], v[116:119]
	v_mfma_f32_16x16x32_bf16 v[116:119], v[176:179], v[200:203], v[116:119]
	v_mfma_f32_16x16x32_bf16 v[124:127], v[184:187], v[200:203], v[124:127]
	v_mfma_f32_16x16x32_bf16 v[124:127], v[188:191], v[204:207], v[124:127]
	v_mfma_f32_16x16x32_bf16 v[112:115], v[196:199], v[204:207], v[112:115]
	v_mfma_f32_16x16x32_bf16 v[112:115], v[192:195], v[200:203], v[112:115]
	v_mfma_f32_16x16x32_bf16 v[96:99], v[192:195], v[208:211], v[96:99]
	v_mfma_f32_16x16x32_bf16 v[96:99], v[196:199], v[212:215], v[96:99]
	v_mfma_f32_16x16x32_bf16 v[104:107], v[188:191], v[212:215], v[104:107]
	v_mfma_f32_16x16x32_bf16 v[104:107], v[184:187], v[208:211], v[104:107]
	v_mfma_f32_16x16x32_bf16 v[100:103], v[176:179], v[208:211], v[100:103]
	v_mfma_f32_16x16x32_bf16 v[100:103], v[180:183], v[212:215], v[100:103]
	v_mfma_f32_16x16x32_bf16 v[108:111], v[172:175], v[212:215], v[108:111]
	v_mfma_f32_16x16x32_bf16 v[108:111], v[168:171], v[208:211], v[108:111]
	v_mfma_f32_16x16x32_bf16 v[92:95], v[168:171], v[216:219], v[92:95]
	v_mfma_f32_16x16x32_bf16 v[92:95], v[172:175], v[222:225], v[92:95]
	v_mfma_f32_16x16x32_bf16 v[84:87], v[180:183], v[222:225], v[84:87]
	v_mfma_f32_16x16x32_bf16 v[84:87], v[176:179], v[216:219], v[84:87]
	v_mfma_f32_16x16x32_bf16 v[88:91], v[184:187], v[216:219], v[88:91]
	v_mfma_f32_16x16x32_bf16 v[88:91], v[188:191], v[222:225], v[88:91]
	v_mfma_f32_16x16x32_bf16 v[80:83], v[196:199], v[222:225], v[80:83]
	v_mfma_f32_16x16x32_bf16 v[80:83], v[192:195], v[216:219], v[80:83]
	v_mfma_f32_16x16x32_bf16 v[64:67], v[192:195], v[226:229], v[64:67]
	v_mfma_f32_16x16x32_bf16 v[64:67], v[196:199], v[230:233], v[64:67]
	v_mfma_f32_16x16x32_bf16 v[72:75], v[188:191], v[230:233], v[72:75]
	v_mfma_f32_16x16x32_bf16 v[72:75], v[184:187], v[226:229], v[72:75]
	v_mfma_f32_16x16x32_bf16 v[68:71], v[176:179], v[226:229], v[68:71]
	v_mfma_f32_16x16x32_bf16 v[68:71], v[180:183], v[230:233], v[68:71]
	v_mfma_f32_16x16x32_bf16 v[76:79], v[172:175], v[230:233], v[76:79]
	v_mfma_f32_16x16x32_bf16 v[76:79], v[168:171], v[226:229], v[76:79]
	s_setprio 1
	s_barrier
	s_add_i32 s22, s55, s28
	v_lshl_add_u64 v[234:235], v[234:235], 0, s[14:15]
	s_mov_b32 m0, s22
	ds_read_b128 v[200:203], v167 offset:49152
	ds_read_b128 v[204:207], v167 offset:50176
	ds_read_b128 v[208:211], v167 offset:51200
	ds_read_b128 v[212:215], v167 offset:52224
	ds_read_b128 v[216:219], v167 offset:53248
	ds_read_b128 v[222:225], v167 offset:54272
	ds_read_b128 v[226:229], v167 offset:55296
	ds_read_b128 v[230:233], v167 offset:56320
	global_load_lds_dwordx4 v[234:235], off
	v_lshl_add_u64 v[234:235], v[236:237], 0, s[14:15]
	s_add_i32 m0, s22, 0x2000
	s_add_i32 s22, s60, s28
	global_load_lds_dwordx4 v[234:235], off
	v_lshl_add_u64 v[234:235], v[238:239], 0, s[14:15]
	s_mov_b32 m0, s22
	s_nop 0
	global_load_lds_dwordx4 v[234:235], off
	v_lshl_add_u64 v[234:235], v[240:241], 0, s[14:15]
	s_add_i32 m0, s22, 0x2000
	s_nop 0
	global_load_lds_dwordx4 v[234:235], off
	v_lshl_add_u64 v[234:235], v[242:243], 0, s[14:15]
	s_mov_b32 m0, s39
	s_nop 0
	global_load_lds_dwordx4 v[234:235], off
	v_lshl_add_u64 v[234:235], v[244:245], 0, s[14:15]
	s_mov_b32 m0, s40
	s_nop 0
	global_load_lds_dwordx4 v[234:235], off
	s_waitcnt vmcnt(8)
	s_waitcnt lgkmcnt(0)
	s_barrier
	s_waitcnt lgkmcnt(0)
	s_setprio 0
	v_mfma_f32_16x16x32_bf16 v[60:63], v[168:171], v[200:203], v[60:63]
	v_mfma_f32_16x16x32_bf16 v[60:63], v[172:175], v[204:207], v[60:63]
	v_mfma_f32_16x16x32_bf16 v[52:55], v[180:183], v[204:207], v[52:55]
	v_mfma_f32_16x16x32_bf16 v[52:55], v[176:179], v[200:203], v[52:55]
	v_mfma_f32_16x16x32_bf16 v[56:59], v[184:187], v[200:203], v[56:59]
	v_mfma_f32_16x16x32_bf16 v[56:59], v[188:191], v[204:207], v[56:59]
	v_mfma_f32_16x16x32_bf16 v[48:51], v[196:199], v[204:207], v[48:51]
	v_mfma_f32_16x16x32_bf16 v[48:51], v[192:195], v[200:203], v[48:51]
	v_mfma_f32_16x16x32_bf16 v[32:35], v[192:195], v[208:211], v[32:35]
	v_mfma_f32_16x16x32_bf16 v[32:35], v[196:199], v[212:215], v[32:35]
	v_mfma_f32_16x16x32_bf16 v[40:43], v[188:191], v[212:215], v[40:43]
	v_mfma_f32_16x16x32_bf16 v[40:43], v[184:187], v[208:211], v[40:43]
	v_mfma_f32_16x16x32_bf16 v[36:39], v[176:179], v[208:211], v[36:39]
	v_mfma_f32_16x16x32_bf16 v[36:39], v[180:183], v[212:215], v[36:39]
	v_mfma_f32_16x16x32_bf16 v[44:47], v[172:175], v[212:215], v[44:47]
	v_mfma_f32_16x16x32_bf16 v[44:47], v[168:171], v[208:211], v[44:47]
	v_mfma_f32_16x16x32_bf16 v[28:31], v[168:171], v[216:219], v[28:31]
	v_mfma_f32_16x16x32_bf16 v[28:31], v[172:175], v[222:225], v[28:31]
	v_mfma_f32_16x16x32_bf16 v[20:23], v[180:183], v[222:225], v[20:23]
	v_mfma_f32_16x16x32_bf16 v[20:23], v[176:179], v[216:219], v[20:23]
	v_mfma_f32_16x16x32_bf16 v[24:27], v[184:187], v[216:219], v[24:27]
	v_mfma_f32_16x16x32_bf16 v[24:27], v[188:191], v[222:225], v[24:27]
	v_mfma_f32_16x16x32_bf16 v[16:19], v[196:199], v[222:225], v[16:19]
	v_mfma_f32_16x16x32_bf16 v[16:19], v[192:195], v[216:219], v[16:19]
	v_mfma_f32_16x16x32_bf16 v[0:3], v[192:195], v[226:229], v[0:3]
	v_mfma_f32_16x16x32_bf16 v[0:3], v[196:199], v[230:233], v[0:3]
	v_mfma_f32_16x16x32_bf16 v[8:11], v[188:191], v[230:233], v[8:11]
	v_mfma_f32_16x16x32_bf16 v[8:11], v[184:187], v[226:229], v[8:11]
	v_mfma_f32_16x16x32_bf16 v[4:7], v[176:179], v[226:229], v[4:7]
	v_mfma_f32_16x16x32_bf16 v[4:7], v[180:183], v[230:233], v[4:7]
	v_mfma_f32_16x16x32_bf16 v[12:15], v[172:175], v[230:233], v[12:15]
	v_mfma_f32_16x16x32_bf16 v[12:15], v[168:171], v[226:229], v[12:15]
	s_setprio 1
	s_barrier
	s_add_u32 s20, s20, 0x100
	s_addc_u32 s21, s21, 0
	s_add_u32 s52, s52, 0x100
	s_addc_u32 s53, s53, 0
	s_cmp_ge_i32 s54, s41
	s_mov_b32 s22, s54
	s_cbranch_scc0 .LBB0_142

.LBB0_228:
	ds_read_b128 v[140:143], v219
	ds_read_b128 v[144:147], v219 offset:1024
	ds_read_b128 v[148:151], v219 offset:2048
	ds_read_b128 v[152:155], v219 offset:3072
	ds_read_b128 v[156:159], v221
	ds_read_b128 v[164:167], v221 offset:1024
	ds_read_b128 v[168:171], v221 offset:2048
	ds_read_b128 v[172:175], v221 offset:3072
	s_add_i32 s62, s26, 2
	s_add_u32 s27, s24, 0x4000
	s_addc_u32 s28, s25, 0
	s_cmp_eq_u32 s46, s26
	s_cselect_b32 s30, s0, s27
	s_cselect_b32 s31, s1, s28
	s_cselect_b32 s28, s22, s60
	s_cselect_b32 s29, s23, s61
	s_add_u32 s26, s30, 0x8000
	s_addc_u32 s27, s31, 0
	v_lshl_add_u64 v[160:161], s[24:25], 0, v[132:133]
	s_add_i32 m0, s38, 0xc000
	ds_read_b128 v[176:179], v222
	ds_read_b128 v[180:183], v222 offset:1024
	ds_read_b128 v[184:187], v222 offset:2048
	ds_read_b128 v[188:191], v222 offset:3072
	ds_read_b128 v[192:195], v222 offset:4096
	ds_read_b128 v[196:199], v222 offset:5120
	ds_read_b128 v[200:203], v222 offset:6144
	ds_read_b128 v[204:207], v222 offset:7168
	global_load_lds_dwordx4 v[160:161], off
	v_lshl_add_u64 v[160:161], s[24:25], 0, v[134:135]
	s_add_i32 m0, s38, 0xe000
	s_nop 0
	global_load_lds_dwordx4 v[160:161], off
	s_waitcnt vmcnt(8)
	s_waitcnt lgkmcnt(0)
	s_barrier
	s_waitcnt lgkmcnt(0)
	s_setprio 0
	v_mfma_f32_16x16x32_bf16 v[124:127], v[140:143], v[176:179], v[124:127]
	v_mfma_f32_16x16x32_bf16 v[124:127], v[144:147], v[180:183], v[124:127]
	v_mfma_f32_16x16x32_bf16 v[120:123], v[152:155], v[180:183], v[120:123]
	v_mfma_f32_16x16x32_bf16 v[120:123], v[148:151], v[176:179], v[120:123]
	v_mfma_f32_16x16x32_bf16 v[108:111], v[156:159], v[176:179], v[108:111]
	v_mfma_f32_16x16x32_bf16 v[108:111], v[164:167], v[180:183], v[108:111]
	v_mfma_f32_16x16x32_bf16 v[100:103], v[172:175], v[180:183], v[100:103]
	v_mfma_f32_16x16x32_bf16 v[100:103], v[168:171], v[176:179], v[100:103]
	v_mfma_f32_16x16x32_bf16 v[84:87], v[168:171], v[184:187], v[84:87]
	v_mfma_f32_16x16x32_bf16 v[84:87], v[172:175], v[188:191], v[84:87]
	v_mfma_f32_16x16x32_bf16 v[92:95], v[164:167], v[188:191], v[92:95]
	v_mfma_f32_16x16x32_bf16 v[92:95], v[156:159], v[184:187], v[92:95]
	v_mfma_f32_16x16x32_bf16 v[112:115], v[148:151], v[184:187], v[112:115]
	v_mfma_f32_16x16x32_bf16 v[112:115], v[152:155], v[188:191], v[112:115]
	v_mfma_f32_16x16x32_bf16 v[116:119], v[144:147], v[188:191], v[116:119]
	v_mfma_f32_16x16x32_bf16 v[116:119], v[140:143], v[184:187], v[116:119]
	v_mfma_f32_16x16x32_bf16 v[104:107], v[140:143], v[192:195], v[104:107]
	v_mfma_f32_16x16x32_bf16 v[104:107], v[144:147], v[196:199], v[104:107]
	v_mfma_f32_16x16x32_bf16 v[96:99], v[152:155], v[196:199], v[96:99]
	v_mfma_f32_16x16x32_bf16 v[96:99], v[148:151], v[192:195], v[96:99]
	v_mfma_f32_16x16x32_bf16 v[76:79], v[156:159], v[192:195], v[76:79]
	v_mfma_f32_16x16x32_bf16 v[76:79], v[164:167], v[196:199], v[76:79]
	v_mfma_f32_16x16x32_bf16 v[72:75], v[172:175], v[196:199], v[72:75]
	v_mfma_f32_16x16x32_bf16 v[72:75], v[168:171], v[192:195], v[72:75]
	v_mfma_f32_16x16x32_bf16 v[64:67], v[168:171], v[200:203], v[64:67]
	v_mfma_f32_16x16x32_bf16 v[64:67], v[172:175], v[204:207], v[64:67]
	v_mfma_f32_16x16x32_bf16 v[68:71], v[164:167], v[204:207], v[68:71]
	v_mfma_f32_16x16x32_bf16 v[68:71], v[156:159], v[200:203], v[68:71]
	v_mfma_f32_16x16x32_bf16 v[80:83], v[148:151], v[200:203], v[80:83]
	v_mfma_f32_16x16x32_bf16 v[80:83], v[152:155], v[204:207], v[80:83]
	v_mfma_f32_16x16x32_bf16 v[88:91], v[144:147], v[204:207], v[88:91]
	v_mfma_f32_16x16x32_bf16 v[88:91], v[140:143], v[200:203], v[88:91]
	s_setprio 1
	s_barrier
	s_add_i32 s63, s50, s37
	v_lshl_add_u64 v[160:161], s[28:29], 0, v[128:129]
	s_mov_b32 m0, s63
	ds_read_b128 v[176:179], v222 offset:16384
	ds_read_b128 v[180:183], v222 offset:17408
	ds_read_b128 v[184:187], v222 offset:18432
	ds_read_b128 v[188:191], v222 offset:19456
	ds_read_b128 v[192:195], v222 offset:20480
	ds_read_b128 v[196:199], v222 offset:21504
	ds_read_b128 v[200:203], v222 offset:22528
	ds_read_b128 v[204:207], v222 offset:23552
	global_load_lds_dwordx4 v[160:161], off
	s_add_i32 m0, s63, 0x2000
	s_add_u32 s64, s28, 0x4000
	v_lshl_add_u64 v[160:161], s[28:29], 0, v[130:131]
	s_addc_u32 s65, s29, 0
	s_add_i32 s63, s51, s37
	global_load_lds_dwordx4 v[160:161], off
	v_lshl_add_u64 v[160:161], s[64:65], 0, v[128:129]
	s_mov_b32 m0, s63
	s_nop 0
	global_load_lds_dwordx4 v[160:161], off
	v_lshl_add_u64 v[160:161], s[64:65], 0, v[130:131]
	s_add_i32 m0, s63, 0x2000
	s_nop 0
	global_load_lds_dwordx4 v[160:161], off
	v_lshl_add_u64 v[160:161], s[30:31], 0, v[128:129]
	s_mov_b32 m0, s38
	s_nop 0
	global_load_lds_dwordx4 v[160:161], off
	v_lshl_add_u64 v[160:161], s[30:31], 0, v[130:131]
	s_mov_b32 m0, s39
	s_nop 0
	global_load_lds_dwordx4 v[160:161], off
	s_waitcnt vmcnt(8)
	s_waitcnt lgkmcnt(0)
	s_barrier
	s_waitcnt lgkmcnt(0)
	s_setprio 0
	v_mfma_f32_16x16x32_bf16 v[60:63], v[140:143], v[176:179], v[60:63]
	v_mfma_f32_16x16x32_bf16 v[60:63], v[144:147], v[180:183], v[60:63]
	v_mfma_f32_16x16x32_bf16 v[56:59], v[152:155], v[180:183], v[56:59]
	v_mfma_f32_16x16x32_bf16 v[56:59], v[148:151], v[176:179], v[56:59]
	v_mfma_f32_16x16x32_bf16 v[44:47], v[156:159], v[176:179], v[44:47]
	v_mfma_f32_16x16x32_bf16 v[44:47], v[164:167], v[180:183], v[44:47]
	v_mfma_f32_16x16x32_bf16 v[36:39], v[172:175], v[180:183], v[36:39]
	v_mfma_f32_16x16x32_bf16 v[36:39], v[168:171], v[176:179], v[36:39]
	v_mfma_f32_16x16x32_bf16 v[20:23], v[168:171], v[184:187], v[20:23]
	v_mfma_f32_16x16x32_bf16 v[20:23], v[172:175], v[188:191], v[20:23]
	v_mfma_f32_16x16x32_bf16 v[28:31], v[164:167], v[188:191], v[28:31]
	v_mfma_f32_16x16x32_bf16 v[28:31], v[156:159], v[184:187], v[28:31]
	v_mfma_f32_16x16x32_bf16 v[48:51], v[148:151], v[184:187], v[48:51]
	v_mfma_f32_16x16x32_bf16 v[48:51], v[152:155], v[188:191], v[48:51]
	v_mfma_f32_16x16x32_bf16 v[52:55], v[144:147], v[188:191], v[52:55]
	v_mfma_f32_16x16x32_bf16 v[52:55], v[140:143], v[184:187], v[52:55]
	v_mfma_f32_16x16x32_bf16 v[40:43], v[140:143], v[192:195], v[40:43]
	v_mfma_f32_16x16x32_bf16 v[40:43], v[144:147], v[196:199], v[40:43]
	v_mfma_f32_16x16x32_bf16 v[32:35], v[152:155], v[196:199], v[32:35]
	v_mfma_f32_16x16x32_bf16 v[32:35], v[148:151], v[192:195], v[32:35]
	v_mfma_f32_16x16x32_bf16 v[12:15], v[156:159], v[192:195], v[12:15]
	v_mfma_f32_16x16x32_bf16 v[12:15], v[164:167], v[196:199], v[12:15]
	v_mfma_f32_16x16x32_bf16 v[8:11], v[172:175], v[196:199], v[8:11]
	v_mfma_f32_16x16x32_bf16 v[8:11], v[168:171], v[192:195], v[8:11]
	v_mfma_f32_16x16x32_bf16 v[0:3], v[168:171], v[200:203], v[0:3]
	v_mfma_f32_16x16x32_bf16 v[0:3], v[172:175], v[204:207], v[0:3]
	v_mfma_f32_16x16x32_bf16 v[4:7], v[164:167], v[204:207], v[4:7]
	v_mfma_f32_16x16x32_bf16 v[4:7], v[156:159], v[200:203], v[4:7]
	v_mfma_f32_16x16x32_bf16 v[16:19], v[148:151], v[200:203], v[16:19]
	v_mfma_f32_16x16x32_bf16 v[16:19], v[152:155], v[204:207], v[16:19]
	v_mfma_f32_16x16x32_bf16 v[24:27], v[144:147], v[204:207], v[24:27]
	v_mfma_f32_16x16x32_bf16 v[24:27], v[140:143], v[200:203], v[24:27]
	s_setprio 1
	s_barrier
	s_add_i32 s63, 0, 0x18000
	s_add_i32 s64, 0, 0x1c000
	v_add_u32_e32 v152, s63, v217
	v_add_u32_e32 v160, s64, v217
	ds_read_b128 v[140:143], v152
	ds_read_b128 v[144:147], v152 offset:1024
	ds_read_b128 v[148:151], v152 offset:2048
	ds_read_b128 v[152:155], v152 offset:3072
	ds_read_b128 v[156:159], v160
	ds_read_b128 v[164:167], v160 offset:1024
	ds_read_b128 v[168:171], v160 offset:2048
	ds_read_b128 v[172:175], v160 offset:3072
	s_add_u32 s30, s30, 0x4000
	s_addc_u32 s31, s31, 0
	s_mov_b32 m0, s40
	v_lshl_add_u64 v[160:161], s[30:31], 0, v[128:129]
	ds_read_b128 v[176:179], v222 offset:32768
	ds_read_b128 v[180:183], v222 offset:33792
	ds_read_b128 v[184:187], v222 offset:34816
	ds_read_b128 v[188:191], v222 offset:35840
	ds_read_b128 v[192:195], v222 offset:36864
	ds_read_b128 v[196:199], v222 offset:37888
	ds_read_b128 v[200:203], v222 offset:38912
	ds_read_b128 v[204:207], v222 offset:39936
	global_load_lds_dwordx4 v[160:161], off
	v_lshl_add_u64 v[160:161], s[30:31], 0, v[130:131]
	s_mov_b32 m0, s41
	s_nop 0
	global_load_lds_dwordx4 v[160:161], off
	s_waitcnt vmcnt(8)
	s_waitcnt lgkmcnt(0)
	s_barrier
	s_waitcnt lgkmcnt(0)
	s_setprio 0
	v_mfma_f32_16x16x32_bf16 v[124:127], v[140:143], v[176:179], v[124:127]
	v_mfma_f32_16x16x32_bf16 v[124:127], v[144:147], v[180:183], v[124:127]
	v_mfma_f32_16x16x32_bf16 v[120:123], v[152:155], v[180:183], v[120:123]
	v_mfma_f32_16x16x32_bf16 v[120:123], v[148:151], v[176:179], v[120:123]
	v_mfma_f32_16x16x32_bf16 v[108:111], v[156:159], v[176:179], v[108:111]
	v_mfma_f32_16x16x32_bf16 v[108:111], v[164:167], v[180:183], v[108:111]
	v_mfma_f32_16x16x32_bf16 v[100:103], v[172:175], v[180:183], v[100:103]
	v_mfma_f32_16x16x32_bf16 v[100:103], v[168:171], v[176:179], v[100:103]
	v_mfma_f32_16x16x32_bf16 v[84:87], v[168:171], v[184:187], v[84:87]
	v_mfma_f32_16x16x32_bf16 v[84:87], v[172:175], v[188:191], v[84:87]
	v_mfma_f32_16x16x32_bf16 v[92:95], v[164:167], v[188:191], v[92:95]
	v_mfma_f32_16x16x32_bf16 v[92:95], v[156:159], v[184:187], v[92:95]
	v_mfma_f32_16x16x32_bf16 v[112:115], v[148:151], v[184:187], v[112:115]
	v_mfma_f32_16x16x32_bf16 v[112:115], v[152:155], v[188:191], v[112:115]
	v_mfma_f32_16x16x32_bf16 v[116:119], v[144:147], v[188:191], v[116:119]
	v_mfma_f32_16x16x32_bf16 v[116:119], v[140:143], v[184:187], v[116:119]
	v_mfma_f32_16x16x32_bf16 v[104:107], v[140:143], v[192:195], v[104:107]
	v_mfma_f32_16x16x32_bf16 v[104:107], v[144:147], v[196:199], v[104:107]
	v_mfma_f32_16x16x32_bf16 v[96:99], v[152:155], v[196:199], v[96:99]
	v_mfma_f32_16x16x32_bf16 v[96:99], v[148:151], v[192:195], v[96:99]
	v_mfma_f32_16x16x32_bf16 v[76:79], v[156:159], v[192:195], v[76:79]
	v_mfma_f32_16x16x32_bf16 v[76:79], v[164:167], v[196:199], v[76:79]
	v_mfma_f32_16x16x32_bf16 v[72:75], v[172:175], v[196:199], v[72:75]
	v_mfma_f32_16x16x32_bf16 v[72:75], v[168:171], v[192:195], v[72:75]
	v_mfma_f32_16x16x32_bf16 v[64:67], v[168:171], v[200:203], v[64:67]
	v_mfma_f32_16x16x32_bf16 v[64:67], v[172:175], v[204:207], v[64:67]
	v_mfma_f32_16x16x32_bf16 v[68:71], v[164:167], v[204:207], v[68:71]
	v_mfma_f32_16x16x32_bf16 v[68:71], v[156:159], v[200:203], v[68:71]
	v_mfma_f32_16x16x32_bf16 v[80:83], v[148:151], v[200:203], v[80:83]
	v_mfma_f32_16x16x32_bf16 v[80:83], v[152:155], v[204:207], v[80:83]
	v_mfma_f32_16x16x32_bf16 v[88:91], v[144:147], v[204:207], v[88:91]
	v_mfma_f32_16x16x32_bf16 v[88:91], v[140:143], v[200:203], v[88:91]
	s_setprio 1
	s_barrier
	s_add_u32 s30, s28, 0x8000
	s_addc_u32 s31, s29, 0
	s_add_i32 s63, s63, s37
	v_lshl_add_u64 v[160:161], s[30:31], 0, v[128:129]
	s_mov_b32 m0, s63
	ds_read_b128 v[176:179], v222 offset:49152
	ds_read_b128 v[180:183], v222 offset:50176
	ds_read_b128 v[184:187], v222 offset:51200
	ds_read_b128 v[188:191], v222 offset:52224
	ds_read_b128 v[192:195], v222 offset:53248
	ds_read_b128 v[196:199], v222 offset:54272
	ds_read_b128 v[200:203], v222 offset:55296
	ds_read_b128 v[204:207], v222 offset:56320
	global_load_lds_dwordx4 v[160:161], off
	s_add_i32 m0, s63, 0x2000
	s_add_u32 s28, s28, 0xc000
	v_lshl_add_u64 v[160:161], s[30:31], 0, v[130:131]
	s_addc_u32 s29, s29, 0
	s_add_i32 s30, s64, s37
	global_load_lds_dwordx4 v[160:161], off
	v_lshl_add_u64 v[160:161], s[28:29], 0, v[128:129]
	s_mov_b32 m0, s30
	s_nop 0
	global_load_lds_dwordx4 v[160:161], off
	v_lshl_add_u64 v[160:161], s[28:29], 0, v[130:131]
	s_add_i32 m0, s30, 0x2000
	s_nop 0
	global_load_lds_dwordx4 v[160:161], off
	v_lshl_add_u64 v[160:161], s[26:27], 0, v[128:129]
	s_mov_b32 m0, s44
	s_nop 0
	global_load_lds_dwordx4 v[160:161], off
	v_lshl_add_u64 v[160:161], s[26:27], 0, v[130:131]
	s_mov_b32 m0, s45
	s_nop 0
	global_load_lds_dwordx4 v[160:161], off
	s_waitcnt vmcnt(8)
	s_waitcnt lgkmcnt(0)
	s_barrier
	s_waitcnt lgkmcnt(0)
	s_setprio 0
	v_mfma_f32_16x16x32_bf16 v[60:63], v[140:143], v[176:179], v[60:63]
	v_mfma_f32_16x16x32_bf16 v[60:63], v[144:147], v[180:183], v[60:63]
	v_mfma_f32_16x16x32_bf16 v[56:59], v[152:155], v[180:183], v[56:59]
	v_mfma_f32_16x16x32_bf16 v[56:59], v[148:151], v[176:179], v[56:59]
	v_mfma_f32_16x16x32_bf16 v[44:47], v[156:159], v[176:179], v[44:47]
	v_mfma_f32_16x16x32_bf16 v[44:47], v[164:167], v[180:183], v[44:47]
	v_mfma_f32_16x16x32_bf16 v[36:39], v[172:175], v[180:183], v[36:39]
	v_mfma_f32_16x16x32_bf16 v[36:39], v[168:171], v[176:179], v[36:39]
	v_mfma_f32_16x16x32_bf16 v[20:23], v[168:171], v[184:187], v[20:23]
	v_mfma_f32_16x16x32_bf16 v[20:23], v[172:175], v[188:191], v[20:23]
	v_mfma_f32_16x16x32_bf16 v[28:31], v[164:167], v[188:191], v[28:31]
	v_mfma_f32_16x16x32_bf16 v[28:31], v[156:159], v[184:187], v[28:31]
	v_mfma_f32_16x16x32_bf16 v[48:51], v[148:151], v[184:187], v[48:51]
	v_mfma_f32_16x16x32_bf16 v[48:51], v[152:155], v[188:191], v[48:51]
	v_mfma_f32_16x16x32_bf16 v[52:55], v[144:147], v[188:191], v[52:55]
	v_mfma_f32_16x16x32_bf16 v[52:55], v[140:143], v[184:187], v[52:55]
	v_mfma_f32_16x16x32_bf16 v[40:43], v[140:143], v[192:195], v[40:43]
	v_mfma_f32_16x16x32_bf16 v[40:43], v[144:147], v[196:199], v[40:43]
	v_mfma_f32_16x16x32_bf16 v[32:35], v[152:155], v[196:199], v[32:35]
	v_mfma_f32_16x16x32_bf16 v[32:35], v[148:151], v[192:195], v[32:35]
	v_mfma_f32_16x16x32_bf16 v[12:15], v[156:159], v[192:195], v[12:15]
	v_mfma_f32_16x16x32_bf16 v[12:15], v[164:167], v[196:199], v[12:15]
	v_mfma_f32_16x16x32_bf16 v[8:11], v[172:175], v[196:199], v[8:11]
	v_mfma_f32_16x16x32_bf16 v[8:11], v[168:171], v[192:195], v[8:11]
	v_mfma_f32_16x16x32_bf16 v[0:3], v[168:171], v[200:203], v[0:3]
	v_mfma_f32_16x16x32_bf16 v[0:3], v[172:175], v[204:207], v[0:3]
	v_mfma_f32_16x16x32_bf16 v[4:7], v[164:167], v[204:207], v[4:7]
	v_mfma_f32_16x16x32_bf16 v[4:7], v[156:159], v[200:203], v[4:7]
	v_mfma_f32_16x16x32_bf16 v[16:19], v[148:151], v[200:203], v[16:19]
	v_mfma_f32_16x16x32_bf16 v[16:19], v[152:155], v[204:207], v[16:19]
	v_mfma_f32_16x16x32_bf16 v[24:27], v[144:147], v[204:207], v[24:27]
	v_mfma_f32_16x16x32_bf16 v[24:27], v[140:143], v[200:203], v[24:27]
	s_setprio 1
	s_barrier
	s_add_u32 s24, s24, 0x10000
	s_addc_u32 s25, s25, 0
	s_add_u32 s60, s60, 0x10000
	s_addc_u32 s61, s61, 0
	s_cmp_ge_i32 s62, s43
	s_mov_b32 s26, s62
	s_cbranch_scc0 .LBB0_228
	v_pk_mul_f32 v[200:201], v[126:127], 0.5 op_sel_hi:[1,0]
	v_pk_mul_f32 v[202:203], v[124:125], 0.5 op_sel_hi:[1,0]
	v_pk_mul_f32 v[204:205], v[122:123], 0.5 op_sel_hi:[1,0]
	v_pk_mul_f32 v[206:207], v[120:121], 0.5 op_sel_hi:[1,0]
	v_pk_mul_f32 v[210:211], v[110:111], 0.5 op_sel_hi:[1,0]
	v_pk_mul_f32 v[208:209], v[108:109], 0.5 op_sel_hi:[1,0]
	v_pk_mul_f32 v[198:199], v[102:103], 0.5 op_sel_hi:[1,0]
	v_pk_mul_f32 v[196:197], v[100:101], 0.5 op_sel_hi:[1,0]
	v_pk_mul_f32 v[194:195], v[118:119], 0.5 op_sel_hi:[1,0]
	v_pk_mul_f32 v[192:193], v[116:117], 0.5 op_sel_hi:[1,0]
	v_pk_mul_f32 v[190:191], v[114:115], 0.5 op_sel_hi:[1,0]
	v_pk_mul_f32 v[188:189], v[112:113], 0.5 op_sel_hi:[1,0]
	v_pk_mul_f32 v[186:187], v[94:95], 0.5 op_sel_hi:[1,0]
	v_pk_mul_f32 v[184:185], v[92:93], 0.5 op_sel_hi:[1,0]
	v_pk_mul_f32 v[182:183], v[86:87], 0.5 op_sel_hi:[1,0]
	v_pk_mul_f32 v[180:181], v[84:85], 0.5 op_sel_hi:[1,0]
	v_pk_mul_f32 v[178:179], v[106:107], 0.5 op_sel_hi:[1,0]
	v_pk_mul_f32 v[176:177], v[104:105], 0.5 op_sel_hi:[1,0]
	v_pk_mul_f32 v[174:175], v[98:99], 0.5 op_sel_hi:[1,0]
	v_pk_mul_f32 v[172:173], v[96:97], 0.5 op_sel_hi:[1,0]
	v_pk_mul_f32 v[170:171], v[78:79], 0.5 op_sel_hi:[1,0]
	v_pk_mul_f32 v[168:169], v[76:77], 0.5 op_sel_hi:[1,0]
	v_pk_mul_f32 v[166:167], v[74:75], 0.5 op_sel_hi:[1,0]
	v_pk_mul_f32 v[164:165], v[72:73], 0.5 op_sel_hi:[1,0]
	v_pk_mul_f32 v[160:161], v[90:91], 0.5 op_sel_hi:[1,0]
	v_pk_mul_f32 v[158:159], v[88:89], 0.5 op_sel_hi:[1,0]
	v_pk_mul_f32 v[156:157], v[82:83], 0.5 op_sel_hi:[1,0]
	v_pk_mul_f32 v[154:155], v[80:81], 0.5 op_sel_hi:[1,0]
	v_pk_mul_f32 v[152:153], v[70:71], 0.5 op_sel_hi:[1,0]
	v_pk_mul_f32 v[150:151], v[68:69], 0.5 op_sel_hi:[1,0]
	v_pk_mul_f32 v[148:149], v[66:67], 0.5 op_sel_hi:[1,0]
	v_pk_mul_f32 v[146:147], v[64:65], 0.5 op_sel_hi:[1,0]
	v_pk_mul_f32 v[144:145], v[62:63], 0.5 op_sel_hi:[1,0]
	v_pk_mul_f32 v[142:143], v[60:61], 0.5 op_sel_hi:[1,0]
	v_pk_mul_f32 v[126:127], v[58:59], 0.5 op_sel_hi:[1,0]
	v_pk_mul_f32 v[124:125], v[56:57], 0.5 op_sel_hi:[1,0]
	v_pk_mul_f32 v[122:123], v[46:47], 0.5 op_sel_hi:[1,0]
	v_pk_mul_f32 v[120:121], v[44:45], 0.5 op_sel_hi:[1,0]
	v_pk_mul_f32 v[118:119], v[38:39], 0.5 op_sel_hi:[1,0]
	v_pk_mul_f32 v[116:117], v[36:37], 0.5 op_sel_hi:[1,0]
	v_pk_mul_f32 v[114:115], v[54:55], 0.5 op_sel_hi:[1,0]
	v_pk_mul_f32 v[112:113], v[52:53], 0.5 op_sel_hi:[1,0]
	v_pk_mul_f32 v[110:111], v[50:51], 0.5 op_sel_hi:[1,0]
	v_pk_mul_f32 v[108:109], v[48:49], 0.5 op_sel_hi:[1,0]
	v_pk_mul_f32 v[106:107], v[30:31], 0.5 op_sel_hi:[1,0]
	v_pk_mul_f32 v[104:105], v[28:29], 0.5 op_sel_hi:[1,0]
	v_pk_mul_f32 v[102:103], v[22:23], 0.5 op_sel_hi:[1,0]
	v_pk_mul_f32 v[100:101], v[20:21], 0.5 op_sel_hi:[1,0]
	v_pk_mul_f32 v[98:99], v[42:43], 0.5 op_sel_hi:[1,0]
	v_pk_mul_f32 v[96:97], v[40:41], 0.5 op_sel_hi:[1,0]
	v_pk_mul_f32 v[94:95], v[34:35], 0.5 op_sel_hi:[1,0]
	v_pk_mul_f32 v[92:93], v[32:33], 0.5 op_sel_hi:[1,0]
	v_pk_mul_f32 v[90:91], v[14:15], 0.5 op_sel_hi:[1,0]
	v_pk_mul_f32 v[88:89], v[12:13], 0.5 op_sel_hi:[1,0]
	v_pk_mul_f32 v[86:87], v[10:11], 0.5 op_sel_hi:[1,0]
	v_pk_mul_f32 v[84:85], v[8:9], 0.5 op_sel_hi:[1,0]
	v_pk_mul_f32 v[82:83], v[26:27], 0.5 op_sel_hi:[1,0]
	v_pk_mul_f32 v[80:81], v[24:25], 0.5 op_sel_hi:[1,0]
	v_pk_mul_f32 v[78:79], v[18:19], 0.5 op_sel_hi:[1,0]
	v_pk_mul_f32 v[76:77], v[16:17], 0.5 op_sel_hi:[1,0]
	v_pk_mul_f32 v[74:75], v[6:7], 0.5 op_sel_hi:[1,0]
	v_pk_mul_f32 v[72:73], v[4:5], 0.5 op_sel_hi:[1,0]
	v_pk_mul_f32 v[70:71], v[2:3], 0.5 op_sel_hi:[1,0]
	v_pk_mul_f32 v[68:69], v[0:1], 0.5 op_sel_hi:[1,0]

.LBB0_323:
	ds_read_b128 v[128:131], v222
	ds_read_b128 v[132:135], v222 offset:1024
	ds_read_b128 v[136:139], v222 offset:2048
	ds_read_b128 v[140:143], v222 offset:3072
	ds_read_b128 v[144:147], v223
	ds_read_b128 v[148:151], v223 offset:1024
	ds_read_b128 v[152:155], v223 offset:2048
	ds_read_b128 v[156:159], v223 offset:3072
	s_add_i32 s53, s50, 2
	s_add_u32 s54, s0, 0x80
	s_addc_u32 s51, s1, 0
	s_cmp_eq_u32 s78, s50
	s_cselect_b32 s50, s46, s54
	s_cselect_b32 s51, s47, s51
	s_cselect_b32 s55, s49, s52
	s_cselect_b32 s54, s48, s33
	v_lshl_add_u64 v[160:161], s[0:1], 0, v[176:177]
	s_add_i32 m0, s71, 0xc000
	ds_read_b128 v[184:187], v224
	ds_read_b128 v[188:191], v224 offset:1024
	ds_read_b128 v[192:195], v224 offset:2048
	ds_read_b128 v[196:199], v224 offset:3072
	ds_read_b128 v[200:203], v224 offset:4096
	ds_read_b128 v[204:207], v224 offset:5120
	ds_read_b128 v[208:211], v224 offset:6144
	ds_read_b128 v[212:215], v224 offset:7168
	global_load_lds_dwordx4 v[160:161], off
	v_lshl_add_u64 v[160:161], s[0:1], 0, v[178:179]
	s_add_i32 m0, s71, 0xe000
	s_nop 0
	global_load_lds_dwordx4 v[160:161], off
	s_waitcnt vmcnt(8)
	s_waitcnt lgkmcnt(0)
	s_barrier
	s_waitcnt lgkmcnt(0)
	s_setprio 0
	v_mfma_f32_16x16x32_bf16 v[124:127], v[128:131], v[184:187], v[124:127]
	v_mfma_f32_16x16x32_bf16 v[124:127], v[132:135], v[188:191], v[124:127]
	v_mfma_f32_16x16x32_bf16 v[120:123], v[140:143], v[188:191], v[120:123]
	v_mfma_f32_16x16x32_bf16 v[120:123], v[136:139], v[184:187], v[120:123]
	v_mfma_f32_16x16x32_bf16 v[116:119], v[144:147], v[184:187], v[116:119]
	v_mfma_f32_16x16x32_bf16 v[116:119], v[148:151], v[188:191], v[116:119]
	v_mfma_f32_16x16x32_bf16 v[112:115], v[156:159], v[188:191], v[112:115]
	v_mfma_f32_16x16x32_bf16 v[112:115], v[152:155], v[184:187], v[112:115]
	v_mfma_f32_16x16x32_bf16 v[96:99], v[152:155], v[192:195], v[96:99]
	v_mfma_f32_16x16x32_bf16 v[96:99], v[156:159], v[196:199], v[96:99]
	v_mfma_f32_16x16x32_bf16 v[100:103], v[148:151], v[196:199], v[100:103]
	v_mfma_f32_16x16x32_bf16 v[100:103], v[144:147], v[192:195], v[100:103]
	v_mfma_f32_16x16x32_bf16 v[104:107], v[136:139], v[192:195], v[104:107]
	v_mfma_f32_16x16x32_bf16 v[104:107], v[140:143], v[196:199], v[104:107]
	v_mfma_f32_16x16x32_bf16 v[108:111], v[132:135], v[196:199], v[108:111]
	v_mfma_f32_16x16x32_bf16 v[108:111], v[128:131], v[192:195], v[108:111]
	v_mfma_f32_16x16x32_bf16 v[92:95], v[128:131], v[200:203], v[92:95]
	v_mfma_f32_16x16x32_bf16 v[92:95], v[132:135], v[204:207], v[92:95]
	v_mfma_f32_16x16x32_bf16 v[88:91], v[140:143], v[204:207], v[88:91]
	v_mfma_f32_16x16x32_bf16 v[88:91], v[136:139], v[200:203], v[88:91]
	v_mfma_f32_16x16x32_bf16 v[84:87], v[144:147], v[200:203], v[84:87]
	v_mfma_f32_16x16x32_bf16 v[84:87], v[148:151], v[204:207], v[84:87]
	v_mfma_f32_16x16x32_bf16 v[80:83], v[156:159], v[204:207], v[80:83]
	v_mfma_f32_16x16x32_bf16 v[80:83], v[152:155], v[200:203], v[80:83]
	v_mfma_f32_16x16x32_bf16 v[64:67], v[152:155], v[208:211], v[64:67]
	v_mfma_f32_16x16x32_bf16 v[64:67], v[156:159], v[212:215], v[64:67]
	v_mfma_f32_16x16x32_bf16 v[68:71], v[148:151], v[212:215], v[68:71]
	v_mfma_f32_16x16x32_bf16 v[68:71], v[144:147], v[208:211], v[68:71]
	v_mfma_f32_16x16x32_bf16 v[72:75], v[136:139], v[208:211], v[72:75]
	v_mfma_f32_16x16x32_bf16 v[72:75], v[140:143], v[212:215], v[72:75]
	v_mfma_f32_16x16x32_bf16 v[76:79], v[132:135], v[212:215], v[76:79]
	v_mfma_f32_16x16x32_bf16 v[76:79], v[128:131], v[208:211], v[76:79]
	s_setprio 1
	s_barrier
	s_add_i32 s60, s82, s70
	v_lshl_add_u64 v[160:161], s[54:55], 0, v[166:167]
	s_mov_b32 m0, s60
	ds_read_b128 v[184:187], v224 offset:16384
	ds_read_b128 v[188:191], v224 offset:17408
	ds_read_b128 v[192:195], v224 offset:18432
	ds_read_b128 v[196:199], v224 offset:19456
	ds_read_b128 v[200:203], v224 offset:20480
	ds_read_b128 v[204:207], v224 offset:21504
	ds_read_b128 v[208:211], v224 offset:22528
	ds_read_b128 v[212:215], v224 offset:23552
	global_load_lds_dwordx4 v[160:161], off
	s_add_i32 m0, s60, 0x2000
	v_lshl_add_u64 v[216:217], s[54:55], 0, v[170:171]
	s_add_u32 s54, s54, s10
	s_addc_u32 s55, s55, s11
	s_add_i32 s60, s83, s70
	global_load_lds_dwordx4 v[216:217], off
	v_lshl_add_u64 v[218:219], s[54:55], 0, v[166:167]
	s_mov_b32 m0, s60
	v_lshl_add_u64 v[230:231], s[54:55], 0, v[170:171]
	global_load_lds_dwordx4 v[218:219], off
	s_add_i32 m0, s60, 0x2000
	v_lshl_add_u64 v[232:233], s[50:51], 0, v[164:165]
	global_load_lds_dwordx4 v[230:231], off
	s_mov_b32 m0, s71
	v_lshl_add_u64 v[234:235], s[50:51], 0, v[168:169]
	global_load_lds_dwordx4 v[232:233], off
	s_mov_b32 m0, s72
	s_nop 0
	global_load_lds_dwordx4 v[234:235], off
	s_waitcnt vmcnt(8)
	s_waitcnt lgkmcnt(0)
	s_barrier
	s_waitcnt lgkmcnt(0)
	s_setprio 0
	v_mfma_f32_16x16x32_bf16 v[60:63], v[128:131], v[184:187], v[60:63]
	v_mfma_f32_16x16x32_bf16 v[60:63], v[132:135], v[188:191], v[60:63]
	v_mfma_f32_16x16x32_bf16 v[56:59], v[140:143], v[188:191], v[56:59]
	v_mfma_f32_16x16x32_bf16 v[56:59], v[136:139], v[184:187], v[56:59]
	v_mfma_f32_16x16x32_bf16 v[52:55], v[144:147], v[184:187], v[52:55]
	v_mfma_f32_16x16x32_bf16 v[52:55], v[148:151], v[188:191], v[52:55]
	v_mfma_f32_16x16x32_bf16 v[48:51], v[156:159], v[188:191], v[48:51]
	v_mfma_f32_16x16x32_bf16 v[48:51], v[152:155], v[184:187], v[48:51]
	v_mfma_f32_16x16x32_bf16 v[32:35], v[152:155], v[192:195], v[32:35]
	v_mfma_f32_16x16x32_bf16 v[32:35], v[156:159], v[196:199], v[32:35]
	v_mfma_f32_16x16x32_bf16 v[36:39], v[148:151], v[196:199], v[36:39]
	v_mfma_f32_16x16x32_bf16 v[36:39], v[144:147], v[192:195], v[36:39]
	v_mfma_f32_16x16x32_bf16 v[40:43], v[136:139], v[192:195], v[40:43]
	v_mfma_f32_16x16x32_bf16 v[40:43], v[140:143], v[196:199], v[40:43]
	v_mfma_f32_16x16x32_bf16 v[44:47], v[132:135], v[196:199], v[44:47]
	v_mfma_f32_16x16x32_bf16 v[44:47], v[128:131], v[192:195], v[44:47]
	v_mfma_f32_16x16x32_bf16 v[28:31], v[128:131], v[200:203], v[28:31]
	v_mfma_f32_16x16x32_bf16 v[28:31], v[132:135], v[204:207], v[28:31]
	v_mfma_f32_16x16x32_bf16 v[24:27], v[140:143], v[204:207], v[24:27]
	v_mfma_f32_16x16x32_bf16 v[24:27], v[136:139], v[200:203], v[24:27]
	v_mfma_f32_16x16x32_bf16 v[20:23], v[144:147], v[200:203], v[20:23]
	v_mfma_f32_16x16x32_bf16 v[20:23], v[148:151], v[204:207], v[20:23]
	v_mfma_f32_16x16x32_bf16 v[16:19], v[156:159], v[204:207], v[16:19]
	v_mfma_f32_16x16x32_bf16 v[16:19], v[152:155], v[200:203], v[16:19]
	v_mfma_f32_16x16x32_bf16 v[0:3], v[152:155], v[208:211], v[0:3]
	v_mfma_f32_16x16x32_bf16 v[0:3], v[156:159], v[212:215], v[0:3]
	v_mfma_f32_16x16x32_bf16 v[4:7], v[148:151], v[212:215], v[4:7]
	v_mfma_f32_16x16x32_bf16 v[4:7], v[144:147], v[208:211], v[4:7]
	v_mfma_f32_16x16x32_bf16 v[8:11], v[136:139], v[208:211], v[8:11]
	v_mfma_f32_16x16x32_bf16 v[8:11], v[140:143], v[212:215], v[8:11]
	v_mfma_f32_16x16x32_bf16 v[12:15], v[132:135], v[212:215], v[12:15]
	v_mfma_f32_16x16x32_bf16 v[12:15], v[128:131], v[208:211], v[12:15]
	s_setprio 1
	s_barrier
	s_add_i32 s54, 0, 0x18000
	s_add_i32 s55, 0, 0x1c000
	v_add_u32_e32 v140, s54, v221
	v_add_u32_e32 v156, s55, v221
	ds_read_b128 v[128:131], v140
	ds_read_b128 v[132:135], v140 offset:1024
	ds_read_b128 v[136:139], v140 offset:2048
	ds_read_b128 v[140:143], v140 offset:3072
	ds_read_b128 v[144:147], v156
	ds_read_b128 v[148:151], v156 offset:1024
	ds_read_b128 v[152:155], v156 offset:2048
	ds_read_b128 v[156:159], v156 offset:3072
	s_add_u32 s50, s50, s10
	s_addc_u32 s51, s51, s11
	s_mov_b32 m0, s73
	v_lshl_add_u64 v[236:237], s[50:51], 0, v[164:165]
	ds_read_b128 v[184:187], v224 offset:32768
	ds_read_b128 v[188:191], v224 offset:33792
	ds_read_b128 v[192:195], v224 offset:34816
	ds_read_b128 v[196:199], v224 offset:35840
	ds_read_b128 v[200:203], v224 offset:36864
	ds_read_b128 v[204:207], v224 offset:37888
	ds_read_b128 v[208:211], v224 offset:38912
	ds_read_b128 v[212:215], v224 offset:39936
	global_load_lds_dwordx4 v[236:237], off
	v_lshl_add_u64 v[236:237], s[50:51], 0, v[168:169]
	s_mov_b32 m0, s74
	s_nop 0
	global_load_lds_dwordx4 v[236:237], off
	s_waitcnt vmcnt(8)
	s_waitcnt lgkmcnt(0)
	s_barrier
	s_waitcnt lgkmcnt(0)
	s_setprio 0
	v_mfma_f32_16x16x32_bf16 v[124:127], v[128:131], v[184:187], v[124:127]
	v_mfma_f32_16x16x32_bf16 v[124:127], v[132:135], v[188:191], v[124:127]
	v_mfma_f32_16x16x32_bf16 v[120:123], v[140:143], v[188:191], v[120:123]
	v_mfma_f32_16x16x32_bf16 v[120:123], v[136:139], v[184:187], v[120:123]
	v_mfma_f32_16x16x32_bf16 v[116:119], v[144:147], v[184:187], v[116:119]
	v_mfma_f32_16x16x32_bf16 v[116:119], v[148:151], v[188:191], v[116:119]
	v_mfma_f32_16x16x32_bf16 v[112:115], v[156:159], v[188:191], v[112:115]
	v_mfma_f32_16x16x32_bf16 v[112:115], v[152:155], v[184:187], v[112:115]
	v_mfma_f32_16x16x32_bf16 v[96:99], v[152:155], v[192:195], v[96:99]
	v_mfma_f32_16x16x32_bf16 v[96:99], v[156:159], v[196:199], v[96:99]
	v_mfma_f32_16x16x32_bf16 v[100:103], v[148:151], v[196:199], v[100:103]
	v_mfma_f32_16x16x32_bf16 v[100:103], v[144:147], v[192:195], v[100:103]
	v_mfma_f32_16x16x32_bf16 v[104:107], v[136:139], v[192:195], v[104:107]
	v_mfma_f32_16x16x32_bf16 v[104:107], v[140:143], v[196:199], v[104:107]
	v_mfma_f32_16x16x32_bf16 v[108:111], v[132:135], v[196:199], v[108:111]
	v_mfma_f32_16x16x32_bf16 v[108:111], v[128:131], v[192:195], v[108:111]
	v_mfma_f32_16x16x32_bf16 v[92:95], v[128:131], v[200:203], v[92:95]
	v_mfma_f32_16x16x32_bf16 v[92:95], v[132:135], v[204:207], v[92:95]
	v_mfma_f32_16x16x32_bf16 v[88:91], v[140:143], v[204:207], v[88:91]
	v_mfma_f32_16x16x32_bf16 v[88:91], v[136:139], v[200:203], v[88:91]
	v_mfma_f32_16x16x32_bf16 v[84:87], v[144:147], v[200:203], v[84:87]
	v_mfma_f32_16x16x32_bf16 v[84:87], v[148:151], v[204:207], v[84:87]
	v_mfma_f32_16x16x32_bf16 v[80:83], v[156:159], v[204:207], v[80:83]
	v_mfma_f32_16x16x32_bf16 v[80:83], v[152:155], v[200:203], v[80:83]
	v_mfma_f32_16x16x32_bf16 v[64:67], v[152:155], v[208:211], v[64:67]
	v_mfma_f32_16x16x32_bf16 v[64:67], v[156:159], v[212:215], v[64:67]
	v_mfma_f32_16x16x32_bf16 v[68:71], v[148:151], v[212:215], v[68:71]
	v_mfma_f32_16x16x32_bf16 v[68:71], v[144:147], v[208:211], v[68:71]
	v_mfma_f32_16x16x32_bf16 v[72:75], v[136:139], v[208:211], v[72:75]
	v_mfma_f32_16x16x32_bf16 v[72:75], v[140:143], v[212:215], v[72:75]
	v_mfma_f32_16x16x32_bf16 v[76:79], v[132:135], v[212:215], v[76:79]
	v_mfma_f32_16x16x32_bf16 v[76:79], v[128:131], v[208:211], v[76:79]
	s_setprio 1
	s_barrier
	s_add_i32 s50, s54, s70
	v_lshl_add_u64 v[160:161], v[160:161], 0, s[36:37]
	s_mov_b32 m0, s50
	ds_read_b128 v[184:187], v224 offset:49152
	ds_read_b128 v[188:191], v224 offset:50176
	ds_read_b128 v[192:195], v224 offset:51200
	ds_read_b128 v[196:199], v224 offset:52224
	ds_read_b128 v[200:203], v224 offset:53248
	ds_read_b128 v[204:207], v224 offset:54272
	ds_read_b128 v[208:211], v224 offset:55296
	ds_read_b128 v[212:215], v224 offset:56320
	global_load_lds_dwordx4 v[160:161], off
	v_lshl_add_u64 v[160:161], v[216:217], 0, s[36:37]
	s_add_i32 m0, s50, 0x2000
	s_add_i32 s50, s55, s70
	global_load_lds_dwordx4 v[160:161], off
	v_lshl_add_u64 v[160:161], v[218:219], 0, s[36:37]
	s_mov_b32 m0, s50
	s_nop 0
	global_load_lds_dwordx4 v[160:161], off
	v_lshl_add_u64 v[160:161], v[230:231], 0, s[36:37]
	s_add_i32 m0, s50, 0x2000
	s_nop 0
	global_load_lds_dwordx4 v[160:161], off
	v_lshl_add_u64 v[160:161], v[232:233], 0, s[36:37]
	s_mov_b32 m0, s76
	s_nop 0
	global_load_lds_dwordx4 v[160:161], off
	v_lshl_add_u64 v[160:161], v[234:235], 0, s[36:37]
	s_mov_b32 m0, s77
	s_nop 0
	global_load_lds_dwordx4 v[160:161], off
	s_waitcnt vmcnt(8)
	s_waitcnt lgkmcnt(0)
	s_barrier
	s_waitcnt lgkmcnt(0)
	s_setprio 0
	v_mfma_f32_16x16x32_bf16 v[60:63], v[128:131], v[184:187], v[60:63]
	v_mfma_f32_16x16x32_bf16 v[60:63], v[132:135], v[188:191], v[60:63]
	v_mfma_f32_16x16x32_bf16 v[56:59], v[140:143], v[188:191], v[56:59]
	v_mfma_f32_16x16x32_bf16 v[56:59], v[136:139], v[184:187], v[56:59]
	v_mfma_f32_16x16x32_bf16 v[52:55], v[144:147], v[184:187], v[52:55]
	v_mfma_f32_16x16x32_bf16 v[52:55], v[148:151], v[188:191], v[52:55]
	v_mfma_f32_16x16x32_bf16 v[48:51], v[156:159], v[188:191], v[48:51]
	v_mfma_f32_16x16x32_bf16 v[48:51], v[152:155], v[184:187], v[48:51]
	v_mfma_f32_16x16x32_bf16 v[32:35], v[152:155], v[192:195], v[32:35]
	v_mfma_f32_16x16x32_bf16 v[32:35], v[156:159], v[196:199], v[32:35]
	v_mfma_f32_16x16x32_bf16 v[36:39], v[148:151], v[196:199], v[36:39]
	v_mfma_f32_16x16x32_bf16 v[36:39], v[144:147], v[192:195], v[36:39]
	v_mfma_f32_16x16x32_bf16 v[40:43], v[136:139], v[192:195], v[40:43]
	v_mfma_f32_16x16x32_bf16 v[40:43], v[140:143], v[196:199], v[40:43]
	v_mfma_f32_16x16x32_bf16 v[44:47], v[132:135], v[196:199], v[44:47]
	v_mfma_f32_16x16x32_bf16 v[44:47], v[128:131], v[192:195], v[44:47]
	v_mfma_f32_16x16x32_bf16 v[28:31], v[128:131], v[200:203], v[28:31]
	v_mfma_f32_16x16x32_bf16 v[28:31], v[132:135], v[204:207], v[28:31]
	v_mfma_f32_16x16x32_bf16 v[24:27], v[140:143], v[204:207], v[24:27]
	v_mfma_f32_16x16x32_bf16 v[24:27], v[136:139], v[200:203], v[24:27]
	v_mfma_f32_16x16x32_bf16 v[20:23], v[144:147], v[200:203], v[20:23]
	v_mfma_f32_16x16x32_bf16 v[20:23], v[148:151], v[204:207], v[20:23]
	v_mfma_f32_16x16x32_bf16 v[16:19], v[156:159], v[204:207], v[16:19]
	v_mfma_f32_16x16x32_bf16 v[16:19], v[152:155], v[200:203], v[16:19]
	v_mfma_f32_16x16x32_bf16 v[0:3], v[152:155], v[208:211], v[0:3]
	v_mfma_f32_16x16x32_bf16 v[0:3], v[156:159], v[212:215], v[0:3]
	v_mfma_f32_16x16x32_bf16 v[4:7], v[148:151], v[212:215], v[4:7]
	v_mfma_f32_16x16x32_bf16 v[4:7], v[144:147], v[208:211], v[4:7]
	v_mfma_f32_16x16x32_bf16 v[8:11], v[136:139], v[208:211], v[8:11]
	v_mfma_f32_16x16x32_bf16 v[8:11], v[140:143], v[212:215], v[8:11]
	v_mfma_f32_16x16x32_bf16 v[12:15], v[132:135], v[212:215], v[12:15]
	v_mfma_f32_16x16x32_bf16 v[12:15], v[128:131], v[208:211], v[12:15]
	s_setprio 1
	s_barrier
	s_add_u32 s0, s0, 0x100
	s_addc_u32 s1, s1, 0
	s_add_u32 s33, s33, 0x100
	s_addc_u32 s52, s52, 0
	s_cmp_ge_i32 s53, s75
	s_mov_b32 s50, s53
	s_cbranch_scc0 .LBB0_323

.LBB0_592:
	ds_read_b128 v[144:147], v157
	ds_read_b128 v[148:151], v157 offset:1024
	ds_read_b128 v[164:167], v157 offset:2048
	ds_read_b128 v[168:171], v157 offset:3072
	ds_read_b128 v[172:175], v158
	ds_read_b128 v[176:179], v158 offset:1024
	ds_read_b128 v[180:183], v158 offset:2048
	ds_read_b128 v[184:187], v158 offset:3072
	s_add_i32 s64, s34, 2
	s_add_u32 s65, s30, 0x80
	s_addc_u32 s35, s31, 0
	s_cmp_eq_u32 s49, s34
	s_cselect_b32 s34, s2, s65
	s_cselect_b32 s35, s3, s35
	s_cselect_b32 s67, s29, s63
	s_cselect_b32 s66, s28, s62
	v_lshl_add_u64 v[152:153], s[30:31], 0, v[136:137]
	s_add_i32 m0, s41, 0xc000
	ds_read_b128 v[188:191], v159
	ds_read_b128 v[192:195], v159 offset:1024
	ds_read_b128 v[196:199], v159 offset:2048
	ds_read_b128 v[200:203], v159 offset:3072
	ds_read_b128 v[204:207], v159 offset:4096
	ds_read_b128 v[208:211], v159 offset:5120
	ds_read_b128 v[212:215], v159 offset:6144
	ds_read_b128 v[216:219], v159 offset:7168
	global_load_lds_dwordx4 v[152:153], off
	v_lshl_add_u64 v[152:153], s[30:31], 0, v[138:139]
	s_add_i32 m0, s41, 0xe000
	s_nop 0
	global_load_lds_dwordx4 v[152:153], off
	s_waitcnt vmcnt(8)
	s_waitcnt lgkmcnt(0)
	s_barrier
	s_waitcnt lgkmcnt(0)
	s_setprio 0
	v_mfma_f32_16x16x32_bf16 v[120:123], v[144:147], v[188:191], v[120:123]
	v_mfma_f32_16x16x32_bf16 v[120:123], v[148:151], v[192:195], v[120:123]
	v_mfma_f32_16x16x32_bf16 v[124:127], v[168:171], v[192:195], v[124:127]
	v_mfma_f32_16x16x32_bf16 v[124:127], v[164:167], v[188:191], v[124:127]
	v_mfma_f32_16x16x32_bf16 v[116:119], v[172:175], v[188:191], v[116:119]
	v_mfma_f32_16x16x32_bf16 v[116:119], v[176:179], v[192:195], v[116:119]
	v_mfma_f32_16x16x32_bf16 v[112:115], v[184:187], v[192:195], v[112:115]
	v_mfma_f32_16x16x32_bf16 v[112:115], v[180:183], v[188:191], v[112:115]
	v_mfma_f32_16x16x32_bf16 v[96:99], v[180:183], v[196:199], v[96:99]
	v_mfma_f32_16x16x32_bf16 v[96:99], v[184:187], v[200:203], v[96:99]
	v_mfma_f32_16x16x32_bf16 v[100:103], v[176:179], v[200:203], v[100:103]
	v_mfma_f32_16x16x32_bf16 v[100:103], v[172:175], v[196:199], v[100:103]
	v_mfma_f32_16x16x32_bf16 v[104:107], v[164:167], v[196:199], v[104:107]
	v_mfma_f32_16x16x32_bf16 v[104:107], v[168:171], v[200:203], v[104:107]
	v_mfma_f32_16x16x32_bf16 v[108:111], v[148:151], v[200:203], v[108:111]
	v_mfma_f32_16x16x32_bf16 v[108:111], v[144:147], v[196:199], v[108:111]
	v_mfma_f32_16x16x32_bf16 v[92:95], v[144:147], v[204:207], v[92:95]
	v_mfma_f32_16x16x32_bf16 v[92:95], v[148:151], v[208:211], v[92:95]
	v_mfma_f32_16x16x32_bf16 v[88:91], v[168:171], v[208:211], v[88:91]
	v_mfma_f32_16x16x32_bf16 v[88:91], v[164:167], v[204:207], v[88:91]
	v_mfma_f32_16x16x32_bf16 v[84:87], v[172:175], v[204:207], v[84:87]
	v_mfma_f32_16x16x32_bf16 v[84:87], v[176:179], v[208:211], v[84:87]
	v_mfma_f32_16x16x32_bf16 v[80:83], v[184:187], v[208:211], v[80:83]
	v_mfma_f32_16x16x32_bf16 v[80:83], v[180:183], v[204:207], v[80:83]
	v_mfma_f32_16x16x32_bf16 v[64:67], v[180:183], v[212:215], v[64:67]
	v_mfma_f32_16x16x32_bf16 v[64:67], v[184:187], v[216:219], v[64:67]
	v_mfma_f32_16x16x32_bf16 v[68:71], v[176:179], v[216:219], v[68:71]
	v_mfma_f32_16x16x32_bf16 v[68:71], v[172:175], v[212:215], v[68:71]
	v_mfma_f32_16x16x32_bf16 v[72:75], v[164:167], v[212:215], v[72:75]
	v_mfma_f32_16x16x32_bf16 v[72:75], v[168:171], v[216:219], v[72:75]
	v_mfma_f32_16x16x32_bf16 v[76:79], v[148:151], v[216:219], v[76:79]
	v_mfma_f32_16x16x32_bf16 v[76:79], v[144:147], v[212:215], v[76:79]
	s_setprio 1
	s_barrier
	s_add_i32 s65, s52, s40
	v_lshl_add_u64 v[152:153], s[66:67], 0, v[130:131]
	s_mov_b32 m0, s65
	ds_read_b128 v[188:191], v159 offset:16384
	ds_read_b128 v[192:195], v159 offset:17408
	ds_read_b128 v[196:199], v159 offset:18432
	ds_read_b128 v[200:203], v159 offset:19456
	ds_read_b128 v[204:207], v159 offset:20480
	ds_read_b128 v[208:211], v159 offset:21504
	ds_read_b128 v[212:215], v159 offset:22528
	ds_read_b128 v[216:219], v159 offset:23552
	global_load_lds_dwordx4 v[152:153], off
	s_add_i32 m0, s65, 0x2000
	v_lshl_add_u64 v[160:161], s[66:67], 0, v[134:135]
	s_add_u32 s66, s66, s8
	s_addc_u32 s67, s67, s9
	s_add_i32 s65, s53, s40
	global_load_lds_dwordx4 v[160:161], off
	v_lshl_add_u64 v[222:223], s[66:67], 0, v[130:131]
	s_mov_b32 m0, s65
	v_lshl_add_u64 v[224:225], s[66:67], 0, v[134:135]
	global_load_lds_dwordx4 v[222:223], off
	s_add_i32 m0, s65, 0x2000
	v_lshl_add_u64 v[226:227], s[34:35], 0, v[128:129]
	global_load_lds_dwordx4 v[224:225], off
	s_mov_b32 m0, s41
	v_lshl_add_u64 v[228:229], s[34:35], 0, v[132:133]
	global_load_lds_dwordx4 v[226:227], off
	s_mov_b32 m0, s42
	s_nop 0
	global_load_lds_dwordx4 v[228:229], off
	s_waitcnt vmcnt(8)
	s_waitcnt lgkmcnt(0)
	s_barrier
	s_waitcnt lgkmcnt(0)
	s_setprio 0
	v_mfma_f32_16x16x32_bf16 v[60:63], v[144:147], v[188:191], v[60:63]
	v_mfma_f32_16x16x32_bf16 v[60:63], v[148:151], v[192:195], v[60:63]
	v_mfma_f32_16x16x32_bf16 v[56:59], v[168:171], v[192:195], v[56:59]
	v_mfma_f32_16x16x32_bf16 v[56:59], v[164:167], v[188:191], v[56:59]
	v_mfma_f32_16x16x32_bf16 v[52:55], v[172:175], v[188:191], v[52:55]
	v_mfma_f32_16x16x32_bf16 v[52:55], v[176:179], v[192:195], v[52:55]
	v_mfma_f32_16x16x32_bf16 v[48:51], v[184:187], v[192:195], v[48:51]
	v_mfma_f32_16x16x32_bf16 v[48:51], v[180:183], v[188:191], v[48:51]
	v_mfma_f32_16x16x32_bf16 v[32:35], v[180:183], v[196:199], v[32:35]
	v_mfma_f32_16x16x32_bf16 v[32:35], v[184:187], v[200:203], v[32:35]
	v_mfma_f32_16x16x32_bf16 v[36:39], v[176:179], v[200:203], v[36:39]
	v_mfma_f32_16x16x32_bf16 v[36:39], v[172:175], v[196:199], v[36:39]
	v_mfma_f32_16x16x32_bf16 v[40:43], v[164:167], v[196:199], v[40:43]
	v_mfma_f32_16x16x32_bf16 v[40:43], v[168:171], v[200:203], v[40:43]
	v_mfma_f32_16x16x32_bf16 v[44:47], v[148:151], v[200:203], v[44:47]
	v_mfma_f32_16x16x32_bf16 v[44:47], v[144:147], v[196:199], v[44:47]
	v_mfma_f32_16x16x32_bf16 v[28:31], v[144:147], v[204:207], v[28:31]
	v_mfma_f32_16x16x32_bf16 v[28:31], v[148:151], v[208:211], v[28:31]
	v_mfma_f32_16x16x32_bf16 v[24:27], v[168:171], v[208:211], v[24:27]
	v_mfma_f32_16x16x32_bf16 v[24:27], v[164:167], v[204:207], v[24:27]
	v_mfma_f32_16x16x32_bf16 v[20:23], v[172:175], v[204:207], v[20:23]
	v_mfma_f32_16x16x32_bf16 v[20:23], v[176:179], v[208:211], v[20:23]
	v_mfma_f32_16x16x32_bf16 v[16:19], v[184:187], v[208:211], v[16:19]
	v_mfma_f32_16x16x32_bf16 v[16:19], v[180:183], v[204:207], v[16:19]
	v_mfma_f32_16x16x32_bf16 v[0:3], v[180:183], v[212:215], v[0:3]
	v_mfma_f32_16x16x32_bf16 v[0:3], v[184:187], v[216:219], v[0:3]
	v_mfma_f32_16x16x32_bf16 v[4:7], v[176:179], v[216:219], v[4:7]
	v_mfma_f32_16x16x32_bf16 v[4:7], v[172:175], v[212:215], v[4:7]
	v_mfma_f32_16x16x32_bf16 v[8:11], v[164:167], v[212:215], v[8:11]
	v_mfma_f32_16x16x32_bf16 v[8:11], v[168:171], v[216:219], v[8:11]
	v_mfma_f32_16x16x32_bf16 v[12:15], v[148:151], v[216:219], v[12:15]
	v_mfma_f32_16x16x32_bf16 v[12:15], v[144:147], v[212:215], v[12:15]
	s_setprio 1
	s_barrier
	s_add_i32 s65, 0, 0x18000
	s_add_i32 s66, 0, 0x1c000
	v_add_u32_e32 v168, s65, v155
	v_add_u32_e32 v184, s66, v155
	ds_read_b128 v[144:147], v168
	ds_read_b128 v[148:151], v168 offset:1024
	ds_read_b128 v[164:167], v168 offset:2048
	ds_read_b128 v[168:171], v168 offset:3072
	ds_read_b128 v[172:175], v184
	ds_read_b128 v[176:179], v184 offset:1024
	ds_read_b128 v[180:183], v184 offset:2048
	ds_read_b128 v[184:187], v184 offset:3072
	s_add_u32 s34, s34, s8
	s_addc_u32 s35, s35, s9
	s_mov_b32 m0, s43
	v_lshl_add_u64 v[230:231], s[34:35], 0, v[128:129]
	ds_read_b128 v[188:191], v159 offset:32768
	ds_read_b128 v[192:195], v159 offset:33792
	ds_read_b128 v[196:199], v159 offset:34816
	ds_read_b128 v[200:203], v159 offset:35840
	ds_read_b128 v[204:207], v159 offset:36864
	ds_read_b128 v[208:211], v159 offset:37888
	ds_read_b128 v[212:215], v159 offset:38912
	ds_read_b128 v[216:219], v159 offset:39936
	global_load_lds_dwordx4 v[230:231], off
	v_lshl_add_u64 v[230:231], s[34:35], 0, v[132:133]
	s_mov_b32 m0, s44
	s_nop 0
	global_load_lds_dwordx4 v[230:231], off
	s_waitcnt vmcnt(8)
	s_waitcnt lgkmcnt(0)
	s_barrier
	s_waitcnt lgkmcnt(0)
	s_setprio 0
	v_mfma_f32_16x16x32_bf16 v[120:123], v[144:147], v[188:191], v[120:123]
	v_mfma_f32_16x16x32_bf16 v[120:123], v[148:151], v[192:195], v[120:123]
	v_mfma_f32_16x16x32_bf16 v[124:127], v[168:171], v[192:195], v[124:127]
	v_mfma_f32_16x16x32_bf16 v[124:127], v[164:167], v[188:191], v[124:127]
	v_mfma_f32_16x16x32_bf16 v[116:119], v[172:175], v[188:191], v[116:119]
	v_mfma_f32_16x16x32_bf16 v[116:119], v[176:179], v[192:195], v[116:119]
	v_mfma_f32_16x16x32_bf16 v[112:115], v[184:187], v[192:195], v[112:115]
	v_mfma_f32_16x16x32_bf16 v[112:115], v[180:183], v[188:191], v[112:115]
	v_mfma_f32_16x16x32_bf16 v[96:99], v[180:183], v[196:199], v[96:99]
	v_mfma_f32_16x16x32_bf16 v[96:99], v[184:187], v[200:203], v[96:99]
	v_mfma_f32_16x16x32_bf16 v[100:103], v[176:179], v[200:203], v[100:103]
	v_mfma_f32_16x16x32_bf16 v[100:103], v[172:175], v[196:199], v[100:103]
	v_mfma_f32_16x16x32_bf16 v[104:107], v[164:167], v[196:199], v[104:107]
	v_mfma_f32_16x16x32_bf16 v[104:107], v[168:171], v[200:203], v[104:107]
	v_mfma_f32_16x16x32_bf16 v[108:111], v[148:151], v[200:203], v[108:111]
	v_mfma_f32_16x16x32_bf16 v[108:111], v[144:147], v[196:199], v[108:111]
	v_mfma_f32_16x16x32_bf16 v[92:95], v[144:147], v[204:207], v[92:95]
	v_mfma_f32_16x16x32_bf16 v[92:95], v[148:151], v[208:211], v[92:95]
	v_mfma_f32_16x16x32_bf16 v[88:91], v[168:171], v[208:211], v[88:91]
	v_mfma_f32_16x16x32_bf16 v[88:91], v[164:167], v[204:207], v[88:91]
	v_mfma_f32_16x16x32_bf16 v[84:87], v[172:175], v[204:207], v[84:87]
	v_mfma_f32_16x16x32_bf16 v[84:87], v[176:179], v[208:211], v[84:87]
	v_mfma_f32_16x16x32_bf16 v[80:83], v[184:187], v[208:211], v[80:83]
	v_mfma_f32_16x16x32_bf16 v[80:83], v[180:183], v[204:207], v[80:83]
	v_mfma_f32_16x16x32_bf16 v[64:67], v[180:183], v[212:215], v[64:67]
	v_mfma_f32_16x16x32_bf16 v[64:67], v[184:187], v[216:219], v[64:67]
	v_mfma_f32_16x16x32_bf16 v[68:71], v[176:179], v[216:219], v[68:71]
	v_mfma_f32_16x16x32_bf16 v[68:71], v[172:175], v[212:215], v[68:71]
	v_mfma_f32_16x16x32_bf16 v[72:75], v[164:167], v[212:215], v[72:75]
	v_mfma_f32_16x16x32_bf16 v[72:75], v[168:171], v[216:219], v[72:75]
	v_mfma_f32_16x16x32_bf16 v[76:79], v[148:151], v[216:219], v[76:79]
	v_mfma_f32_16x16x32_bf16 v[76:79], v[144:147], v[212:215], v[76:79]
	s_setprio 1
	s_barrier
	s_add_i32 s34, s65, s40
	v_lshl_add_u64 v[152:153], v[152:153], 0, s[14:15]
	s_mov_b32 m0, s34
	ds_read_b128 v[188:191], v159 offset:49152
	ds_read_b128 v[192:195], v159 offset:50176
	ds_read_b128 v[196:199], v159 offset:51200
	ds_read_b128 v[200:203], v159 offset:52224
	ds_read_b128 v[204:207], v159 offset:53248
	ds_read_b128 v[208:211], v159 offset:54272
	ds_read_b128 v[212:215], v159 offset:55296
	ds_read_b128 v[216:219], v159 offset:56320
	global_load_lds_dwordx4 v[152:153], off
	v_lshl_add_u64 v[152:153], v[160:161], 0, s[14:15]
	s_add_i32 m0, s34, 0x2000
	s_add_i32 s34, s66, s40
	global_load_lds_dwordx4 v[152:153], off
	v_lshl_add_u64 v[152:153], v[222:223], 0, s[14:15]
	s_mov_b32 m0, s34
	s_nop 0
	global_load_lds_dwordx4 v[152:153], off
	v_lshl_add_u64 v[152:153], v[224:225], 0, s[14:15]
	s_add_i32 m0, s34, 0x2000
	s_nop 0
	global_load_lds_dwordx4 v[152:153], off
	v_lshl_add_u64 v[152:153], v[226:227], 0, s[14:15]
	s_mov_b32 m0, s46
	s_nop 0
	global_load_lds_dwordx4 v[152:153], off
	v_lshl_add_u64 v[152:153], v[228:229], 0, s[14:15]
	s_mov_b32 m0, s47
	s_nop 0
	global_load_lds_dwordx4 v[152:153], off
	s_waitcnt vmcnt(8)
	s_waitcnt lgkmcnt(0)
	s_barrier
	s_waitcnt lgkmcnt(0)
	s_setprio 0
	v_mfma_f32_16x16x32_bf16 v[60:63], v[144:147], v[188:191], v[60:63]
	v_mfma_f32_16x16x32_bf16 v[60:63], v[148:151], v[192:195], v[60:63]
	v_mfma_f32_16x16x32_bf16 v[56:59], v[168:171], v[192:195], v[56:59]
	v_mfma_f32_16x16x32_bf16 v[56:59], v[164:167], v[188:191], v[56:59]
	v_mfma_f32_16x16x32_bf16 v[52:55], v[172:175], v[188:191], v[52:55]
	v_mfma_f32_16x16x32_bf16 v[52:55], v[176:179], v[192:195], v[52:55]
	v_mfma_f32_16x16x32_bf16 v[48:51], v[184:187], v[192:195], v[48:51]
	v_mfma_f32_16x16x32_bf16 v[48:51], v[180:183], v[188:191], v[48:51]
	v_mfma_f32_16x16x32_bf16 v[32:35], v[180:183], v[196:199], v[32:35]
	v_mfma_f32_16x16x32_bf16 v[32:35], v[184:187], v[200:203], v[32:35]
	v_mfma_f32_16x16x32_bf16 v[36:39], v[176:179], v[200:203], v[36:39]
	v_mfma_f32_16x16x32_bf16 v[36:39], v[172:175], v[196:199], v[36:39]
	v_mfma_f32_16x16x32_bf16 v[40:43], v[164:167], v[196:199], v[40:43]
	v_mfma_f32_16x16x32_bf16 v[40:43], v[168:171], v[200:203], v[40:43]
	v_mfma_f32_16x16x32_bf16 v[44:47], v[148:151], v[200:203], v[44:47]
	v_mfma_f32_16x16x32_bf16 v[44:47], v[144:147], v[196:199], v[44:47]
	v_mfma_f32_16x16x32_bf16 v[28:31], v[144:147], v[204:207], v[28:31]
	v_mfma_f32_16x16x32_bf16 v[28:31], v[148:151], v[208:211], v[28:31]
	v_mfma_f32_16x16x32_bf16 v[24:27], v[168:171], v[208:211], v[24:27]
	v_mfma_f32_16x16x32_bf16 v[24:27], v[164:167], v[204:207], v[24:27]
	v_mfma_f32_16x16x32_bf16 v[20:23], v[172:175], v[204:207], v[20:23]
	v_mfma_f32_16x16x32_bf16 v[20:23], v[176:179], v[208:211], v[20:23]
	v_mfma_f32_16x16x32_bf16 v[16:19], v[184:187], v[208:211], v[16:19]
	v_mfma_f32_16x16x32_bf16 v[16:19], v[180:183], v[204:207], v[16:19]
	v_mfma_f32_16x16x32_bf16 v[0:3], v[180:183], v[212:215], v[0:3]
	v_mfma_f32_16x16x32_bf16 v[0:3], v[184:187], v[216:219], v[0:3]
	v_mfma_f32_16x16x32_bf16 v[4:7], v[176:179], v[216:219], v[4:7]
	v_mfma_f32_16x16x32_bf16 v[4:7], v[172:175], v[212:215], v[4:7]
	v_mfma_f32_16x16x32_bf16 v[8:11], v[164:167], v[212:215], v[8:11]
	v_mfma_f32_16x16x32_bf16 v[8:11], v[168:171], v[216:219], v[8:11]
	v_mfma_f32_16x16x32_bf16 v[12:15], v[148:151], v[216:219], v[12:15]
	v_mfma_f32_16x16x32_bf16 v[12:15], v[144:147], v[212:215], v[12:15]
	s_setprio 1
	s_barrier
	s_add_u32 s30, s30, 0x100
	s_addc_u32 s31, s31, 0
	s_add_u32 s62, s62, 0x100
	s_addc_u32 s63, s63, 0
	s_cmp_ge_i32 s64, s48
	s_mov_b32 s34, s64
	s_cbranch_scc0 .LBB0_592

.LBB0_763:
	ds_read_b128 v[128:131], v181
	ds_read_b128 v[132:135], v181 offset:1024
	ds_read_b128 v[136:139], v181 offset:2048
	ds_read_b128 v[140:143], v181 offset:3072
	ds_read_b128 v[144:147], v182
	ds_read_b128 v[148:151], v182 offset:1024
	ds_read_b128 v[168:171], v182 offset:2048
	ds_read_b128 v[172:175], v182 offset:3072
	s_add_i32 s54, s26, 2
	s_add_u32 s55, s24, 0x80
	s_addc_u32 s27, s25, 0
	s_cmp_eq_u32 s43, s26
	s_cselect_b32 s26, s2, s55
	s_cselect_b32 s27, s3, s27
	s_cselect_b32 s61, s23, s53
	s_cselect_b32 s60, s22, s52
	v_lshl_add_u64 v[176:177], s[24:25], 0, v[160:161]
	s_add_i32 m0, s35, 0xc000
	ds_read_b128 v[184:187], v183
	ds_read_b128 v[188:191], v183 offset:1024
	ds_read_b128 v[192:195], v183 offset:2048
	ds_read_b128 v[196:199], v183 offset:3072
	ds_read_b128 v[200:203], v183 offset:4096
	ds_read_b128 v[204:207], v183 offset:5120
	ds_read_b128 v[208:211], v183 offset:6144
	ds_read_b128 v[212:215], v183 offset:7168
	global_load_lds_dwordx4 v[176:177], off
	v_lshl_add_u64 v[176:177], s[24:25], 0, v[162:163]
	s_add_i32 m0, s35, 0xe000
	s_nop 0
	global_load_lds_dwordx4 v[176:177], off
	s_waitcnt vmcnt(8)
	s_waitcnt lgkmcnt(0)
	s_barrier
	s_waitcnt lgkmcnt(0)
	s_setprio 0
	v_mfma_f32_16x16x32_bf16 v[120:123], v[128:131], v[184:187], v[120:123]
	v_mfma_f32_16x16x32_bf16 v[120:123], v[132:135], v[188:191], v[120:123]
	v_mfma_f32_16x16x32_bf16 v[124:127], v[140:143], v[188:191], v[124:127]
	v_mfma_f32_16x16x32_bf16 v[124:127], v[136:139], v[184:187], v[124:127]
	v_mfma_f32_16x16x32_bf16 v[116:119], v[144:147], v[184:187], v[116:119]
	v_mfma_f32_16x16x32_bf16 v[116:119], v[148:151], v[188:191], v[116:119]
	v_mfma_f32_16x16x32_bf16 v[112:115], v[172:175], v[188:191], v[112:115]
	v_mfma_f32_16x16x32_bf16 v[112:115], v[168:171], v[184:187], v[112:115]
	v_mfma_f32_16x16x32_bf16 v[96:99], v[168:171], v[192:195], v[96:99]
	v_mfma_f32_16x16x32_bf16 v[96:99], v[172:175], v[196:199], v[96:99]
	v_mfma_f32_16x16x32_bf16 v[100:103], v[148:151], v[196:199], v[100:103]
	v_mfma_f32_16x16x32_bf16 v[100:103], v[144:147], v[192:195], v[100:103]
	v_mfma_f32_16x16x32_bf16 v[104:107], v[136:139], v[192:195], v[104:107]
	v_mfma_f32_16x16x32_bf16 v[104:107], v[140:143], v[196:199], v[104:107]
	v_mfma_f32_16x16x32_bf16 v[108:111], v[132:135], v[196:199], v[108:111]
	v_mfma_f32_16x16x32_bf16 v[108:111], v[128:131], v[192:195], v[108:111]
	v_mfma_f32_16x16x32_bf16 v[92:95], v[128:131], v[200:203], v[92:95]
	v_mfma_f32_16x16x32_bf16 v[92:95], v[132:135], v[204:207], v[92:95]
	v_mfma_f32_16x16x32_bf16 v[88:91], v[140:143], v[204:207], v[88:91]
	v_mfma_f32_16x16x32_bf16 v[88:91], v[136:139], v[200:203], v[88:91]
	v_mfma_f32_16x16x32_bf16 v[84:87], v[144:147], v[200:203], v[84:87]
	v_mfma_f32_16x16x32_bf16 v[84:87], v[148:151], v[204:207], v[84:87]
	v_mfma_f32_16x16x32_bf16 v[80:83], v[172:175], v[204:207], v[80:83]
	v_mfma_f32_16x16x32_bf16 v[80:83], v[168:171], v[200:203], v[80:83]
	v_mfma_f32_16x16x32_bf16 v[64:67], v[168:171], v[208:211], v[64:67]
	v_mfma_f32_16x16x32_bf16 v[64:67], v[172:175], v[212:215], v[64:67]
	v_mfma_f32_16x16x32_bf16 v[68:71], v[148:151], v[212:215], v[68:71]
	v_mfma_f32_16x16x32_bf16 v[68:71], v[144:147], v[208:211], v[68:71]
	v_mfma_f32_16x16x32_bf16 v[72:75], v[136:139], v[208:211], v[72:75]
	v_mfma_f32_16x16x32_bf16 v[72:75], v[140:143], v[212:215], v[72:75]
	v_mfma_f32_16x16x32_bf16 v[76:79], v[132:135], v[212:215], v[76:79]
	v_mfma_f32_16x16x32_bf16 v[76:79], v[128:131], v[208:211], v[76:79]
	s_setprio 1
	s_barrier
	s_add_i32 s55, s46, s34
	v_lshl_add_u64 v[176:177], s[60:61], 0, v[154:155]
	s_mov_b32 m0, s55
	ds_read_b128 v[184:187], v183 offset:16384
	ds_read_b128 v[188:191], v183 offset:17408
	ds_read_b128 v[192:195], v183 offset:18432
	ds_read_b128 v[196:199], v183 offset:19456
	ds_read_b128 v[200:203], v183 offset:20480
	ds_read_b128 v[204:207], v183 offset:21504
	ds_read_b128 v[208:211], v183 offset:22528
	ds_read_b128 v[212:215], v183 offset:23552
	global_load_lds_dwordx4 v[176:177], off
	s_add_i32 m0, s55, 0x2000
	v_lshl_add_u64 v[216:217], s[60:61], 0, v[158:159]
	s_add_u32 s60, s60, s8
	s_addc_u32 s61, s61, s9
	s_add_i32 s55, s47, s34
	global_load_lds_dwordx4 v[216:217], off
	v_lshl_add_u64 v[218:219], s[60:61], 0, v[154:155]
	s_mov_b32 m0, s55
	v_lshl_add_u64 v[222:223], s[60:61], 0, v[158:159]
	global_load_lds_dwordx4 v[218:219], off
	s_add_i32 m0, s55, 0x2000
	v_lshl_add_u64 v[224:225], s[26:27], 0, v[152:153]
	global_load_lds_dwordx4 v[222:223], off
	s_mov_b32 m0, s35
	v_lshl_add_u64 v[226:227], s[26:27], 0, v[156:157]
	global_load_lds_dwordx4 v[224:225], off
	s_mov_b32 m0, s36
	s_nop 0
	global_load_lds_dwordx4 v[226:227], off
	s_waitcnt vmcnt(8)
	s_waitcnt lgkmcnt(0)
	s_barrier
	s_waitcnt lgkmcnt(0)
	s_setprio 0
	v_mfma_f32_16x16x32_bf16 v[60:63], v[128:131], v[184:187], v[60:63]
	v_mfma_f32_16x16x32_bf16 v[60:63], v[132:135], v[188:191], v[60:63]
	v_mfma_f32_16x16x32_bf16 v[56:59], v[140:143], v[188:191], v[56:59]
	v_mfma_f32_16x16x32_bf16 v[56:59], v[136:139], v[184:187], v[56:59]
	v_mfma_f32_16x16x32_bf16 v[52:55], v[144:147], v[184:187], v[52:55]
	v_mfma_f32_16x16x32_bf16 v[52:55], v[148:151], v[188:191], v[52:55]
	v_mfma_f32_16x16x32_bf16 v[48:51], v[172:175], v[188:191], v[48:51]
	v_mfma_f32_16x16x32_bf16 v[48:51], v[168:171], v[184:187], v[48:51]
	v_mfma_f32_16x16x32_bf16 v[32:35], v[168:171], v[192:195], v[32:35]
	v_mfma_f32_16x16x32_bf16 v[32:35], v[172:175], v[196:199], v[32:35]
	v_mfma_f32_16x16x32_bf16 v[36:39], v[148:151], v[196:199], v[36:39]
	v_mfma_f32_16x16x32_bf16 v[36:39], v[144:147], v[192:195], v[36:39]
	v_mfma_f32_16x16x32_bf16 v[40:43], v[136:139], v[192:195], v[40:43]
	v_mfma_f32_16x16x32_bf16 v[40:43], v[140:143], v[196:199], v[40:43]
	v_mfma_f32_16x16x32_bf16 v[44:47], v[132:135], v[196:199], v[44:47]
	v_mfma_f32_16x16x32_bf16 v[44:47], v[128:131], v[192:195], v[44:47]
	v_mfma_f32_16x16x32_bf16 v[28:31], v[128:131], v[200:203], v[28:31]
	v_mfma_f32_16x16x32_bf16 v[28:31], v[132:135], v[204:207], v[28:31]
	v_mfma_f32_16x16x32_bf16 v[24:27], v[140:143], v[204:207], v[24:27]
	v_mfma_f32_16x16x32_bf16 v[24:27], v[136:139], v[200:203], v[24:27]
	v_mfma_f32_16x16x32_bf16 v[20:23], v[144:147], v[200:203], v[20:23]
	v_mfma_f32_16x16x32_bf16 v[20:23], v[148:151], v[204:207], v[20:23]
	v_mfma_f32_16x16x32_bf16 v[16:19], v[172:175], v[204:207], v[16:19]
	v_mfma_f32_16x16x32_bf16 v[16:19], v[168:171], v[200:203], v[16:19]
	v_mfma_f32_16x16x32_bf16 v[0:3], v[168:171], v[208:211], v[0:3]
	v_mfma_f32_16x16x32_bf16 v[0:3], v[172:175], v[212:215], v[0:3]
	v_mfma_f32_16x16x32_bf16 v[4:7], v[148:151], v[212:215], v[4:7]
	v_mfma_f32_16x16x32_bf16 v[4:7], v[144:147], v[208:211], v[4:7]
	v_mfma_f32_16x16x32_bf16 v[8:11], v[136:139], v[208:211], v[8:11]
	v_mfma_f32_16x16x32_bf16 v[8:11], v[140:143], v[212:215], v[8:11]
	v_mfma_f32_16x16x32_bf16 v[12:15], v[132:135], v[212:215], v[12:15]
	v_mfma_f32_16x16x32_bf16 v[12:15], v[128:131], v[208:211], v[12:15]
	s_setprio 1
	s_barrier
	s_add_i32 s55, 0, 0x18000
	s_add_i32 s60, 0, 0x1c000
	v_add_u32_e32 v140, s55, v179
	v_add_u32_e32 v172, s60, v179
	ds_read_b128 v[128:131], v140
	ds_read_b128 v[132:135], v140 offset:1024
	ds_read_b128 v[136:139], v140 offset:2048
	ds_read_b128 v[140:143], v140 offset:3072
	ds_read_b128 v[144:147], v172
	ds_read_b128 v[148:151], v172 offset:1024
	ds_read_b128 v[168:171], v172 offset:2048
	ds_read_b128 v[172:175], v172 offset:3072
	s_add_u32 s26, s26, s8
	s_addc_u32 s27, s27, s9
	s_mov_b32 m0, s37
	v_lshl_add_u64 v[228:229], s[26:27], 0, v[152:153]
	ds_read_b128 v[184:187], v183 offset:32768
	ds_read_b128 v[188:191], v183 offset:33792
	ds_read_b128 v[192:195], v183 offset:34816
	ds_read_b128 v[196:199], v183 offset:35840
	ds_read_b128 v[200:203], v183 offset:36864
	ds_read_b128 v[204:207], v183 offset:37888
	ds_read_b128 v[208:211], v183 offset:38912
	ds_read_b128 v[212:215], v183 offset:39936
	global_load_lds_dwordx4 v[228:229], off
	v_lshl_add_u64 v[228:229], s[26:27], 0, v[156:157]
	s_mov_b32 m0, s38
	s_nop 0
	global_load_lds_dwordx4 v[228:229], off
	s_waitcnt vmcnt(8)
	s_waitcnt lgkmcnt(0)
	s_barrier
	s_waitcnt lgkmcnt(0)
	s_setprio 0
	v_mfma_f32_16x16x32_bf16 v[120:123], v[128:131], v[184:187], v[120:123]
	v_mfma_f32_16x16x32_bf16 v[120:123], v[132:135], v[188:191], v[120:123]
	v_mfma_f32_16x16x32_bf16 v[124:127], v[140:143], v[188:191], v[124:127]
	v_mfma_f32_16x16x32_bf16 v[124:127], v[136:139], v[184:187], v[124:127]
	v_mfma_f32_16x16x32_bf16 v[116:119], v[144:147], v[184:187], v[116:119]
	v_mfma_f32_16x16x32_bf16 v[116:119], v[148:151], v[188:191], v[116:119]
	v_mfma_f32_16x16x32_bf16 v[112:115], v[172:175], v[188:191], v[112:115]
	v_mfma_f32_16x16x32_bf16 v[112:115], v[168:171], v[184:187], v[112:115]
	v_mfma_f32_16x16x32_bf16 v[96:99], v[168:171], v[192:195], v[96:99]
	v_mfma_f32_16x16x32_bf16 v[96:99], v[172:175], v[196:199], v[96:99]
	v_mfma_f32_16x16x32_bf16 v[100:103], v[148:151], v[196:199], v[100:103]
	v_mfma_f32_16x16x32_bf16 v[100:103], v[144:147], v[192:195], v[100:103]
	v_mfma_f32_16x16x32_bf16 v[104:107], v[136:139], v[192:195], v[104:107]
	v_mfma_f32_16x16x32_bf16 v[104:107], v[140:143], v[196:199], v[104:107]
	v_mfma_f32_16x16x32_bf16 v[108:111], v[132:135], v[196:199], v[108:111]
	v_mfma_f32_16x16x32_bf16 v[108:111], v[128:131], v[192:195], v[108:111]
	v_mfma_f32_16x16x32_bf16 v[92:95], v[128:131], v[200:203], v[92:95]
	v_mfma_f32_16x16x32_bf16 v[92:95], v[132:135], v[204:207], v[92:95]
	v_mfma_f32_16x16x32_bf16 v[88:91], v[140:143], v[204:207], v[88:91]
	v_mfma_f32_16x16x32_bf16 v[88:91], v[136:139], v[200:203], v[88:91]
	v_mfma_f32_16x16x32_bf16 v[84:87], v[144:147], v[200:203], v[84:87]
	v_mfma_f32_16x16x32_bf16 v[84:87], v[148:151], v[204:207], v[84:87]
	v_mfma_f32_16x16x32_bf16 v[80:83], v[172:175], v[204:207], v[80:83]
	v_mfma_f32_16x16x32_bf16 v[80:83], v[168:171], v[200:203], v[80:83]
	v_mfma_f32_16x16x32_bf16 v[64:67], v[168:171], v[208:211], v[64:67]
	v_mfma_f32_16x16x32_bf16 v[64:67], v[172:175], v[212:215], v[64:67]
	v_mfma_f32_16x16x32_bf16 v[68:71], v[148:151], v[212:215], v[68:71]
	v_mfma_f32_16x16x32_bf16 v[68:71], v[144:147], v[208:211], v[68:71]
	v_mfma_f32_16x16x32_bf16 v[72:75], v[136:139], v[208:211], v[72:75]
	v_mfma_f32_16x16x32_bf16 v[72:75], v[140:143], v[212:215], v[72:75]
	v_mfma_f32_16x16x32_bf16 v[76:79], v[132:135], v[212:215], v[76:79]
	v_mfma_f32_16x16x32_bf16 v[76:79], v[128:131], v[208:211], v[76:79]
	s_setprio 1
	s_barrier
	s_add_i32 s26, s55, s34
	v_lshl_add_u64 v[176:177], v[176:177], 0, s[16:17]
	s_mov_b32 m0, s26
	ds_read_b128 v[184:187], v183 offset:49152
	ds_read_b128 v[188:191], v183 offset:50176
	ds_read_b128 v[192:195], v183 offset:51200
	ds_read_b128 v[196:199], v183 offset:52224
	ds_read_b128 v[200:203], v183 offset:53248
	ds_read_b128 v[204:207], v183 offset:54272
	ds_read_b128 v[208:211], v183 offset:55296
	ds_read_b128 v[212:215], v183 offset:56320
	global_load_lds_dwordx4 v[176:177], off
	v_lshl_add_u64 v[176:177], v[216:217], 0, s[16:17]
	s_add_i32 m0, s26, 0x2000
	s_add_i32 s26, s60, s34
	global_load_lds_dwordx4 v[176:177], off
	v_lshl_add_u64 v[176:177], v[218:219], 0, s[16:17]
	s_mov_b32 m0, s26
	s_nop 0
	global_load_lds_dwordx4 v[176:177], off
	v_lshl_add_u64 v[176:177], v[222:223], 0, s[16:17]
	s_add_i32 m0, s26, 0x2000
	s_nop 0
	global_load_lds_dwordx4 v[176:177], off
	v_lshl_add_u64 v[176:177], v[224:225], 0, s[16:17]
	s_mov_b32 m0, s40
	s_nop 0
	global_load_lds_dwordx4 v[176:177], off
	v_lshl_add_u64 v[176:177], v[226:227], 0, s[16:17]
	s_mov_b32 m0, s41
	s_nop 0
	global_load_lds_dwordx4 v[176:177], off
	s_waitcnt vmcnt(8)
	s_waitcnt lgkmcnt(0)
	s_barrier
	s_waitcnt lgkmcnt(0)
	s_setprio 0
	v_mfma_f32_16x16x32_bf16 v[60:63], v[128:131], v[184:187], v[60:63]
	v_mfma_f32_16x16x32_bf16 v[60:63], v[132:135], v[188:191], v[60:63]
	v_mfma_f32_16x16x32_bf16 v[56:59], v[140:143], v[188:191], v[56:59]
	v_mfma_f32_16x16x32_bf16 v[56:59], v[136:139], v[184:187], v[56:59]
	v_mfma_f32_16x16x32_bf16 v[52:55], v[144:147], v[184:187], v[52:55]
	v_mfma_f32_16x16x32_bf16 v[52:55], v[148:151], v[188:191], v[52:55]
	v_mfma_f32_16x16x32_bf16 v[48:51], v[172:175], v[188:191], v[48:51]
	v_mfma_f32_16x16x32_bf16 v[48:51], v[168:171], v[184:187], v[48:51]
	v_mfma_f32_16x16x32_bf16 v[32:35], v[168:171], v[192:195], v[32:35]
	v_mfma_f32_16x16x32_bf16 v[32:35], v[172:175], v[196:199], v[32:35]
	v_mfma_f32_16x16x32_bf16 v[36:39], v[148:151], v[196:199], v[36:39]
	v_mfma_f32_16x16x32_bf16 v[36:39], v[144:147], v[192:195], v[36:39]
	v_mfma_f32_16x16x32_bf16 v[40:43], v[136:139], v[192:195], v[40:43]
	v_mfma_f32_16x16x32_bf16 v[40:43], v[140:143], v[196:199], v[40:43]
	v_mfma_f32_16x16x32_bf16 v[44:47], v[132:135], v[196:199], v[44:47]
	v_mfma_f32_16x16x32_bf16 v[44:47], v[128:131], v[192:195], v[44:47]
	v_mfma_f32_16x16x32_bf16 v[28:31], v[128:131], v[200:203], v[28:31]
	v_mfma_f32_16x16x32_bf16 v[28:31], v[132:135], v[204:207], v[28:31]
	v_mfma_f32_16x16x32_bf16 v[24:27], v[140:143], v[204:207], v[24:27]
	v_mfma_f32_16x16x32_bf16 v[24:27], v[136:139], v[200:203], v[24:27]
	v_mfma_f32_16x16x32_bf16 v[20:23], v[144:147], v[200:203], v[20:23]
	v_mfma_f32_16x16x32_bf16 v[20:23], v[148:151], v[204:207], v[20:23]
	v_mfma_f32_16x16x32_bf16 v[16:19], v[172:175], v[204:207], v[16:19]
	v_mfma_f32_16x16x32_bf16 v[16:19], v[168:171], v[200:203], v[16:19]
	v_mfma_f32_16x16x32_bf16 v[0:3], v[168:171], v[208:211], v[0:3]
	v_mfma_f32_16x16x32_bf16 v[0:3], v[172:175], v[212:215], v[0:3]
	v_mfma_f32_16x16x32_bf16 v[4:7], v[148:151], v[212:215], v[4:7]
	v_mfma_f32_16x16x32_bf16 v[4:7], v[144:147], v[208:211], v[4:7]
	v_mfma_f32_16x16x32_bf16 v[8:11], v[136:139], v[208:211], v[8:11]
	v_mfma_f32_16x16x32_bf16 v[8:11], v[140:143], v[212:215], v[8:11]
	v_mfma_f32_16x16x32_bf16 v[12:15], v[132:135], v[212:215], v[12:15]
	v_mfma_f32_16x16x32_bf16 v[12:15], v[128:131], v[208:211], v[12:15]
	s_setprio 1
	s_barrier
	s_add_u32 s24, s24, 0x100
	s_addc_u32 s25, s25, 0
	s_add_u32 s52, s52, 0x100
	s_addc_u32 s53, s53, 0
	s_cmp_ge_i32 s54, s42
	s_mov_b32 s26, s54
	s_cbranch_scc0 .LBB0_763

.LBB0_849:
	ds_read_b128 v[112:115], v209
	ds_read_b128 v[116:119], v209 offset:1024
	ds_read_b128 v[120:123], v209 offset:2048
	ds_read_b128 v[128:131], v209 offset:3072
	ds_read_b128 v[144:147], v210
	ds_read_b128 v[148:151], v210 offset:1024
	ds_read_b128 v[152:155], v210 offset:2048
	ds_read_b128 v[156:159], v210 offset:3072
	s_add_i32 s62, s30, 2
	s_add_u32 s63, s28, 0x80
	s_addc_u32 s31, s29, 0
	s_cmp_eq_u32 s46, s30
	s_cselect_b32 s30, s4, s63
	s_cselect_b32 s31, s5, s31
	s_cselect_b32 s65, s27, s61
	s_cselect_b32 s64, s26, s60
	v_lshl_add_u64 v[204:205], s[28:29], 0, v[180:181]
	s_add_i32 m0, s38, 0xc000
	ds_read_b128 v[160:163], v211
	ds_read_b128 v[164:167], v211 offset:1024
	ds_read_b128 v[168:171], v211 offset:2048
	ds_read_b128 v[172:175], v211 offset:3072
	ds_read_b128 v[188:191], v211 offset:4096
	ds_read_b128 v[192:195], v211 offset:5120
	ds_read_b128 v[196:199], v211 offset:6144
	ds_read_b128 v[200:203], v211 offset:7168
	global_load_lds_dwordx4 v[204:205], off
	v_lshl_add_u64 v[204:205], s[28:29], 0, v[182:183]
	s_add_i32 m0, s38, 0xe000
	s_nop 0
	global_load_lds_dwordx4 v[204:205], off
	s_waitcnt vmcnt(8)
	s_waitcnt lgkmcnt(0)
	s_barrier
	s_waitcnt lgkmcnt(0)
	s_setprio 0
	v_mfma_f32_16x16x32_bf16 v[136:139], v[112:115], v[160:163], v[136:139]
	v_mfma_f32_16x16x32_bf16 v[136:139], v[116:119], v[164:167], v[136:139]
	v_mfma_f32_16x16x32_bf16 v[140:143], v[128:131], v[164:167], v[140:143]
	v_mfma_f32_16x16x32_bf16 v[140:143], v[120:123], v[160:163], v[140:143]
	v_mfma_f32_16x16x32_bf16 v[132:135], v[144:147], v[160:163], v[132:135]
	v_mfma_f32_16x16x32_bf16 v[132:135], v[148:151], v[164:167], v[132:135]
	v_mfma_f32_16x16x32_bf16 v[124:127], v[156:159], v[164:167], v[124:127]
	v_mfma_f32_16x16x32_bf16 v[124:127], v[152:155], v[160:163], v[124:127]
	v_mfma_f32_16x16x32_bf16 v[96:99], v[152:155], v[168:171], v[96:99]
	v_mfma_f32_16x16x32_bf16 v[96:99], v[156:159], v[172:175], v[96:99]
	v_mfma_f32_16x16x32_bf16 v[100:103], v[148:151], v[172:175], v[100:103]
	v_mfma_f32_16x16x32_bf16 v[100:103], v[144:147], v[168:171], v[100:103]
	v_mfma_f32_16x16x32_bf16 v[104:107], v[120:123], v[168:171], v[104:107]
	v_mfma_f32_16x16x32_bf16 v[104:107], v[128:131], v[172:175], v[104:107]
	v_mfma_f32_16x16x32_bf16 v[108:111], v[116:119], v[172:175], v[108:111]
	v_mfma_f32_16x16x32_bf16 v[108:111], v[112:115], v[168:171], v[108:111]
	v_mfma_f32_16x16x32_bf16 v[92:95], v[112:115], v[188:191], v[92:95]
	v_mfma_f32_16x16x32_bf16 v[92:95], v[116:119], v[192:195], v[92:95]
	v_mfma_f32_16x16x32_bf16 v[88:91], v[128:131], v[192:195], v[88:91]
	v_mfma_f32_16x16x32_bf16 v[88:91], v[120:123], v[188:191], v[88:91]
	v_mfma_f32_16x16x32_bf16 v[84:87], v[144:147], v[188:191], v[84:87]
	v_mfma_f32_16x16x32_bf16 v[84:87], v[148:151], v[192:195], v[84:87]
	v_mfma_f32_16x16x32_bf16 v[80:83], v[156:159], v[192:195], v[80:83]
	v_mfma_f32_16x16x32_bf16 v[80:83], v[152:155], v[188:191], v[80:83]
	v_mfma_f32_16x16x32_bf16 v[64:67], v[152:155], v[196:199], v[64:67]
	v_mfma_f32_16x16x32_bf16 v[64:67], v[156:159], v[200:203], v[64:67]
	v_mfma_f32_16x16x32_bf16 v[68:71], v[148:151], v[200:203], v[68:71]
	v_mfma_f32_16x16x32_bf16 v[68:71], v[144:147], v[196:199], v[68:71]
	v_mfma_f32_16x16x32_bf16 v[72:75], v[120:123], v[196:199], v[72:75]
	v_mfma_f32_16x16x32_bf16 v[72:75], v[128:131], v[200:203], v[72:75]
	v_mfma_f32_16x16x32_bf16 v[76:79], v[116:119], v[200:203], v[76:79]
	v_mfma_f32_16x16x32_bf16 v[76:79], v[112:115], v[196:199], v[76:79]
	s_setprio 1
	s_barrier
	s_add_i32 s63, s50, s37
	v_lshl_add_u64 v[204:205], s[64:65], 0, v[176:177]
	s_mov_b32 m0, s63
	ds_read_b128 v[160:163], v211 offset:16384
	ds_read_b128 v[164:167], v211 offset:17408
	ds_read_b128 v[168:171], v211 offset:18432
	ds_read_b128 v[172:175], v211 offset:19456
	ds_read_b128 v[188:191], v211 offset:20480
	ds_read_b128 v[192:195], v211 offset:21504
	ds_read_b128 v[196:199], v211 offset:22528
	ds_read_b128 v[200:203], v211 offset:23552
	global_load_lds_dwordx4 v[204:205], off
	s_add_i32 m0, s63, 0x2000
	v_lshl_add_u64 v[214:215], s[64:65], 0, v[178:179]
	s_add_u32 s64, s64, s10
	s_addc_u32 s65, s65, s11
	s_add_i32 s63, s51, s37
	global_load_lds_dwordx4 v[214:215], off
	v_lshl_add_u64 v[216:217], s[64:65], 0, v[176:177]
	s_mov_b32 m0, s63
	v_lshl_add_u64 v[218:219], s[64:65], 0, v[178:179]
	global_load_lds_dwordx4 v[216:217], off
	s_add_i32 m0, s63, 0x2000
	v_lshl_add_u64 v[222:223], s[30:31], 0, v[176:177]
	global_load_lds_dwordx4 v[218:219], off
	s_mov_b32 m0, s38
	v_lshl_add_u64 v[224:225], s[30:31], 0, v[178:179]
	global_load_lds_dwordx4 v[222:223], off
	s_mov_b32 m0, s39
	s_nop 0
	global_load_lds_dwordx4 v[224:225], off
	s_waitcnt vmcnt(8)
	s_waitcnt lgkmcnt(0)
	s_barrier
	s_waitcnt lgkmcnt(0)
	s_setprio 0
	v_mfma_f32_16x16x32_bf16 v[60:63], v[112:115], v[160:163], v[60:63]
	v_mfma_f32_16x16x32_bf16 v[60:63], v[116:119], v[164:167], v[60:63]
	v_mfma_f32_16x16x32_bf16 v[56:59], v[128:131], v[164:167], v[56:59]
	v_mfma_f32_16x16x32_bf16 v[56:59], v[120:123], v[160:163], v[56:59]
	v_mfma_f32_16x16x32_bf16 v[52:55], v[144:147], v[160:163], v[52:55]
	v_mfma_f32_16x16x32_bf16 v[52:55], v[148:151], v[164:167], v[52:55]
	v_mfma_f32_16x16x32_bf16 v[48:51], v[156:159], v[164:167], v[48:51]
	v_mfma_f32_16x16x32_bf16 v[48:51], v[152:155], v[160:163], v[48:51]
	v_mfma_f32_16x16x32_bf16 v[32:35], v[152:155], v[168:171], v[32:35]
	v_mfma_f32_16x16x32_bf16 v[32:35], v[156:159], v[172:175], v[32:35]
	v_mfma_f32_16x16x32_bf16 v[36:39], v[148:151], v[172:175], v[36:39]
	v_mfma_f32_16x16x32_bf16 v[36:39], v[144:147], v[168:171], v[36:39]
	v_mfma_f32_16x16x32_bf16 v[40:43], v[120:123], v[168:171], v[40:43]
	v_mfma_f32_16x16x32_bf16 v[40:43], v[128:131], v[172:175], v[40:43]
	v_mfma_f32_16x16x32_bf16 v[44:47], v[116:119], v[172:175], v[44:47]
	v_mfma_f32_16x16x32_bf16 v[44:47], v[112:115], v[168:171], v[44:47]
	v_mfma_f32_16x16x32_bf16 v[28:31], v[112:115], v[188:191], v[28:31]
	v_mfma_f32_16x16x32_bf16 v[28:31], v[116:119], v[192:195], v[28:31]
	v_mfma_f32_16x16x32_bf16 v[24:27], v[128:131], v[192:195], v[24:27]
	v_mfma_f32_16x16x32_bf16 v[24:27], v[120:123], v[188:191], v[24:27]
	v_mfma_f32_16x16x32_bf16 v[20:23], v[144:147], v[188:191], v[20:23]
	v_mfma_f32_16x16x32_bf16 v[20:23], v[148:151], v[192:195], v[20:23]
	v_mfma_f32_16x16x32_bf16 v[16:19], v[156:159], v[192:195], v[16:19]
	v_mfma_f32_16x16x32_bf16 v[16:19], v[152:155], v[188:191], v[16:19]
	v_mfma_f32_16x16x32_bf16 v[0:3], v[152:155], v[196:199], v[0:3]
	v_mfma_f32_16x16x32_bf16 v[0:3], v[156:159], v[200:203], v[0:3]
	v_mfma_f32_16x16x32_bf16 v[4:7], v[148:151], v[200:203], v[4:7]
	v_mfma_f32_16x16x32_bf16 v[4:7], v[144:147], v[196:199], v[4:7]
	v_mfma_f32_16x16x32_bf16 v[8:11], v[120:123], v[196:199], v[8:11]
	v_mfma_f32_16x16x32_bf16 v[8:11], v[128:131], v[200:203], v[8:11]
	v_mfma_f32_16x16x32_bf16 v[12:15], v[116:119], v[200:203], v[12:15]
	v_mfma_f32_16x16x32_bf16 v[12:15], v[112:115], v[196:199], v[12:15]
	s_setprio 1
	s_barrier
	s_add_i32 s63, 0, 0x18000
	s_add_i32 s64, 0, 0x1c000
	v_add_u32_e32 v128, s63, v207
	v_add_u32_e32 v156, s64, v207
	ds_read_b128 v[112:115], v128
	ds_read_b128 v[116:119], v128 offset:1024
	ds_read_b128 v[120:123], v128 offset:2048
	ds_read_b128 v[128:131], v128 offset:3072
	ds_read_b128 v[144:147], v156
	ds_read_b128 v[148:151], v156 offset:1024
	ds_read_b128 v[152:155], v156 offset:2048
	ds_read_b128 v[156:159], v156 offset:3072
	s_add_u32 s30, s30, s10
	s_addc_u32 s31, s31, s11
	s_mov_b32 m0, s40
	v_lshl_add_u64 v[226:227], s[30:31], 0, v[176:177]
	ds_read_b128 v[160:163], v211 offset:32768
	ds_read_b128 v[164:167], v211 offset:33792
	ds_read_b128 v[168:171], v211 offset:34816
	ds_read_b128 v[172:175], v211 offset:35840
	ds_read_b128 v[188:191], v211 offset:36864
	ds_read_b128 v[192:195], v211 offset:37888
	ds_read_b128 v[196:199], v211 offset:38912
	ds_read_b128 v[200:203], v211 offset:39936
	global_load_lds_dwordx4 v[226:227], off
	v_lshl_add_u64 v[226:227], s[30:31], 0, v[178:179]
	s_mov_b32 m0, s41
	s_nop 0
	global_load_lds_dwordx4 v[226:227], off
	s_waitcnt vmcnt(8)
	s_waitcnt lgkmcnt(0)
	s_barrier
	s_waitcnt lgkmcnt(0)
	s_setprio 0
	v_mfma_f32_16x16x32_bf16 v[136:139], v[112:115], v[160:163], v[136:139]
	v_mfma_f32_16x16x32_bf16 v[136:139], v[116:119], v[164:167], v[136:139]
	v_mfma_f32_16x16x32_bf16 v[140:143], v[128:131], v[164:167], v[140:143]
	v_mfma_f32_16x16x32_bf16 v[140:143], v[120:123], v[160:163], v[140:143]
	v_mfma_f32_16x16x32_bf16 v[132:135], v[144:147], v[160:163], v[132:135]
	v_mfma_f32_16x16x32_bf16 v[132:135], v[148:151], v[164:167], v[132:135]
	v_mfma_f32_16x16x32_bf16 v[124:127], v[156:159], v[164:167], v[124:127]
	v_mfma_f32_16x16x32_bf16 v[124:127], v[152:155], v[160:163], v[124:127]
	v_mfma_f32_16x16x32_bf16 v[96:99], v[152:155], v[168:171], v[96:99]
	v_mfma_f32_16x16x32_bf16 v[96:99], v[156:159], v[172:175], v[96:99]
	v_mfma_f32_16x16x32_bf16 v[100:103], v[148:151], v[172:175], v[100:103]
	v_mfma_f32_16x16x32_bf16 v[100:103], v[144:147], v[168:171], v[100:103]
	v_mfma_f32_16x16x32_bf16 v[104:107], v[120:123], v[168:171], v[104:107]
	v_mfma_f32_16x16x32_bf16 v[104:107], v[128:131], v[172:175], v[104:107]
	v_mfma_f32_16x16x32_bf16 v[108:111], v[116:119], v[172:175], v[108:111]
	v_mfma_f32_16x16x32_bf16 v[108:111], v[112:115], v[168:171], v[108:111]
	v_mfma_f32_16x16x32_bf16 v[92:95], v[112:115], v[188:191], v[92:95]
	v_mfma_f32_16x16x32_bf16 v[92:95], v[116:119], v[192:195], v[92:95]
	v_mfma_f32_16x16x32_bf16 v[88:91], v[128:131], v[192:195], v[88:91]
	v_mfma_f32_16x16x32_bf16 v[88:91], v[120:123], v[188:191], v[88:91]
	v_mfma_f32_16x16x32_bf16 v[84:87], v[144:147], v[188:191], v[84:87]
	v_mfma_f32_16x16x32_bf16 v[84:87], v[148:151], v[192:195], v[84:87]
	v_mfma_f32_16x16x32_bf16 v[80:83], v[156:159], v[192:195], v[80:83]
	v_mfma_f32_16x16x32_bf16 v[80:83], v[152:155], v[188:191], v[80:83]
	v_mfma_f32_16x16x32_bf16 v[64:67], v[152:155], v[196:199], v[64:67]
	v_mfma_f32_16x16x32_bf16 v[64:67], v[156:159], v[200:203], v[64:67]
	v_mfma_f32_16x16x32_bf16 v[68:71], v[148:151], v[200:203], v[68:71]
	v_mfma_f32_16x16x32_bf16 v[68:71], v[144:147], v[196:199], v[68:71]
	v_mfma_f32_16x16x32_bf16 v[72:75], v[120:123], v[196:199], v[72:75]
	v_mfma_f32_16x16x32_bf16 v[72:75], v[128:131], v[200:203], v[72:75]
	v_mfma_f32_16x16x32_bf16 v[76:79], v[116:119], v[200:203], v[76:79]
	v_mfma_f32_16x16x32_bf16 v[76:79], v[112:115], v[196:199], v[76:79]
	s_setprio 1
	s_barrier
	s_add_i32 s30, s63, s37
	v_lshl_add_u64 v[204:205], v[204:205], 0, s[18:19]
	s_mov_b32 m0, s30
	ds_read_b128 v[160:163], v211 offset:49152
	ds_read_b128 v[164:167], v211 offset:50176
	ds_read_b128 v[168:171], v211 offset:51200
	ds_read_b128 v[172:175], v211 offset:52224
	ds_read_b128 v[188:191], v211 offset:53248
	ds_read_b128 v[192:195], v211 offset:54272
	ds_read_b128 v[196:199], v211 offset:55296
	ds_read_b128 v[200:203], v211 offset:56320
	global_load_lds_dwordx4 v[204:205], off
	v_lshl_add_u64 v[204:205], v[214:215], 0, s[18:19]
	s_add_i32 m0, s30, 0x2000
	s_add_i32 s30, s64, s37
	global_load_lds_dwordx4 v[204:205], off
	v_lshl_add_u64 v[204:205], v[216:217], 0, s[18:19]
	s_mov_b32 m0, s30
	s_nop 0
	global_load_lds_dwordx4 v[204:205], off
	v_lshl_add_u64 v[204:205], v[218:219], 0, s[18:19]
	s_add_i32 m0, s30, 0x2000
	s_nop 0
	global_load_lds_dwordx4 v[204:205], off
	v_lshl_add_u64 v[204:205], v[222:223], 0, s[18:19]
	s_mov_b32 m0, s43
	s_nop 0
	global_load_lds_dwordx4 v[204:205], off
	v_lshl_add_u64 v[204:205], v[224:225], 0, s[18:19]
	s_mov_b32 m0, s44
	s_nop 0
	global_load_lds_dwordx4 v[204:205], off
	s_waitcnt vmcnt(8)
	s_waitcnt lgkmcnt(0)
	s_barrier
	s_waitcnt lgkmcnt(0)
	s_setprio 0
	v_mfma_f32_16x16x32_bf16 v[60:63], v[112:115], v[160:163], v[60:63]
	v_mfma_f32_16x16x32_bf16 v[60:63], v[116:119], v[164:167], v[60:63]
	v_mfma_f32_16x16x32_bf16 v[56:59], v[128:131], v[164:167], v[56:59]
	v_mfma_f32_16x16x32_bf16 v[56:59], v[120:123], v[160:163], v[56:59]
	v_mfma_f32_16x16x32_bf16 v[52:55], v[144:147], v[160:163], v[52:55]
	v_mfma_f32_16x16x32_bf16 v[52:55], v[148:151], v[164:167], v[52:55]
	v_mfma_f32_16x16x32_bf16 v[48:51], v[156:159], v[164:167], v[48:51]
	v_mfma_f32_16x16x32_bf16 v[48:51], v[152:155], v[160:163], v[48:51]
	v_mfma_f32_16x16x32_bf16 v[32:35], v[152:155], v[168:171], v[32:35]
	v_mfma_f32_16x16x32_bf16 v[32:35], v[156:159], v[172:175], v[32:35]
	v_mfma_f32_16x16x32_bf16 v[36:39], v[148:151], v[172:175], v[36:39]
	v_mfma_f32_16x16x32_bf16 v[36:39], v[144:147], v[168:171], v[36:39]
	v_mfma_f32_16x16x32_bf16 v[40:43], v[120:123], v[168:171], v[40:43]
	v_mfma_f32_16x16x32_bf16 v[40:43], v[128:131], v[172:175], v[40:43]
	v_mfma_f32_16x16x32_bf16 v[44:47], v[116:119], v[172:175], v[44:47]
	v_mfma_f32_16x16x32_bf16 v[44:47], v[112:115], v[168:171], v[44:47]
	v_mfma_f32_16x16x32_bf16 v[28:31], v[112:115], v[188:191], v[28:31]
	v_mfma_f32_16x16x32_bf16 v[28:31], v[116:119], v[192:195], v[28:31]
	v_mfma_f32_16x16x32_bf16 v[24:27], v[128:131], v[192:195], v[24:27]
	v_mfma_f32_16x16x32_bf16 v[24:27], v[120:123], v[188:191], v[24:27]
	v_mfma_f32_16x16x32_bf16 v[20:23], v[144:147], v[188:191], v[20:23]
	v_mfma_f32_16x16x32_bf16 v[20:23], v[148:151], v[192:195], v[20:23]
	v_mfma_f32_16x16x32_bf16 v[16:19], v[156:159], v[192:195], v[16:19]
	v_mfma_f32_16x16x32_bf16 v[16:19], v[152:155], v[188:191], v[16:19]
	v_mfma_f32_16x16x32_bf16 v[0:3], v[152:155], v[196:199], v[0:3]
	v_mfma_f32_16x16x32_bf16 v[0:3], v[156:159], v[200:203], v[0:3]
	v_mfma_f32_16x16x32_bf16 v[4:7], v[148:151], v[200:203], v[4:7]
	v_mfma_f32_16x16x32_bf16 v[4:7], v[144:147], v[196:199], v[4:7]
	v_mfma_f32_16x16x32_bf16 v[8:11], v[120:123], v[196:199], v[8:11]
	v_mfma_f32_16x16x32_bf16 v[8:11], v[128:131], v[200:203], v[8:11]
	v_mfma_f32_16x16x32_bf16 v[12:15], v[116:119], v[200:203], v[12:15]
	v_mfma_f32_16x16x32_bf16 v[12:15], v[112:115], v[196:199], v[12:15]
	s_setprio 1
	s_barrier
	s_add_u32 s28, s28, 0x100
	s_addc_u32 s29, s29, 0
	s_add_u32 s60, s60, 0x100
	s_addc_u32 s61, s61, 0
	s_cmp_ge_i32 s62, s45
	s_mov_b32 s30, s62
	s_cbranch_scc0 .LBB0_849

.LBB0_949:
	ds_read_b128 v[164:167], v157
	ds_read_b128 v[168:171], v157 offset:1024
	ds_read_b128 v[172:175], v157 offset:2048
	ds_read_b128 v[176:179], v157 offset:3072
	ds_read_b128 v[180:183], v162
	ds_read_b128 v[184:187], v162 offset:1024
	ds_read_b128 v[188:191], v162 offset:2048
	ds_read_b128 v[192:195], v162 offset:3072
	s_add_i32 s68, s34, 2
	s_add_u32 s69, s30, 0x80
	s_addc_u32 s35, s31, 0
	s_cmp_eq_u32 s49, s34
	s_cselect_b32 s34, s2, s69
	s_cselect_b32 s35, s3, s35
	s_cselect_b32 s71, s29, s67
	s_cselect_b32 s70, s28, s66
	v_lshl_add_u64 v[230:231], s[30:31], 0, v[136:137]
	s_add_i32 m0, s41, 0xc000
	ds_read_b128 v[196:199], v163
	ds_read_b128 v[200:203], v163 offset:1024
	ds_read_b128 v[204:207], v163 offset:2048
	ds_read_b128 v[208:211], v163 offset:3072
	ds_read_b128 v[212:215], v163 offset:4096
	ds_read_b128 v[216:219], v163 offset:5120
	ds_read_b128 v[222:225], v163 offset:6144
	ds_read_b128 v[226:229], v163 offset:7168
	global_load_lds_dwordx4 v[230:231], off
	v_lshl_add_u64 v[230:231], s[30:31], 0, v[138:139]
	s_add_i32 m0, s41, 0xe000
	s_nop 0
	global_load_lds_dwordx4 v[230:231], off
	s_waitcnt vmcnt(8)
	s_waitcnt lgkmcnt(0)
	s_barrier
	s_waitcnt lgkmcnt(0)
	s_setprio 0
	v_mfma_f32_16x16x32_bf16 v[120:123], v[164:167], v[196:199], v[120:123]
	v_mfma_f32_16x16x32_bf16 v[120:123], v[168:171], v[200:203], v[120:123]
	v_mfma_f32_16x16x32_bf16 v[124:127], v[176:179], v[200:203], v[124:127]
	v_mfma_f32_16x16x32_bf16 v[124:127], v[172:175], v[196:199], v[124:127]
	v_mfma_f32_16x16x32_bf16 v[116:119], v[180:183], v[196:199], v[116:119]
	v_mfma_f32_16x16x32_bf16 v[116:119], v[184:187], v[200:203], v[116:119]
	v_mfma_f32_16x16x32_bf16 v[112:115], v[192:195], v[200:203], v[112:115]
	v_mfma_f32_16x16x32_bf16 v[112:115], v[188:191], v[196:199], v[112:115]
	v_mfma_f32_16x16x32_bf16 v[96:99], v[188:191], v[204:207], v[96:99]
	v_mfma_f32_16x16x32_bf16 v[96:99], v[192:195], v[208:211], v[96:99]
	v_mfma_f32_16x16x32_bf16 v[100:103], v[184:187], v[208:211], v[100:103]
	v_mfma_f32_16x16x32_bf16 v[100:103], v[180:183], v[204:207], v[100:103]
	v_mfma_f32_16x16x32_bf16 v[104:107], v[172:175], v[204:207], v[104:107]
	v_mfma_f32_16x16x32_bf16 v[104:107], v[176:179], v[208:211], v[104:107]
	v_mfma_f32_16x16x32_bf16 v[108:111], v[168:171], v[208:211], v[108:111]
	v_mfma_f32_16x16x32_bf16 v[108:111], v[164:167], v[204:207], v[108:111]
	v_mfma_f32_16x16x32_bf16 v[92:95], v[164:167], v[212:215], v[92:95]
	v_mfma_f32_16x16x32_bf16 v[92:95], v[168:171], v[216:219], v[92:95]
	v_mfma_f32_16x16x32_bf16 v[88:91], v[176:179], v[216:219], v[88:91]
	v_mfma_f32_16x16x32_bf16 v[88:91], v[172:175], v[212:215], v[88:91]
	v_mfma_f32_16x16x32_bf16 v[84:87], v[180:183], v[212:215], v[84:87]
	v_mfma_f32_16x16x32_bf16 v[84:87], v[184:187], v[216:219], v[84:87]
	v_mfma_f32_16x16x32_bf16 v[80:83], v[192:195], v[216:219], v[80:83]
	v_mfma_f32_16x16x32_bf16 v[80:83], v[188:191], v[212:215], v[80:83]
	v_mfma_f32_16x16x32_bf16 v[64:67], v[188:191], v[222:225], v[64:67]
	v_mfma_f32_16x16x32_bf16 v[64:67], v[192:195], v[226:229], v[64:67]
	v_mfma_f32_16x16x32_bf16 v[68:71], v[184:187], v[226:229], v[68:71]
	v_mfma_f32_16x16x32_bf16 v[68:71], v[180:183], v[222:225], v[68:71]
	v_mfma_f32_16x16x32_bf16 v[72:75], v[172:175], v[222:225], v[72:75]
	v_mfma_f32_16x16x32_bf16 v[72:75], v[176:179], v[226:229], v[72:75]
	v_mfma_f32_16x16x32_bf16 v[76:79], v[168:171], v[226:229], v[76:79]
	v_mfma_f32_16x16x32_bf16 v[76:79], v[164:167], v[222:225], v[76:79]
	s_setprio 1
	s_barrier
	s_add_i32 s69, s52, s40
	v_lshl_add_u64 v[230:231], s[70:71], 0, v[130:131]
	s_mov_b32 m0, s69
	ds_read_b128 v[196:199], v163 offset:16384
	ds_read_b128 v[200:203], v163 offset:17408
	ds_read_b128 v[204:207], v163 offset:18432
	ds_read_b128 v[208:211], v163 offset:19456
	ds_read_b128 v[212:215], v163 offset:20480
	ds_read_b128 v[216:219], v163 offset:21504
	ds_read_b128 v[222:225], v163 offset:22528
	ds_read_b128 v[226:229], v163 offset:23552
	global_load_lds_dwordx4 v[230:231], off
	s_add_i32 m0, s69, 0x2000
	v_lshl_add_u64 v[232:233], s[70:71], 0, v[134:135]
	s_add_u32 s70, s70, s6
	s_addc_u32 s71, s71, s7
	s_add_i32 s69, s53, s40
	global_load_lds_dwordx4 v[232:233], off
	v_lshl_add_u64 v[234:235], s[70:71], 0, v[130:131]
	s_mov_b32 m0, s69
	v_lshl_add_u64 v[236:237], s[70:71], 0, v[134:135]
	global_load_lds_dwordx4 v[234:235], off
	s_add_i32 m0, s69, 0x2000
	v_lshl_add_u64 v[238:239], s[34:35], 0, v[128:129]
	global_load_lds_dwordx4 v[236:237], off
	s_mov_b32 m0, s41
	v_lshl_add_u64 v[240:241], s[34:35], 0, v[132:133]
	global_load_lds_dwordx4 v[238:239], off
	s_mov_b32 m0, s42
	s_nop 0
	global_load_lds_dwordx4 v[240:241], off
	s_waitcnt vmcnt(8)
	s_waitcnt lgkmcnt(0)
	s_barrier
	s_waitcnt lgkmcnt(0)
	s_setprio 0
	v_mfma_f32_16x16x32_bf16 v[60:63], v[164:167], v[196:199], v[60:63]
	v_mfma_f32_16x16x32_bf16 v[60:63], v[168:171], v[200:203], v[60:63]
	v_mfma_f32_16x16x32_bf16 v[56:59], v[176:179], v[200:203], v[56:59]
	v_mfma_f32_16x16x32_bf16 v[56:59], v[172:175], v[196:199], v[56:59]
	v_mfma_f32_16x16x32_bf16 v[52:55], v[180:183], v[196:199], v[52:55]
	v_mfma_f32_16x16x32_bf16 v[52:55], v[184:187], v[200:203], v[52:55]
	v_mfma_f32_16x16x32_bf16 v[48:51], v[192:195], v[200:203], v[48:51]
	v_mfma_f32_16x16x32_bf16 v[48:51], v[188:191], v[196:199], v[48:51]
	v_mfma_f32_16x16x32_bf16 v[32:35], v[188:191], v[204:207], v[32:35]
	v_mfma_f32_16x16x32_bf16 v[32:35], v[192:195], v[208:211], v[32:35]
	v_mfma_f32_16x16x32_bf16 v[36:39], v[184:187], v[208:211], v[36:39]
	v_mfma_f32_16x16x32_bf16 v[36:39], v[180:183], v[204:207], v[36:39]
	v_mfma_f32_16x16x32_bf16 v[40:43], v[172:175], v[204:207], v[40:43]
	v_mfma_f32_16x16x32_bf16 v[40:43], v[176:179], v[208:211], v[40:43]
	v_mfma_f32_16x16x32_bf16 v[44:47], v[168:171], v[208:211], v[44:47]
	v_mfma_f32_16x16x32_bf16 v[44:47], v[164:167], v[204:207], v[44:47]
	v_mfma_f32_16x16x32_bf16 v[28:31], v[164:167], v[212:215], v[28:31]
	v_mfma_f32_16x16x32_bf16 v[28:31], v[168:171], v[216:219], v[28:31]
	v_mfma_f32_16x16x32_bf16 v[24:27], v[176:179], v[216:219], v[24:27]
	v_mfma_f32_16x16x32_bf16 v[24:27], v[172:175], v[212:215], v[24:27]
	v_mfma_f32_16x16x32_bf16 v[20:23], v[180:183], v[212:215], v[20:23]
	v_mfma_f32_16x16x32_bf16 v[20:23], v[184:187], v[216:219], v[20:23]
	v_mfma_f32_16x16x32_bf16 v[16:19], v[192:195], v[216:219], v[16:19]
	v_mfma_f32_16x16x32_bf16 v[16:19], v[188:191], v[212:215], v[16:19]
	v_mfma_f32_16x16x32_bf16 v[0:3], v[188:191], v[222:225], v[0:3]
	v_mfma_f32_16x16x32_bf16 v[0:3], v[192:195], v[226:229], v[0:3]
	v_mfma_f32_16x16x32_bf16 v[4:7], v[184:187], v[226:229], v[4:7]
	v_mfma_f32_16x16x32_bf16 v[4:7], v[180:183], v[222:225], v[4:7]
	v_mfma_f32_16x16x32_bf16 v[8:11], v[172:175], v[222:225], v[8:11]
	v_mfma_f32_16x16x32_bf16 v[8:11], v[176:179], v[226:229], v[8:11]
	v_mfma_f32_16x16x32_bf16 v[12:15], v[168:171], v[226:229], v[12:15]
	v_mfma_f32_16x16x32_bf16 v[12:15], v[164:167], v[222:225], v[12:15]
	s_setprio 1
	s_barrier
	s_add_i32 s69, 0, 0x18000
	s_add_i32 s70, 0, 0x1c000
	v_add_u32_e32 v176, s69, v154
	v_add_u32_e32 v192, s70, v154
	ds_read_b128 v[164:167], v176
	ds_read_b128 v[168:171], v176 offset:1024
	ds_read_b128 v[172:175], v176 offset:2048
	ds_read_b128 v[176:179], v176 offset:3072
	ds_read_b128 v[180:183], v192
	ds_read_b128 v[184:187], v192 offset:1024
	ds_read_b128 v[188:191], v192 offset:2048
	ds_read_b128 v[192:195], v192 offset:3072
	s_add_u32 s34, s34, s6
	s_addc_u32 s35, s35, s7
	s_mov_b32 m0, s43
	v_lshl_add_u64 v[242:243], s[34:35], 0, v[128:129]
	ds_read_b128 v[196:199], v163 offset:32768
	ds_read_b128 v[200:203], v163 offset:33792
	ds_read_b128 v[204:207], v163 offset:34816
	ds_read_b128 v[208:211], v163 offset:35840
	ds_read_b128 v[212:215], v163 offset:36864
	ds_read_b128 v[216:219], v163 offset:37888
	ds_read_b128 v[222:225], v163 offset:38912
	ds_read_b128 v[226:229], v163 offset:39936
	global_load_lds_dwordx4 v[242:243], off
	v_lshl_add_u64 v[242:243], s[34:35], 0, v[132:133]
	s_mov_b32 m0, s44
	s_nop 0
	global_load_lds_dwordx4 v[242:243], off
	s_waitcnt vmcnt(8)
	s_waitcnt lgkmcnt(0)
	s_barrier
	s_waitcnt lgkmcnt(0)
	s_setprio 0
	v_mfma_f32_16x16x32_bf16 v[120:123], v[164:167], v[196:199], v[120:123]
	v_mfma_f32_16x16x32_bf16 v[120:123], v[168:171], v[200:203], v[120:123]
	v_mfma_f32_16x16x32_bf16 v[124:127], v[176:179], v[200:203], v[124:127]
	v_mfma_f32_16x16x32_bf16 v[124:127], v[172:175], v[196:199], v[124:127]
	v_mfma_f32_16x16x32_bf16 v[116:119], v[180:183], v[196:199], v[116:119]
	v_mfma_f32_16x16x32_bf16 v[116:119], v[184:187], v[200:203], v[116:119]
	v_mfma_f32_16x16x32_bf16 v[112:115], v[192:195], v[200:203], v[112:115]
	v_mfma_f32_16x16x32_bf16 v[112:115], v[188:191], v[196:199], v[112:115]
	v_mfma_f32_16x16x32_bf16 v[96:99], v[188:191], v[204:207], v[96:99]
	v_mfma_f32_16x16x32_bf16 v[96:99], v[192:195], v[208:211], v[96:99]
	v_mfma_f32_16x16x32_bf16 v[100:103], v[184:187], v[208:211], v[100:103]
	v_mfma_f32_16x16x32_bf16 v[100:103], v[180:183], v[204:207], v[100:103]
	v_mfma_f32_16x16x32_bf16 v[104:107], v[172:175], v[204:207], v[104:107]
	v_mfma_f32_16x16x32_bf16 v[104:107], v[176:179], v[208:211], v[104:107]
	v_mfma_f32_16x16x32_bf16 v[108:111], v[168:171], v[208:211], v[108:111]
	v_mfma_f32_16x16x32_bf16 v[108:111], v[164:167], v[204:207], v[108:111]
	v_mfma_f32_16x16x32_bf16 v[92:95], v[164:167], v[212:215], v[92:95]
	v_mfma_f32_16x16x32_bf16 v[92:95], v[168:171], v[216:219], v[92:95]
	v_mfma_f32_16x16x32_bf16 v[88:91], v[176:179], v[216:219], v[88:91]
	v_mfma_f32_16x16x32_bf16 v[88:91], v[172:175], v[212:215], v[88:91]
	v_mfma_f32_16x16x32_bf16 v[84:87], v[180:183], v[212:215], v[84:87]
	v_mfma_f32_16x16x32_bf16 v[84:87], v[184:187], v[216:219], v[84:87]
	v_mfma_f32_16x16x32_bf16 v[80:83], v[192:195], v[216:219], v[80:83]
	v_mfma_f32_16x16x32_bf16 v[80:83], v[188:191], v[212:215], v[80:83]
	v_mfma_f32_16x16x32_bf16 v[64:67], v[188:191], v[222:225], v[64:67]
	v_mfma_f32_16x16x32_bf16 v[64:67], v[192:195], v[226:229], v[64:67]
	v_mfma_f32_16x16x32_bf16 v[68:71], v[184:187], v[226:229], v[68:71]
	v_mfma_f32_16x16x32_bf16 v[68:71], v[180:183], v[222:225], v[68:71]
	v_mfma_f32_16x16x32_bf16 v[72:75], v[172:175], v[222:225], v[72:75]
	v_mfma_f32_16x16x32_bf16 v[72:75], v[176:179], v[226:229], v[72:75]
	v_mfma_f32_16x16x32_bf16 v[76:79], v[168:171], v[226:229], v[76:79]
	v_mfma_f32_16x16x32_bf16 v[76:79], v[164:167], v[222:225], v[76:79]
	s_setprio 1
	s_barrier
	s_add_i32 s34, s69, s40
	v_lshl_add_u64 v[230:231], v[230:231], 0, s[12:13]
	s_mov_b32 m0, s34
	ds_read_b128 v[196:199], v163 offset:49152
	ds_read_b128 v[200:203], v163 offset:50176
	ds_read_b128 v[204:207], v163 offset:51200
	ds_read_b128 v[208:211], v163 offset:52224
	ds_read_b128 v[212:215], v163 offset:53248
	ds_read_b128 v[216:219], v163 offset:54272
	ds_read_b128 v[222:225], v163 offset:55296
	ds_read_b128 v[226:229], v163 offset:56320
	global_load_lds_dwordx4 v[230:231], off
	v_lshl_add_u64 v[230:231], v[232:233], 0, s[12:13]
	s_add_i32 m0, s34, 0x2000
	s_add_i32 s34, s70, s40
	global_load_lds_dwordx4 v[230:231], off
	v_lshl_add_u64 v[230:231], v[234:235], 0, s[12:13]
	s_mov_b32 m0, s34
	s_nop 0
	global_load_lds_dwordx4 v[230:231], off
	v_lshl_add_u64 v[230:231], v[236:237], 0, s[12:13]
	s_add_i32 m0, s34, 0x2000
	s_nop 0
	global_load_lds_dwordx4 v[230:231], off
	v_lshl_add_u64 v[230:231], v[238:239], 0, s[12:13]
	s_mov_b32 m0, s46
	s_nop 0
	global_load_lds_dwordx4 v[230:231], off
	v_lshl_add_u64 v[230:231], v[240:241], 0, s[12:13]
	s_mov_b32 m0, s47
	s_nop 0
	global_load_lds_dwordx4 v[230:231], off
	s_waitcnt vmcnt(8)
	s_waitcnt lgkmcnt(0)
	s_barrier
	s_waitcnt lgkmcnt(0)
	s_setprio 0
	v_mfma_f32_16x16x32_bf16 v[60:63], v[164:167], v[196:199], v[60:63]
	v_mfma_f32_16x16x32_bf16 v[60:63], v[168:171], v[200:203], v[60:63]
	v_mfma_f32_16x16x32_bf16 v[56:59], v[176:179], v[200:203], v[56:59]
	v_mfma_f32_16x16x32_bf16 v[56:59], v[172:175], v[196:199], v[56:59]
	v_mfma_f32_16x16x32_bf16 v[52:55], v[180:183], v[196:199], v[52:55]
	v_mfma_f32_16x16x32_bf16 v[52:55], v[184:187], v[200:203], v[52:55]
	v_mfma_f32_16x16x32_bf16 v[48:51], v[192:195], v[200:203], v[48:51]
	v_mfma_f32_16x16x32_bf16 v[48:51], v[188:191], v[196:199], v[48:51]
	v_mfma_f32_16x16x32_bf16 v[32:35], v[188:191], v[204:207], v[32:35]
	v_mfma_f32_16x16x32_bf16 v[32:35], v[192:195], v[208:211], v[32:35]
	v_mfma_f32_16x16x32_bf16 v[36:39], v[184:187], v[208:211], v[36:39]
	v_mfma_f32_16x16x32_bf16 v[36:39], v[180:183], v[204:207], v[36:39]
	v_mfma_f32_16x16x32_bf16 v[40:43], v[172:175], v[204:207], v[40:43]
	v_mfma_f32_16x16x32_bf16 v[40:43], v[176:179], v[208:211], v[40:43]
	v_mfma_f32_16x16x32_bf16 v[44:47], v[168:171], v[208:211], v[44:47]
	v_mfma_f32_16x16x32_bf16 v[44:47], v[164:167], v[204:207], v[44:47]
	v_mfma_f32_16x16x32_bf16 v[28:31], v[164:167], v[212:215], v[28:31]
	v_mfma_f32_16x16x32_bf16 v[28:31], v[168:171], v[216:219], v[28:31]
	v_mfma_f32_16x16x32_bf16 v[24:27], v[176:179], v[216:219], v[24:27]
	v_mfma_f32_16x16x32_bf16 v[24:27], v[172:175], v[212:215], v[24:27]
	v_mfma_f32_16x16x32_bf16 v[20:23], v[180:183], v[212:215], v[20:23]
	v_mfma_f32_16x16x32_bf16 v[20:23], v[184:187], v[216:219], v[20:23]
	v_mfma_f32_16x16x32_bf16 v[16:19], v[192:195], v[216:219], v[16:19]
	v_mfma_f32_16x16x32_bf16 v[16:19], v[188:191], v[212:215], v[16:19]
	v_mfma_f32_16x16x32_bf16 v[0:3], v[188:191], v[222:225], v[0:3]
	v_mfma_f32_16x16x32_bf16 v[0:3], v[192:195], v[226:229], v[0:3]
	v_mfma_f32_16x16x32_bf16 v[4:7], v[184:187], v[226:229], v[4:7]
	v_mfma_f32_16x16x32_bf16 v[4:7], v[180:183], v[222:225], v[4:7]
	v_mfma_f32_16x16x32_bf16 v[8:11], v[172:175], v[222:225], v[8:11]
	v_mfma_f32_16x16x32_bf16 v[8:11], v[176:179], v[226:229], v[8:11]
	v_mfma_f32_16x16x32_bf16 v[12:15], v[168:171], v[226:229], v[12:15]
	v_mfma_f32_16x16x32_bf16 v[12:15], v[164:167], v[222:225], v[12:15]
	s_setprio 1
	s_barrier
	s_add_u32 s30, s30, 0x100
	s_addc_u32 s31, s31, 0
	s_add_u32 s66, s66, 0x100
	s_addc_u32 s67, s67, 0
	s_cmp_ge_i32 s68, s48
	s_mov_b32 s34, s68
	s_cbranch_scc0 .LBB0_949

.LBB0_970:
	ds_read_b128 v[170:173], v139
	ds_read_b128 v[174:177], v139 offset:1024
	ds_read_b128 v[178:181], v139 offset:2048
	ds_read_b128 v[182:185], v139 offset:3072
	ds_read_b128 v[186:189], v165
	ds_read_b128 v[190:193], v165 offset:1024
	ds_read_b128 v[194:197], v165 offset:2048
	ds_read_b128 v[198:201], v165 offset:3072
	s_add_i32 s8, s4, 2
	s_add_u32 s9, s2, 0x80
	s_addc_u32 s5, s3, 0
	s_cmp_eq_u32 s52, s4
	s_cselect_b32 s4, s30, s9
	s_cselect_b32 s5, s31, s5
	s_cselect_b32 s11, s35, s7
	s_cselect_b32 s10, s34, s6
	v_lshl_add_u64 v[218:219], s[2:3], 0, v[156:157]
	s_add_i32 m0, s42, 0xc000
	ds_read_b128 v[202:205], v166
	ds_read_b128 v[206:209], v166 offset:1024
	ds_read_b128 v[210:213], v166 offset:2048
	ds_read_b128 v[214:217], v166 offset:3072
	ds_read_b128 v[222:225], v166 offset:4096
	ds_read_b128 v[226:229], v166 offset:5120
	ds_read_b128 v[230:233], v166 offset:6144
	ds_read_b128 v[234:237], v166 offset:7168
	global_load_lds_dwordx4 v[218:219], off
	v_lshl_add_u64 v[218:219], s[2:3], 0, v[158:159]
	s_add_i32 m0, s42, 0xe000
	s_nop 0
	global_load_lds_dwordx4 v[218:219], off
	s_waitcnt vmcnt(8)
	s_waitcnt lgkmcnt(0)
	s_barrier
	s_waitcnt lgkmcnt(0)
	s_setprio 0
	v_mfma_f32_16x16x32_bf16 v[124:127], v[170:173], v[202:205], v[124:127]
	v_mfma_f32_16x16x32_bf16 v[124:127], v[174:177], v[206:209], v[124:127]
	v_mfma_f32_16x16x32_bf16 v[120:123], v[182:185], v[206:209], v[120:123]
	v_mfma_f32_16x16x32_bf16 v[120:123], v[178:181], v[202:205], v[120:123]
	v_mfma_f32_16x16x32_bf16 v[116:119], v[186:189], v[202:205], v[116:119]
	v_mfma_f32_16x16x32_bf16 v[116:119], v[190:193], v[206:209], v[116:119]
	v_mfma_f32_16x16x32_bf16 v[112:115], v[198:201], v[206:209], v[112:115]
	v_mfma_f32_16x16x32_bf16 v[112:115], v[194:197], v[202:205], v[112:115]
	v_mfma_f32_16x16x32_bf16 v[96:99], v[194:197], v[210:213], v[96:99]
	v_mfma_f32_16x16x32_bf16 v[96:99], v[198:201], v[214:217], v[96:99]
	v_mfma_f32_16x16x32_bf16 v[100:103], v[190:193], v[214:217], v[100:103]
	v_mfma_f32_16x16x32_bf16 v[100:103], v[186:189], v[210:213], v[100:103]
	v_mfma_f32_16x16x32_bf16 v[104:107], v[178:181], v[210:213], v[104:107]
	v_mfma_f32_16x16x32_bf16 v[104:107], v[182:185], v[214:217], v[104:107]
	v_mfma_f32_16x16x32_bf16 v[108:111], v[174:177], v[214:217], v[108:111]
	v_mfma_f32_16x16x32_bf16 v[108:111], v[170:173], v[210:213], v[108:111]
	v_mfma_f32_16x16x32_bf16 v[92:95], v[170:173], v[222:225], v[92:95]
	v_mfma_f32_16x16x32_bf16 v[92:95], v[174:177], v[226:229], v[92:95]
	v_mfma_f32_16x16x32_bf16 v[88:91], v[182:185], v[226:229], v[88:91]
	v_mfma_f32_16x16x32_bf16 v[88:91], v[178:181], v[222:225], v[88:91]
	v_mfma_f32_16x16x32_bf16 v[84:87], v[186:189], v[222:225], v[84:87]
	v_mfma_f32_16x16x32_bf16 v[84:87], v[190:193], v[226:229], v[84:87]
	v_mfma_f32_16x16x32_bf16 v[80:83], v[198:201], v[226:229], v[80:83]
	v_mfma_f32_16x16x32_bf16 v[80:83], v[194:197], v[222:225], v[80:83]
	v_mfma_f32_16x16x32_bf16 v[64:67], v[194:197], v[230:233], v[64:67]
	v_mfma_f32_16x16x32_bf16 v[64:67], v[198:201], v[234:237], v[64:67]
	v_mfma_f32_16x16x32_bf16 v[68:71], v[190:193], v[234:237], v[68:71]
	v_mfma_f32_16x16x32_bf16 v[68:71], v[186:189], v[230:233], v[68:71]
	v_mfma_f32_16x16x32_bf16 v[72:75], v[178:181], v[230:233], v[72:75]
	v_mfma_f32_16x16x32_bf16 v[72:75], v[182:185], v[234:237], v[72:75]
	v_mfma_f32_16x16x32_bf16 v[76:79], v[174:177], v[234:237], v[76:79]
	v_mfma_f32_16x16x32_bf16 v[76:79], v[170:173], v[230:233], v[76:79]
	s_setprio 1
	s_barrier
	s_add_i32 s9, s60, s39
	v_lshl_add_u64 v[218:219], s[10:11], 0, v[132:133]
	s_mov_b32 m0, s9
	ds_read_b128 v[202:205], v166 offset:16384
	ds_read_b128 v[206:209], v166 offset:17408
	ds_read_b128 v[210:213], v166 offset:18432
	ds_read_b128 v[214:217], v166 offset:19456
	ds_read_b128 v[222:225], v166 offset:20480
	ds_read_b128 v[226:229], v166 offset:21504
	ds_read_b128 v[230:233], v166 offset:22528
	ds_read_b128 v[234:237], v166 offset:23552
	global_load_lds_dwordx4 v[218:219], off
	s_add_i32 m0, s9, 0x2000
	v_lshl_add_u64 v[238:239], s[10:11], 0, v[128:129]
	s_add_u32 s10, s10, s18
	s_addc_u32 s11, s11, s19
	s_add_i32 s9, s61, s39
	global_load_lds_dwordx4 v[238:239], off
	v_lshl_add_u64 v[240:241], s[10:11], 0, v[132:133]
	s_mov_b32 m0, s9
	v_lshl_add_u64 v[242:243], s[10:11], 0, v[128:129]
	global_load_lds_dwordx4 v[240:241], off
	s_add_i32 m0, s9, 0x2000
	v_lshl_add_u64 v[244:245], s[4:5], 0, v[134:135]
	global_load_lds_dwordx4 v[242:243], off
	s_mov_b32 m0, s42
	v_lshl_add_u64 v[246:247], s[4:5], 0, v[130:131]
	global_load_lds_dwordx4 v[244:245], off
	s_mov_b32 m0, s43
	s_nop 0
	global_load_lds_dwordx4 v[246:247], off
	s_waitcnt vmcnt(8)
	s_waitcnt lgkmcnt(0)
	s_barrier
	s_waitcnt lgkmcnt(0)
	s_setprio 0
	v_mfma_f32_16x16x32_bf16 v[60:63], v[170:173], v[202:205], v[60:63]
	v_mfma_f32_16x16x32_bf16 v[60:63], v[174:177], v[206:209], v[60:63]
	v_mfma_f32_16x16x32_bf16 v[56:59], v[182:185], v[206:209], v[56:59]
	v_mfma_f32_16x16x32_bf16 v[56:59], v[178:181], v[202:205], v[56:59]
	v_mfma_f32_16x16x32_bf16 v[52:55], v[186:189], v[202:205], v[52:55]
	v_mfma_f32_16x16x32_bf16 v[52:55], v[190:193], v[206:209], v[52:55]
	v_mfma_f32_16x16x32_bf16 v[48:51], v[198:201], v[206:209], v[48:51]
	v_mfma_f32_16x16x32_bf16 v[48:51], v[194:197], v[202:205], v[48:51]
	v_mfma_f32_16x16x32_bf16 v[32:35], v[194:197], v[210:213], v[32:35]
	v_mfma_f32_16x16x32_bf16 v[32:35], v[198:201], v[214:217], v[32:35]
	v_mfma_f32_16x16x32_bf16 v[36:39], v[190:193], v[214:217], v[36:39]
	v_mfma_f32_16x16x32_bf16 v[36:39], v[186:189], v[210:213], v[36:39]
	v_mfma_f32_16x16x32_bf16 v[40:43], v[178:181], v[210:213], v[40:43]
	v_mfma_f32_16x16x32_bf16 v[40:43], v[182:185], v[214:217], v[40:43]
	v_mfma_f32_16x16x32_bf16 v[44:47], v[174:177], v[214:217], v[44:47]
	v_mfma_f32_16x16x32_bf16 v[44:47], v[170:173], v[210:213], v[44:47]
	v_mfma_f32_16x16x32_bf16 v[28:31], v[170:173], v[222:225], v[28:31]
	v_mfma_f32_16x16x32_bf16 v[28:31], v[174:177], v[226:229], v[28:31]
	v_mfma_f32_16x16x32_bf16 v[24:27], v[182:185], v[226:229], v[24:27]
	v_mfma_f32_16x16x32_bf16 v[24:27], v[178:181], v[222:225], v[24:27]
	v_mfma_f32_16x16x32_bf16 v[20:23], v[186:189], v[222:225], v[20:23]
	v_mfma_f32_16x16x32_bf16 v[20:23], v[190:193], v[226:229], v[20:23]
	v_mfma_f32_16x16x32_bf16 v[16:19], v[198:201], v[226:229], v[16:19]
	v_mfma_f32_16x16x32_bf16 v[16:19], v[194:197], v[222:225], v[16:19]
	v_mfma_f32_16x16x32_bf16 v[0:3], v[194:197], v[230:233], v[0:3]
	v_mfma_f32_16x16x32_bf16 v[0:3], v[198:201], v[234:237], v[0:3]
	v_mfma_f32_16x16x32_bf16 v[4:7], v[190:193], v[234:237], v[4:7]
	v_mfma_f32_16x16x32_bf16 v[4:7], v[186:189], v[230:233], v[4:7]
	v_mfma_f32_16x16x32_bf16 v[8:11], v[178:181], v[230:233], v[8:11]
	v_mfma_f32_16x16x32_bf16 v[8:11], v[182:185], v[234:237], v[8:11]
	v_mfma_f32_16x16x32_bf16 v[12:15], v[174:177], v[234:237], v[12:15]
	v_mfma_f32_16x16x32_bf16 v[12:15], v[170:173], v[230:233], v[12:15]
	s_setprio 1
	s_barrier
	s_add_i32 s9, 0, 0x18000
	v_add_u32_e32 v169, s9, v164
	s_add_i32 s10, 0, 0x1c000
	ds_read_b128 v[170:173], v169
	ds_read_b128 v[174:177], v169 offset:1024
	ds_read_b128 v[178:181], v169 offset:2048
	ds_read_b128 v[182:185], v169 offset:3072
	v_add_u32_e32 v169, s10, v164
	ds_read_b128 v[186:189], v169
	ds_read_b128 v[190:193], v169 offset:1024
	ds_read_b128 v[194:197], v169 offset:2048
	ds_read_b128 v[198:201], v169 offset:3072
	s_add_u32 s4, s4, s18
	s_addc_u32 s5, s5, s19
	s_mov_b32 m0, s44
	v_lshl_add_u64 v[248:249], s[4:5], 0, v[134:135]
	ds_read_b128 v[202:205], v166 offset:32768
	ds_read_b128 v[206:209], v166 offset:33792
	ds_read_b128 v[210:213], v166 offset:34816
	ds_read_b128 v[214:217], v166 offset:35840
	ds_read_b128 v[222:225], v166 offset:36864
	ds_read_b128 v[226:229], v166 offset:37888
	ds_read_b128 v[230:233], v166 offset:38912
	ds_read_b128 v[234:237], v166 offset:39936
	global_load_lds_dwordx4 v[248:249], off
	v_lshl_add_u64 v[248:249], s[4:5], 0, v[130:131]
	s_mov_b32 m0, s45
	s_nop 0
	global_load_lds_dwordx4 v[248:249], off
	s_waitcnt vmcnt(8)
	s_waitcnt lgkmcnt(0)
	s_barrier
	s_waitcnt lgkmcnt(0)
	s_setprio 0
	v_mfma_f32_16x16x32_bf16 v[124:127], v[170:173], v[202:205], v[124:127]
	v_mfma_f32_16x16x32_bf16 v[124:127], v[174:177], v[206:209], v[124:127]
	v_mfma_f32_16x16x32_bf16 v[120:123], v[182:185], v[206:209], v[120:123]
	v_mfma_f32_16x16x32_bf16 v[120:123], v[178:181], v[202:205], v[120:123]
	v_mfma_f32_16x16x32_bf16 v[116:119], v[186:189], v[202:205], v[116:119]
	v_mfma_f32_16x16x32_bf16 v[116:119], v[190:193], v[206:209], v[116:119]
	v_mfma_f32_16x16x32_bf16 v[112:115], v[198:201], v[206:209], v[112:115]
	v_mfma_f32_16x16x32_bf16 v[112:115], v[194:197], v[202:205], v[112:115]
	v_mfma_f32_16x16x32_bf16 v[96:99], v[194:197], v[210:213], v[96:99]
	v_mfma_f32_16x16x32_bf16 v[96:99], v[198:201], v[214:217], v[96:99]
	v_mfma_f32_16x16x32_bf16 v[100:103], v[190:193], v[214:217], v[100:103]
	v_mfma_f32_16x16x32_bf16 v[100:103], v[186:189], v[210:213], v[100:103]
	v_mfma_f32_16x16x32_bf16 v[104:107], v[178:181], v[210:213], v[104:107]
	v_mfma_f32_16x16x32_bf16 v[104:107], v[182:185], v[214:217], v[104:107]
	v_mfma_f32_16x16x32_bf16 v[108:111], v[174:177], v[214:217], v[108:111]
	v_mfma_f32_16x16x32_bf16 v[108:111], v[170:173], v[210:213], v[108:111]
	v_mfma_f32_16x16x32_bf16 v[92:95], v[170:173], v[222:225], v[92:95]
	v_mfma_f32_16x16x32_bf16 v[92:95], v[174:177], v[226:229], v[92:95]
	v_mfma_f32_16x16x32_bf16 v[88:91], v[182:185], v[226:229], v[88:91]
	v_mfma_f32_16x16x32_bf16 v[88:91], v[178:181], v[222:225], v[88:91]
	v_mfma_f32_16x16x32_bf16 v[84:87], v[186:189], v[222:225], v[84:87]
	v_mfma_f32_16x16x32_bf16 v[84:87], v[190:193], v[226:229], v[84:87]
	v_mfma_f32_16x16x32_bf16 v[80:83], v[198:201], v[226:229], v[80:83]
	v_mfma_f32_16x16x32_bf16 v[80:83], v[194:197], v[222:225], v[80:83]
	v_mfma_f32_16x16x32_bf16 v[64:67], v[194:197], v[230:233], v[64:67]
	v_mfma_f32_16x16x32_bf16 v[64:67], v[198:201], v[234:237], v[64:67]
	v_mfma_f32_16x16x32_bf16 v[68:71], v[190:193], v[234:237], v[68:71]
	v_mfma_f32_16x16x32_bf16 v[68:71], v[186:189], v[230:233], v[68:71]
	v_mfma_f32_16x16x32_bf16 v[72:75], v[178:181], v[230:233], v[72:75]
	v_mfma_f32_16x16x32_bf16 v[72:75], v[182:185], v[234:237], v[72:75]
	v_mfma_f32_16x16x32_bf16 v[76:79], v[174:177], v[234:237], v[76:79]
	v_mfma_f32_16x16x32_bf16 v[76:79], v[170:173], v[230:233], v[76:79]
	s_setprio 1
	s_barrier
	s_add_i32 s4, s9, s39
	v_lshl_add_u64 v[218:219], v[218:219], 0, s[24:25]
	s_mov_b32 m0, s4
	ds_read_b128 v[202:205], v166 offset:49152
	ds_read_b128 v[206:209], v166 offset:50176
	ds_read_b128 v[210:213], v166 offset:51200
	ds_read_b128 v[214:217], v166 offset:52224
	ds_read_b128 v[222:225], v166 offset:53248
	ds_read_b128 v[226:229], v166 offset:54272
	ds_read_b128 v[230:233], v166 offset:55296
	ds_read_b128 v[234:237], v166 offset:56320
	global_load_lds_dwordx4 v[218:219], off
	v_lshl_add_u64 v[218:219], v[238:239], 0, s[24:25]
	s_add_i32 m0, s4, 0x2000
	s_add_i32 s4, s10, s39
	global_load_lds_dwordx4 v[218:219], off
	v_lshl_add_u64 v[218:219], v[240:241], 0, s[24:25]
	s_mov_b32 m0, s4
	s_nop 0
	global_load_lds_dwordx4 v[218:219], off
	v_lshl_add_u64 v[218:219], v[242:243], 0, s[24:25]
	s_add_i32 m0, s4, 0x2000
	s_nop 0
	global_load_lds_dwordx4 v[218:219], off
	v_lshl_add_u64 v[218:219], v[244:245], 0, s[24:25]
	s_mov_b32 m0, s49
	s_nop 0
	global_load_lds_dwordx4 v[218:219], off
	v_lshl_add_u64 v[218:219], v[246:247], 0, s[24:25]
	s_mov_b32 m0, s50
	s_nop 0
	global_load_lds_dwordx4 v[218:219], off
	s_waitcnt vmcnt(8)
	s_waitcnt lgkmcnt(0)
	s_barrier
	s_waitcnt lgkmcnt(0)
	s_setprio 0
	v_mfma_f32_16x16x32_bf16 v[60:63], v[170:173], v[202:205], v[60:63]
	v_mfma_f32_16x16x32_bf16 v[60:63], v[174:177], v[206:209], v[60:63]
	v_mfma_f32_16x16x32_bf16 v[56:59], v[182:185], v[206:209], v[56:59]
	v_mfma_f32_16x16x32_bf16 v[56:59], v[178:181], v[202:205], v[56:59]
	v_mfma_f32_16x16x32_bf16 v[52:55], v[186:189], v[202:205], v[52:55]
	v_mfma_f32_16x16x32_bf16 v[52:55], v[190:193], v[206:209], v[52:55]
	v_mfma_f32_16x16x32_bf16 v[48:51], v[198:201], v[206:209], v[48:51]
	v_mfma_f32_16x16x32_bf16 v[48:51], v[194:197], v[202:205], v[48:51]
	v_mfma_f32_16x16x32_bf16 v[32:35], v[194:197], v[210:213], v[32:35]
	v_mfma_f32_16x16x32_bf16 v[32:35], v[198:201], v[214:217], v[32:35]
	v_mfma_f32_16x16x32_bf16 v[36:39], v[190:193], v[214:217], v[36:39]
	v_mfma_f32_16x16x32_bf16 v[36:39], v[186:189], v[210:213], v[36:39]
	v_mfma_f32_16x16x32_bf16 v[40:43], v[178:181], v[210:213], v[40:43]
	v_mfma_f32_16x16x32_bf16 v[40:43], v[182:185], v[214:217], v[40:43]
	v_mfma_f32_16x16x32_bf16 v[44:47], v[174:177], v[214:217], v[44:47]
	v_mfma_f32_16x16x32_bf16 v[44:47], v[170:173], v[210:213], v[44:47]
	v_mfma_f32_16x16x32_bf16 v[28:31], v[170:173], v[222:225], v[28:31]
	v_mfma_f32_16x16x32_bf16 v[28:31], v[174:177], v[226:229], v[28:31]
	v_mfma_f32_16x16x32_bf16 v[24:27], v[182:185], v[226:229], v[24:27]
	v_mfma_f32_16x16x32_bf16 v[24:27], v[178:181], v[222:225], v[24:27]
	v_mfma_f32_16x16x32_bf16 v[20:23], v[186:189], v[222:225], v[20:23]
	v_mfma_f32_16x16x32_bf16 v[20:23], v[190:193], v[226:229], v[20:23]
	v_mfma_f32_16x16x32_bf16 v[16:19], v[198:201], v[226:229], v[16:19]
	v_mfma_f32_16x16x32_bf16 v[16:19], v[194:197], v[222:225], v[16:19]
	v_mfma_f32_16x16x32_bf16 v[0:3], v[194:197], v[230:233], v[0:3]
	v_mfma_f32_16x16x32_bf16 v[0:3], v[198:201], v[234:237], v[0:3]
	v_mfma_f32_16x16x32_bf16 v[4:7], v[190:193], v[234:237], v[4:7]
	v_mfma_f32_16x16x32_bf16 v[4:7], v[186:189], v[230:233], v[4:7]
	v_mfma_f32_16x16x32_bf16 v[8:11], v[178:181], v[230:233], v[8:11]
	v_mfma_f32_16x16x32_bf16 v[8:11], v[182:185], v[234:237], v[8:11]
	v_mfma_f32_16x16x32_bf16 v[12:15], v[174:177], v[234:237], v[12:15]
	v_mfma_f32_16x16x32_bf16 v[12:15], v[170:173], v[230:233], v[12:15]
	s_setprio 1
	s_barrier
	s_add_u32 s2, s2, 0x100
	s_addc_u32 s3, s3, 0
	s_add_u32 s6, s6, 0x100
	s_addc_u32 s7, s7, 0
	s_cmp_ge_i32 s8, s51
	s_mov_b32 s4, s8
	s_cbranch_scc0 .LBB0_970

.LBB0_1056:
	ds_read_b128 v[140:143], v222
	ds_read_b128 v[144:147], v222 offset:1024
	ds_read_b128 v[148:151], v222 offset:2048
	ds_read_b128 v[152:155], v222 offset:3072
	ds_read_b128 v[156:159], v223
	ds_read_b128 v[160:163], v223 offset:1024
	ds_read_b128 v[164:167], v223 offset:2048
	ds_read_b128 v[168:171], v223 offset:3072
	s_add_i32 s62, s26, 2
	s_add_u32 s27, s24, 0x4000
	s_addc_u32 s28, s25, 0
	s_cmp_eq_u32 s46, s26
	s_cselect_b32 s30, s0, s27
	s_cselect_b32 s31, s1, s28
	s_cselect_b32 s28, s22, s60
	s_cselect_b32 s29, s23, s61
	s_add_u32 s26, s30, 0x8000
	s_addc_u32 s27, s31, 0
	v_lshl_add_u64 v[204:205], s[24:25], 0, v[132:133]
	s_add_i32 m0, s38, 0xc000
	ds_read_b128 v[172:175], v224
	ds_read_b128 v[176:179], v224 offset:1024
	ds_read_b128 v[180:183], v224 offset:2048
	ds_read_b128 v[184:187], v224 offset:3072
	ds_read_b128 v[188:191], v224 offset:4096
	ds_read_b128 v[192:195], v224 offset:5120
	ds_read_b128 v[196:199], v224 offset:6144
	ds_read_b128 v[200:203], v224 offset:7168
	global_load_lds_dwordx4 v[204:205], off
	v_lshl_add_u64 v[204:205], s[24:25], 0, v[134:135]
	s_add_i32 m0, s38, 0xe000
	s_nop 0
	global_load_lds_dwordx4 v[204:205], off
	s_waitcnt vmcnt(8)
	s_waitcnt lgkmcnt(0)
	s_barrier
	s_waitcnt lgkmcnt(0)
	s_setprio 0
	v_mfma_f32_16x16x32_bf16 v[124:127], v[140:143], v[172:175], v[124:127]
	v_mfma_f32_16x16x32_bf16 v[124:127], v[144:147], v[176:179], v[124:127]
	v_mfma_f32_16x16x32_bf16 v[120:123], v[152:155], v[176:179], v[120:123]
	v_mfma_f32_16x16x32_bf16 v[120:123], v[148:151], v[172:175], v[120:123]
	v_mfma_f32_16x16x32_bf16 v[108:111], v[156:159], v[172:175], v[108:111]
	v_mfma_f32_16x16x32_bf16 v[108:111], v[160:163], v[176:179], v[108:111]
	v_mfma_f32_16x16x32_bf16 v[100:103], v[168:171], v[176:179], v[100:103]
	v_mfma_f32_16x16x32_bf16 v[100:103], v[164:167], v[172:175], v[100:103]
	v_mfma_f32_16x16x32_bf16 v[84:87], v[164:167], v[180:183], v[84:87]
	v_mfma_f32_16x16x32_bf16 v[84:87], v[168:171], v[184:187], v[84:87]
	v_mfma_f32_16x16x32_bf16 v[92:95], v[160:163], v[184:187], v[92:95]
	v_mfma_f32_16x16x32_bf16 v[92:95], v[156:159], v[180:183], v[92:95]
	v_mfma_f32_16x16x32_bf16 v[112:115], v[148:151], v[180:183], v[112:115]
	v_mfma_f32_16x16x32_bf16 v[112:115], v[152:155], v[184:187], v[112:115]
	v_mfma_f32_16x16x32_bf16 v[116:119], v[144:147], v[184:187], v[116:119]
	v_mfma_f32_16x16x32_bf16 v[116:119], v[140:143], v[180:183], v[116:119]
	v_mfma_f32_16x16x32_bf16 v[104:107], v[140:143], v[188:191], v[104:107]
	v_mfma_f32_16x16x32_bf16 v[104:107], v[144:147], v[192:195], v[104:107]
	v_mfma_f32_16x16x32_bf16 v[96:99], v[152:155], v[192:195], v[96:99]
	v_mfma_f32_16x16x32_bf16 v[96:99], v[148:151], v[188:191], v[96:99]
	v_mfma_f32_16x16x32_bf16 v[76:79], v[156:159], v[188:191], v[76:79]
	v_mfma_f32_16x16x32_bf16 v[76:79], v[160:163], v[192:195], v[76:79]
	v_mfma_f32_16x16x32_bf16 v[72:75], v[168:171], v[192:195], v[72:75]
	v_mfma_f32_16x16x32_bf16 v[72:75], v[164:167], v[188:191], v[72:75]
	v_mfma_f32_16x16x32_bf16 v[64:67], v[164:167], v[196:199], v[64:67]
	v_mfma_f32_16x16x32_bf16 v[64:67], v[168:171], v[200:203], v[64:67]
	v_mfma_f32_16x16x32_bf16 v[68:71], v[160:163], v[200:203], v[68:71]
	v_mfma_f32_16x16x32_bf16 v[68:71], v[156:159], v[196:199], v[68:71]
	v_mfma_f32_16x16x32_bf16 v[80:83], v[148:151], v[196:199], v[80:83]
	v_mfma_f32_16x16x32_bf16 v[80:83], v[152:155], v[200:203], v[80:83]
	v_mfma_f32_16x16x32_bf16 v[88:91], v[144:147], v[200:203], v[88:91]
	v_mfma_f32_16x16x32_bf16 v[88:91], v[140:143], v[196:199], v[88:91]
	s_setprio 1
	s_barrier
	s_add_i32 s63, s50, s37
	v_lshl_add_u64 v[204:205], s[28:29], 0, v[128:129]
	s_mov_b32 m0, s63
	ds_read_b128 v[172:175], v224 offset:16384
	ds_read_b128 v[176:179], v224 offset:17408
	ds_read_b128 v[180:183], v224 offset:18432
	ds_read_b128 v[184:187], v224 offset:19456
	ds_read_b128 v[188:191], v224 offset:20480
	ds_read_b128 v[192:195], v224 offset:21504
	ds_read_b128 v[196:199], v224 offset:22528
	ds_read_b128 v[200:203], v224 offset:23552
	global_load_lds_dwordx4 v[204:205], off
	s_add_i32 m0, s63, 0x2000
	s_add_u32 s64, s28, 0x4000
	v_lshl_add_u64 v[204:205], s[28:29], 0, v[130:131]
	s_addc_u32 s65, s29, 0
	s_add_i32 s63, s51, s37
	global_load_lds_dwordx4 v[204:205], off
	v_lshl_add_u64 v[204:205], s[64:65], 0, v[128:129]
	s_mov_b32 m0, s63
	s_nop 0
	global_load_lds_dwordx4 v[204:205], off
	v_lshl_add_u64 v[204:205], s[64:65], 0, v[130:131]
	s_add_i32 m0, s63, 0x2000
	s_nop 0
	global_load_lds_dwordx4 v[204:205], off
	v_lshl_add_u64 v[204:205], s[30:31], 0, v[128:129]
	s_mov_b32 m0, s38
	s_nop 0
	global_load_lds_dwordx4 v[204:205], off
	v_lshl_add_u64 v[204:205], s[30:31], 0, v[130:131]
	s_mov_b32 m0, s39
	s_nop 0
	global_load_lds_dwordx4 v[204:205], off
	s_waitcnt vmcnt(8)
	s_waitcnt lgkmcnt(0)
	s_barrier
	s_waitcnt lgkmcnt(0)
	s_setprio 0
	v_mfma_f32_16x16x32_bf16 v[60:63], v[140:143], v[172:175], v[60:63]
	v_mfma_f32_16x16x32_bf16 v[60:63], v[144:147], v[176:179], v[60:63]
	v_mfma_f32_16x16x32_bf16 v[56:59], v[152:155], v[176:179], v[56:59]
	v_mfma_f32_16x16x32_bf16 v[56:59], v[148:151], v[172:175], v[56:59]
	v_mfma_f32_16x16x32_bf16 v[44:47], v[156:159], v[172:175], v[44:47]
	v_mfma_f32_16x16x32_bf16 v[44:47], v[160:163], v[176:179], v[44:47]
	v_mfma_f32_16x16x32_bf16 v[36:39], v[168:171], v[176:179], v[36:39]
	v_mfma_f32_16x16x32_bf16 v[36:39], v[164:167], v[172:175], v[36:39]
	v_mfma_f32_16x16x32_bf16 v[20:23], v[164:167], v[180:183], v[20:23]
	v_mfma_f32_16x16x32_bf16 v[20:23], v[168:171], v[184:187], v[20:23]
	v_mfma_f32_16x16x32_bf16 v[28:31], v[160:163], v[184:187], v[28:31]
	v_mfma_f32_16x16x32_bf16 v[28:31], v[156:159], v[180:183], v[28:31]
	v_mfma_f32_16x16x32_bf16 v[48:51], v[148:151], v[180:183], v[48:51]
	v_mfma_f32_16x16x32_bf16 v[48:51], v[152:155], v[184:187], v[48:51]
	v_mfma_f32_16x16x32_bf16 v[52:55], v[144:147], v[184:187], v[52:55]
	v_mfma_f32_16x16x32_bf16 v[52:55], v[140:143], v[180:183], v[52:55]
	v_mfma_f32_16x16x32_bf16 v[40:43], v[140:143], v[188:191], v[40:43]
	v_mfma_f32_16x16x32_bf16 v[40:43], v[144:147], v[192:195], v[40:43]
	v_mfma_f32_16x16x32_bf16 v[32:35], v[152:155], v[192:195], v[32:35]
	v_mfma_f32_16x16x32_bf16 v[32:35], v[148:151], v[188:191], v[32:35]
	v_mfma_f32_16x16x32_bf16 v[12:15], v[156:159], v[188:191], v[12:15]
	v_mfma_f32_16x16x32_bf16 v[12:15], v[160:163], v[192:195], v[12:15]
	v_mfma_f32_16x16x32_bf16 v[8:11], v[168:171], v[192:195], v[8:11]
	v_mfma_f32_16x16x32_bf16 v[8:11], v[164:167], v[188:191], v[8:11]
	v_mfma_f32_16x16x32_bf16 v[0:3], v[164:167], v[196:199], v[0:3]
	v_mfma_f32_16x16x32_bf16 v[0:3], v[168:171], v[200:203], v[0:3]
	v_mfma_f32_16x16x32_bf16 v[4:7], v[160:163], v[200:203], v[4:7]
	v_mfma_f32_16x16x32_bf16 v[4:7], v[156:159], v[196:199], v[4:7]
	v_mfma_f32_16x16x32_bf16 v[16:19], v[148:151], v[196:199], v[16:19]
	v_mfma_f32_16x16x32_bf16 v[16:19], v[152:155], v[200:203], v[16:19]
	v_mfma_f32_16x16x32_bf16 v[24:27], v[144:147], v[200:203], v[24:27]
	v_mfma_f32_16x16x32_bf16 v[24:27], v[140:143], v[196:199], v[24:27]
	s_setprio 1
	s_barrier
	s_add_i32 s63, 0, 0x18000
	s_add_i32 s64, 0, 0x1c000
	v_add_u32_e32 v152, s63, v219
	v_add_u32_e32 v168, s64, v219
	ds_read_b128 v[140:143], v152
	ds_read_b128 v[144:147], v152 offset:1024
	ds_read_b128 v[148:151], v152 offset:2048
	ds_read_b128 v[152:155], v152 offset:3072
	ds_read_b128 v[156:159], v168
	ds_read_b128 v[160:163], v168 offset:1024
	ds_read_b128 v[164:167], v168 offset:2048
	ds_read_b128 v[168:171], v168 offset:3072
	s_add_u32 s30, s30, 0x4000
	s_addc_u32 s31, s31, 0
	s_mov_b32 m0, s40
	v_lshl_add_u64 v[204:205], s[30:31], 0, v[128:129]
	ds_read_b128 v[172:175], v224 offset:32768
	ds_read_b128 v[176:179], v224 offset:33792
	ds_read_b128 v[180:183], v224 offset:34816
	ds_read_b128 v[184:187], v224 offset:35840
	ds_read_b128 v[188:191], v224 offset:36864
	ds_read_b128 v[192:195], v224 offset:37888
	ds_read_b128 v[196:199], v224 offset:38912
	ds_read_b128 v[200:203], v224 offset:39936
	global_load_lds_dwordx4 v[204:205], off
	v_lshl_add_u64 v[204:205], s[30:31], 0, v[130:131]
	s_mov_b32 m0, s41
	s_nop 0
	global_load_lds_dwordx4 v[204:205], off
	s_waitcnt vmcnt(8)
	s_waitcnt lgkmcnt(0)
	s_barrier
	s_waitcnt lgkmcnt(0)
	s_setprio 0
	v_mfma_f32_16x16x32_bf16 v[124:127], v[140:143], v[172:175], v[124:127]
	v_mfma_f32_16x16x32_bf16 v[124:127], v[144:147], v[176:179], v[124:127]
	v_mfma_f32_16x16x32_bf16 v[120:123], v[152:155], v[176:179], v[120:123]
	v_mfma_f32_16x16x32_bf16 v[120:123], v[148:151], v[172:175], v[120:123]
	v_mfma_f32_16x16x32_bf16 v[108:111], v[156:159], v[172:175], v[108:111]
	v_mfma_f32_16x16x32_bf16 v[108:111], v[160:163], v[176:179], v[108:111]
	v_mfma_f32_16x16x32_bf16 v[100:103], v[168:171], v[176:179], v[100:103]
	v_mfma_f32_16x16x32_bf16 v[100:103], v[164:167], v[172:175], v[100:103]
	v_mfma_f32_16x16x32_bf16 v[84:87], v[164:167], v[180:183], v[84:87]
	v_mfma_f32_16x16x32_bf16 v[84:87], v[168:171], v[184:187], v[84:87]
	v_mfma_f32_16x16x32_bf16 v[92:95], v[160:163], v[184:187], v[92:95]
	v_mfma_f32_16x16x32_bf16 v[92:95], v[156:159], v[180:183], v[92:95]
	v_mfma_f32_16x16x32_bf16 v[112:115], v[148:151], v[180:183], v[112:115]
	v_mfma_f32_16x16x32_bf16 v[112:115], v[152:155], v[184:187], v[112:115]
	v_mfma_f32_16x16x32_bf16 v[116:119], v[144:147], v[184:187], v[116:119]
	v_mfma_f32_16x16x32_bf16 v[116:119], v[140:143], v[180:183], v[116:119]
	v_mfma_f32_16x16x32_bf16 v[104:107], v[140:143], v[188:191], v[104:107]
	v_mfma_f32_16x16x32_bf16 v[104:107], v[144:147], v[192:195], v[104:107]
	v_mfma_f32_16x16x32_bf16 v[96:99], v[152:155], v[192:195], v[96:99]
	v_mfma_f32_16x16x32_bf16 v[96:99], v[148:151], v[188:191], v[96:99]
	v_mfma_f32_16x16x32_bf16 v[76:79], v[156:159], v[188:191], v[76:79]
	v_mfma_f32_16x16x32_bf16 v[76:79], v[160:163], v[192:195], v[76:79]
	v_mfma_f32_16x16x32_bf16 v[72:75], v[168:171], v[192:195], v[72:75]
	v_mfma_f32_16x16x32_bf16 v[72:75], v[164:167], v[188:191], v[72:75]
	v_mfma_f32_16x16x32_bf16 v[64:67], v[164:167], v[196:199], v[64:67]
	v_mfma_f32_16x16x32_bf16 v[64:67], v[168:171], v[200:203], v[64:67]
	v_mfma_f32_16x16x32_bf16 v[68:71], v[160:163], v[200:203], v[68:71]
	v_mfma_f32_16x16x32_bf16 v[68:71], v[156:159], v[196:199], v[68:71]
	v_mfma_f32_16x16x32_bf16 v[80:83], v[148:151], v[196:199], v[80:83]
	v_mfma_f32_16x16x32_bf16 v[80:83], v[152:155], v[200:203], v[80:83]
	v_mfma_f32_16x16x32_bf16 v[88:91], v[144:147], v[200:203], v[88:91]
	v_mfma_f32_16x16x32_bf16 v[88:91], v[140:143], v[196:199], v[88:91]
	s_setprio 1
	s_barrier
	s_add_u32 s30, s28, 0x8000
	s_addc_u32 s31, s29, 0
	s_add_i32 s63, s63, s37
	v_lshl_add_u64 v[204:205], s[30:31], 0, v[128:129]
	s_mov_b32 m0, s63
	ds_read_b128 v[172:175], v224 offset:49152
	ds_read_b128 v[176:179], v224 offset:50176
	ds_read_b128 v[180:183], v224 offset:51200
	ds_read_b128 v[184:187], v224 offset:52224
	ds_read_b128 v[188:191], v224 offset:53248
	ds_read_b128 v[192:195], v224 offset:54272
	ds_read_b128 v[196:199], v224 offset:55296
	ds_read_b128 v[200:203], v224 offset:56320
	global_load_lds_dwordx4 v[204:205], off
	s_add_i32 m0, s63, 0x2000
	s_add_u32 s28, s28, 0xc000
	v_lshl_add_u64 v[204:205], s[30:31], 0, v[130:131]
	s_addc_u32 s29, s29, 0
	s_add_i32 s30, s64, s37
	global_load_lds_dwordx4 v[204:205], off
	v_lshl_add_u64 v[204:205], s[28:29], 0, v[128:129]
	s_mov_b32 m0, s30
	s_nop 0
	global_load_lds_dwordx4 v[204:205], off
	v_lshl_add_u64 v[204:205], s[28:29], 0, v[130:131]
	s_add_i32 m0, s30, 0x2000
	s_nop 0
	global_load_lds_dwordx4 v[204:205], off
	v_lshl_add_u64 v[204:205], s[26:27], 0, v[128:129]
	s_mov_b32 m0, s44
	s_nop 0
	global_load_lds_dwordx4 v[204:205], off
	v_lshl_add_u64 v[204:205], s[26:27], 0, v[130:131]
	s_mov_b32 m0, s45
	s_nop 0
	global_load_lds_dwordx4 v[204:205], off
	s_waitcnt vmcnt(8)
	s_waitcnt lgkmcnt(0)
	s_barrier
	s_waitcnt lgkmcnt(0)
	s_setprio 0
	v_mfma_f32_16x16x32_bf16 v[60:63], v[140:143], v[172:175], v[60:63]
	v_mfma_f32_16x16x32_bf16 v[60:63], v[144:147], v[176:179], v[60:63]
	v_mfma_f32_16x16x32_bf16 v[56:59], v[152:155], v[176:179], v[56:59]
	v_mfma_f32_16x16x32_bf16 v[56:59], v[148:151], v[172:175], v[56:59]
	v_mfma_f32_16x16x32_bf16 v[44:47], v[156:159], v[172:175], v[44:47]
	v_mfma_f32_16x16x32_bf16 v[44:47], v[160:163], v[176:179], v[44:47]
	v_mfma_f32_16x16x32_bf16 v[36:39], v[168:171], v[176:179], v[36:39]
	v_mfma_f32_16x16x32_bf16 v[36:39], v[164:167], v[172:175], v[36:39]
	v_mfma_f32_16x16x32_bf16 v[20:23], v[164:167], v[180:183], v[20:23]
	v_mfma_f32_16x16x32_bf16 v[20:23], v[168:171], v[184:187], v[20:23]
	v_mfma_f32_16x16x32_bf16 v[28:31], v[160:163], v[184:187], v[28:31]
	v_mfma_f32_16x16x32_bf16 v[28:31], v[156:159], v[180:183], v[28:31]
	v_mfma_f32_16x16x32_bf16 v[48:51], v[148:151], v[180:183], v[48:51]
	v_mfma_f32_16x16x32_bf16 v[48:51], v[152:155], v[184:187], v[48:51]
	v_mfma_f32_16x16x32_bf16 v[52:55], v[144:147], v[184:187], v[52:55]
	v_mfma_f32_16x16x32_bf16 v[52:55], v[140:143], v[180:183], v[52:55]
	v_mfma_f32_16x16x32_bf16 v[40:43], v[140:143], v[188:191], v[40:43]
	v_mfma_f32_16x16x32_bf16 v[40:43], v[144:147], v[192:195], v[40:43]
	v_mfma_f32_16x16x32_bf16 v[32:35], v[152:155], v[192:195], v[32:35]
	v_mfma_f32_16x16x32_bf16 v[32:35], v[148:151], v[188:191], v[32:35]
	v_mfma_f32_16x16x32_bf16 v[12:15], v[156:159], v[188:191], v[12:15]
	v_mfma_f32_16x16x32_bf16 v[12:15], v[160:163], v[192:195], v[12:15]
	v_mfma_f32_16x16x32_bf16 v[8:11], v[168:171], v[192:195], v[8:11]
	v_mfma_f32_16x16x32_bf16 v[8:11], v[164:167], v[188:191], v[8:11]
	v_mfma_f32_16x16x32_bf16 v[0:3], v[164:167], v[196:199], v[0:3]
	v_mfma_f32_16x16x32_bf16 v[0:3], v[168:171], v[200:203], v[0:3]
	v_mfma_f32_16x16x32_bf16 v[4:7], v[160:163], v[200:203], v[4:7]
	v_mfma_f32_16x16x32_bf16 v[4:7], v[156:159], v[196:199], v[4:7]
	v_mfma_f32_16x16x32_bf16 v[16:19], v[148:151], v[196:199], v[16:19]
	v_mfma_f32_16x16x32_bf16 v[16:19], v[152:155], v[200:203], v[16:19]
	v_mfma_f32_16x16x32_bf16 v[24:27], v[144:147], v[200:203], v[24:27]
	v_mfma_f32_16x16x32_bf16 v[24:27], v[140:143], v[196:199], v[24:27]
	s_setprio 1
	s_barrier
	s_add_u32 s24, s24, 0x10000
	s_addc_u32 s25, s25, 0
	s_add_u32 s60, s60, 0x10000
	s_addc_u32 s61, s61, 0
	s_cmp_ge_i32 s62, s43
	s_mov_b32 s26, s62
	s_cbranch_scc0 .LBB0_1056
	v_pk_mul_f32 v[198:199], v[126:127], 0.5 op_sel_hi:[1,0]
	v_pk_mul_f32 v[200:201], v[124:125], 0.5 op_sel_hi:[1,0]
	v_pk_mul_f32 v[202:203], v[122:123], 0.5 op_sel_hi:[1,0]
	v_pk_mul_f32 v[204:205], v[120:121], 0.5 op_sel_hi:[1,0]
	v_pk_mul_f32 v[208:209], v[110:111], 0.5 op_sel_hi:[1,0]
	v_pk_mul_f32 v[206:207], v[108:109], 0.5 op_sel_hi:[1,0]
	v_pk_mul_f32 v[196:197], v[102:103], 0.5 op_sel_hi:[1,0]
	v_pk_mul_f32 v[194:195], v[100:101], 0.5 op_sel_hi:[1,0]
	v_pk_mul_f32 v[192:193], v[118:119], 0.5 op_sel_hi:[1,0]
	v_pk_mul_f32 v[190:191], v[116:117], 0.5 op_sel_hi:[1,0]
	v_pk_mul_f32 v[188:189], v[114:115], 0.5 op_sel_hi:[1,0]
	v_pk_mul_f32 v[186:187], v[112:113], 0.5 op_sel_hi:[1,0]
	v_pk_mul_f32 v[184:185], v[94:95], 0.5 op_sel_hi:[1,0]
	v_pk_mul_f32 v[182:183], v[92:93], 0.5 op_sel_hi:[1,0]
	v_pk_mul_f32 v[180:181], v[86:87], 0.5 op_sel_hi:[1,0]
	v_pk_mul_f32 v[178:179], v[84:85], 0.5 op_sel_hi:[1,0]
	v_pk_mul_f32 v[176:177], v[106:107], 0.5 op_sel_hi:[1,0]
	v_pk_mul_f32 v[174:175], v[104:105], 0.5 op_sel_hi:[1,0]
	v_pk_mul_f32 v[172:173], v[98:99], 0.5 op_sel_hi:[1,0]
	v_pk_mul_f32 v[170:171], v[96:97], 0.5 op_sel_hi:[1,0]
	v_pk_mul_f32 v[168:169], v[78:79], 0.5 op_sel_hi:[1,0]
	v_pk_mul_f32 v[166:167], v[76:77], 0.5 op_sel_hi:[1,0]
	v_pk_mul_f32 v[164:165], v[74:75], 0.5 op_sel_hi:[1,0]
	v_pk_mul_f32 v[162:163], v[72:73], 0.5 op_sel_hi:[1,0]
	v_pk_mul_f32 v[160:161], v[90:91], 0.5 op_sel_hi:[1,0]
	v_pk_mul_f32 v[158:159], v[88:89], 0.5 op_sel_hi:[1,0]
	v_pk_mul_f32 v[156:157], v[82:83], 0.5 op_sel_hi:[1,0]
	v_pk_mul_f32 v[154:155], v[80:81], 0.5 op_sel_hi:[1,0]
	v_pk_mul_f32 v[152:153], v[70:71], 0.5 op_sel_hi:[1,0]
	v_pk_mul_f32 v[150:151], v[68:69], 0.5 op_sel_hi:[1,0]
	v_pk_mul_f32 v[148:149], v[66:67], 0.5 op_sel_hi:[1,0]
	v_pk_mul_f32 v[146:147], v[64:65], 0.5 op_sel_hi:[1,0]
	v_pk_mul_f32 v[142:143], v[62:63], 0.5 op_sel_hi:[1,0]
	v_pk_mul_f32 v[140:141], v[60:61], 0.5 op_sel_hi:[1,0]
	v_pk_mul_f32 v[126:127], v[58:59], 0.5 op_sel_hi:[1,0]
	v_pk_mul_f32 v[124:125], v[56:57], 0.5 op_sel_hi:[1,0]
	v_pk_mul_f32 v[122:123], v[46:47], 0.5 op_sel_hi:[1,0]
	v_pk_mul_f32 v[120:121], v[44:45], 0.5 op_sel_hi:[1,0]
	v_pk_mul_f32 v[118:119], v[38:39], 0.5 op_sel_hi:[1,0]
	v_pk_mul_f32 v[116:117], v[36:37], 0.5 op_sel_hi:[1,0]
	v_pk_mul_f32 v[114:115], v[54:55], 0.5 op_sel_hi:[1,0]
	v_pk_mul_f32 v[112:113], v[52:53], 0.5 op_sel_hi:[1,0]
	v_pk_mul_f32 v[110:111], v[50:51], 0.5 op_sel_hi:[1,0]
	v_pk_mul_f32 v[108:109], v[48:49], 0.5 op_sel_hi:[1,0]
	v_pk_mul_f32 v[106:107], v[30:31], 0.5 op_sel_hi:[1,0]
	v_pk_mul_f32 v[104:105], v[28:29], 0.5 op_sel_hi:[1,0]
	v_pk_mul_f32 v[102:103], v[22:23], 0.5 op_sel_hi:[1,0]
	v_pk_mul_f32 v[100:101], v[20:21], 0.5 op_sel_hi:[1,0]
	v_pk_mul_f32 v[98:99], v[42:43], 0.5 op_sel_hi:[1,0]
	v_pk_mul_f32 v[96:97], v[40:41], 0.5 op_sel_hi:[1,0]
	v_pk_mul_f32 v[94:95], v[34:35], 0.5 op_sel_hi:[1,0]
	v_pk_mul_f32 v[92:93], v[32:33], 0.5 op_sel_hi:[1,0]
	v_pk_mul_f32 v[90:91], v[14:15], 0.5 op_sel_hi:[1,0]
	v_pk_mul_f32 v[88:89], v[12:13], 0.5 op_sel_hi:[1,0]
	v_pk_mul_f32 v[86:87], v[10:11], 0.5 op_sel_hi:[1,0]
	v_pk_mul_f32 v[84:85], v[8:9], 0.5 op_sel_hi:[1,0]
	v_pk_mul_f32 v[82:83], v[26:27], 0.5 op_sel_hi:[1,0]
	v_pk_mul_f32 v[80:81], v[24:25], 0.5 op_sel_hi:[1,0]
	v_pk_mul_f32 v[78:79], v[18:19], 0.5 op_sel_hi:[1,0]
	v_pk_mul_f32 v[76:77], v[16:17], 0.5 op_sel_hi:[1,0]
	v_pk_mul_f32 v[74:75], v[6:7], 0.5 op_sel_hi:[1,0]
	v_pk_mul_f32 v[72:73], v[4:5], 0.5 op_sel_hi:[1,0]
	v_pk_mul_f32 v[70:71], v[2:3], 0.5 op_sel_hi:[1,0]
	v_pk_mul_f32 v[68:69], v[0:1], 0.5 op_sel_hi:[1,0]

.LBB0_1159:
	ds_read_b128 v[128:131], v205
	ds_read_b128 v[132:135], v205 offset:1024
	ds_read_b128 v[136:139], v205 offset:2048
	ds_read_b128 v[140:143], v205 offset:3072
	ds_read_b128 v[144:147], v206
	ds_read_b128 v[160:163], v206 offset:1024
	ds_read_b128 v[164:167], v206 offset:2048
	ds_read_b128 v[168:171], v206 offset:3072
	s_add_i32 s41, s6, 2
	s_add_u32 s68, s0, 0x80
	s_addc_u32 s7, s1, 0
	s_cmp_eq_u32 s57, s6
	s_cselect_b32 s6, s34, s68
	s_cselect_b32 s7, s35, s7
	s_cselect_b32 s69, s37, s39
	s_cselect_b32 s68, s36, s38
	v_lshl_add_u64 v[200:201], s[0:1], 0, v[152:153]
	s_add_i32 m0, s47, 0xc000
	ds_read_b128 v[172:175], v207
	ds_read_b128 v[176:179], v207 offset:1024
	ds_read_b128 v[180:183], v207 offset:2048
	ds_read_b128 v[184:187], v207 offset:3072
	ds_read_b128 v[188:191], v207 offset:4096
	ds_read_b128 v[192:195], v207 offset:5120
	ds_read_b128 v[196:199], v207 offset:6144
	ds_read_b128 v[212:215], v207 offset:7168
	global_load_lds_dwordx4 v[200:201], off
	v_lshl_add_u64 v[200:201], s[0:1], 0, v[154:155]
	s_add_i32 m0, s47, 0xe000
	s_nop 0
	global_load_lds_dwordx4 v[200:201], off
	s_waitcnt vmcnt(8)
	s_waitcnt lgkmcnt(0)
	s_barrier
	s_waitcnt lgkmcnt(0)
	s_setprio 0
	v_mfma_f32_16x16x32_bf16 v[124:127], v[128:131], v[172:175], v[124:127]
	v_mfma_f32_16x16x32_bf16 v[124:127], v[132:135], v[176:179], v[124:127]
	v_mfma_f32_16x16x32_bf16 v[120:123], v[140:143], v[176:179], v[120:123]
	v_mfma_f32_16x16x32_bf16 v[120:123], v[136:139], v[172:175], v[120:123]
	v_mfma_f32_16x16x32_bf16 v[116:119], v[144:147], v[172:175], v[116:119]
	v_mfma_f32_16x16x32_bf16 v[116:119], v[160:163], v[176:179], v[116:119]
	v_mfma_f32_16x16x32_bf16 v[112:115], v[168:171], v[176:179], v[112:115]
	v_mfma_f32_16x16x32_bf16 v[112:115], v[164:167], v[172:175], v[112:115]
	v_mfma_f32_16x16x32_bf16 v[96:99], v[164:167], v[180:183], v[96:99]
	v_mfma_f32_16x16x32_bf16 v[96:99], v[168:171], v[184:187], v[96:99]
	v_mfma_f32_16x16x32_bf16 v[100:103], v[160:163], v[184:187], v[100:103]
	v_mfma_f32_16x16x32_bf16 v[100:103], v[144:147], v[180:183], v[100:103]
	v_mfma_f32_16x16x32_bf16 v[104:107], v[136:139], v[180:183], v[104:107]
	v_mfma_f32_16x16x32_bf16 v[104:107], v[140:143], v[184:187], v[104:107]
	v_mfma_f32_16x16x32_bf16 v[108:111], v[132:135], v[184:187], v[108:111]
	v_mfma_f32_16x16x32_bf16 v[108:111], v[128:131], v[180:183], v[108:111]
	v_mfma_f32_16x16x32_bf16 v[92:95], v[128:131], v[188:191], v[92:95]
	v_mfma_f32_16x16x32_bf16 v[92:95], v[132:135], v[192:195], v[92:95]
	v_mfma_f32_16x16x32_bf16 v[88:91], v[140:143], v[192:195], v[88:91]
	v_mfma_f32_16x16x32_bf16 v[88:91], v[136:139], v[188:191], v[88:91]
	v_mfma_f32_16x16x32_bf16 v[84:87], v[144:147], v[188:191], v[84:87]
	v_mfma_f32_16x16x32_bf16 v[84:87], v[160:163], v[192:195], v[84:87]
	v_mfma_f32_16x16x32_bf16 v[80:83], v[168:171], v[192:195], v[80:83]
	v_mfma_f32_16x16x32_bf16 v[80:83], v[164:167], v[188:191], v[80:83]
	v_mfma_f32_16x16x32_bf16 v[64:67], v[164:167], v[196:199], v[64:67]
	v_mfma_f32_16x16x32_bf16 v[64:67], v[168:171], v[212:215], v[64:67]
	v_mfma_f32_16x16x32_bf16 v[68:71], v[160:163], v[212:215], v[68:71]
	v_mfma_f32_16x16x32_bf16 v[68:71], v[144:147], v[196:199], v[68:71]
	v_mfma_f32_16x16x32_bf16 v[72:75], v[136:139], v[196:199], v[72:75]
	v_mfma_f32_16x16x32_bf16 v[72:75], v[140:143], v[212:215], v[72:75]
	v_mfma_f32_16x16x32_bf16 v[76:79], v[132:135], v[212:215], v[76:79]
	v_mfma_f32_16x16x32_bf16 v[76:79], v[128:131], v[196:199], v[76:79]
	s_setprio 1
	s_barrier
	s_add_i32 s70, s60, s46
	v_lshl_add_u64 v[200:201], s[68:69], 0, v[148:149]
	s_mov_b32 m0, s70
	ds_read_b128 v[172:175], v207 offset:16384
	ds_read_b128 v[176:179], v207 offset:17408
	ds_read_b128 v[180:183], v207 offset:18432
	ds_read_b128 v[184:187], v207 offset:19456
	ds_read_b128 v[188:191], v207 offset:20480
	ds_read_b128 v[192:195], v207 offset:21504
	ds_read_b128 v[196:199], v207 offset:22528
	ds_read_b128 v[212:215], v207 offset:23552
	global_load_lds_dwordx4 v[200:201], off
	s_add_i32 m0, s70, 0x2000
	v_lshl_add_u64 v[216:217], s[68:69], 0, v[150:151]
	s_add_u32 s68, s68, s10
	s_addc_u32 s69, s69, s11
	s_add_i32 s70, s61, s46
	global_load_lds_dwordx4 v[216:217], off
	v_lshl_add_u64 v[218:219], s[68:69], 0, v[148:149]
	s_mov_b32 m0, s70
	v_lshl_add_u64 v[220:221], s[68:69], 0, v[150:151]
	global_load_lds_dwordx4 v[218:219], off
	s_add_i32 m0, s70, 0x2000
	v_lshl_add_u64 v[222:223], s[6:7], 0, v[148:149]
	global_load_lds_dwordx4 v[220:221], off
	s_mov_b32 m0, s47
	v_lshl_add_u64 v[224:225], s[6:7], 0, v[150:151]
	global_load_lds_dwordx4 v[222:223], off
	s_mov_b32 m0, s48
	s_nop 0
	global_load_lds_dwordx4 v[224:225], off
	s_waitcnt vmcnt(8)
	s_waitcnt lgkmcnt(0)
	s_barrier
	s_waitcnt lgkmcnt(0)
	s_setprio 0
	v_mfma_f32_16x16x32_bf16 v[60:63], v[128:131], v[172:175], v[60:63]
	v_mfma_f32_16x16x32_bf16 v[60:63], v[132:135], v[176:179], v[60:63]
	v_mfma_f32_16x16x32_bf16 v[56:59], v[140:143], v[176:179], v[56:59]
	v_mfma_f32_16x16x32_bf16 v[56:59], v[136:139], v[172:175], v[56:59]
	v_mfma_f32_16x16x32_bf16 v[52:55], v[144:147], v[172:175], v[52:55]
	v_mfma_f32_16x16x32_bf16 v[52:55], v[160:163], v[176:179], v[52:55]
	v_mfma_f32_16x16x32_bf16 v[48:51], v[168:171], v[176:179], v[48:51]
	v_mfma_f32_16x16x32_bf16 v[48:51], v[164:167], v[172:175], v[48:51]
	v_mfma_f32_16x16x32_bf16 v[32:35], v[164:167], v[180:183], v[32:35]
	v_mfma_f32_16x16x32_bf16 v[32:35], v[168:171], v[184:187], v[32:35]
	v_mfma_f32_16x16x32_bf16 v[36:39], v[160:163], v[184:187], v[36:39]
	v_mfma_f32_16x16x32_bf16 v[36:39], v[144:147], v[180:183], v[36:39]
	v_mfma_f32_16x16x32_bf16 v[40:43], v[136:139], v[180:183], v[40:43]
	v_mfma_f32_16x16x32_bf16 v[40:43], v[140:143], v[184:187], v[40:43]
	v_mfma_f32_16x16x32_bf16 v[44:47], v[132:135], v[184:187], v[44:47]
	v_mfma_f32_16x16x32_bf16 v[44:47], v[128:131], v[180:183], v[44:47]
	v_mfma_f32_16x16x32_bf16 v[28:31], v[128:131], v[188:191], v[28:31]
	v_mfma_f32_16x16x32_bf16 v[28:31], v[132:135], v[192:195], v[28:31]
	v_mfma_f32_16x16x32_bf16 v[24:27], v[140:143], v[192:195], v[24:27]
	v_mfma_f32_16x16x32_bf16 v[24:27], v[136:139], v[188:191], v[24:27]
	v_mfma_f32_16x16x32_bf16 v[20:23], v[144:147], v[188:191], v[20:23]
	v_mfma_f32_16x16x32_bf16 v[20:23], v[160:163], v[192:195], v[20:23]
	v_mfma_f32_16x16x32_bf16 v[16:19], v[168:171], v[192:195], v[16:19]
	v_mfma_f32_16x16x32_bf16 v[16:19], v[164:167], v[188:191], v[16:19]
	v_mfma_f32_16x16x32_bf16 v[0:3], v[164:167], v[196:199], v[0:3]
	v_mfma_f32_16x16x32_bf16 v[0:3], v[168:171], v[212:215], v[0:3]
	v_mfma_f32_16x16x32_bf16 v[4:7], v[160:163], v[212:215], v[4:7]
	v_mfma_f32_16x16x32_bf16 v[4:7], v[144:147], v[196:199], v[4:7]
	v_mfma_f32_16x16x32_bf16 v[8:11], v[136:139], v[196:199], v[8:11]
	v_mfma_f32_16x16x32_bf16 v[8:11], v[140:143], v[212:215], v[8:11]
	v_mfma_f32_16x16x32_bf16 v[12:15], v[132:135], v[212:215], v[12:15]
	v_mfma_f32_16x16x32_bf16 v[12:15], v[128:131], v[196:199], v[12:15]
	s_setprio 1
	s_barrier
	s_add_i32 s68, 0, 0x18000
	s_add_i32 s69, 0, 0x1c000
	v_add_u32_e32 v140, s68, v203
	v_add_u32_e32 v168, s69, v203
	ds_read_b128 v[128:131], v140
	ds_read_b128 v[132:135], v140 offset:1024
	ds_read_b128 v[136:139], v140 offset:2048
	ds_read_b128 v[140:143], v140 offset:3072
	ds_read_b128 v[144:147], v168
	ds_read_b128 v[160:163], v168 offset:1024
	ds_read_b128 v[164:167], v168 offset:2048
	ds_read_b128 v[168:171], v168 offset:3072
	s_add_u32 s6, s6, s10
	s_addc_u32 s7, s7, s11
	s_mov_b32 m0, s49
	v_lshl_add_u64 v[226:227], s[6:7], 0, v[148:149]
	ds_read_b128 v[172:175], v207 offset:32768
	ds_read_b128 v[176:179], v207 offset:33792
	ds_read_b128 v[180:183], v207 offset:34816
	ds_read_b128 v[184:187], v207 offset:35840
	ds_read_b128 v[188:191], v207 offset:36864
	ds_read_b128 v[192:195], v207 offset:37888
	ds_read_b128 v[196:199], v207 offset:38912
	ds_read_b128 v[212:215], v207 offset:39936
	global_load_lds_dwordx4 v[226:227], off
	v_lshl_add_u64 v[226:227], s[6:7], 0, v[150:151]
	s_mov_b32 m0, s50
	s_nop 0
	global_load_lds_dwordx4 v[226:227], off
	s_waitcnt vmcnt(8)
	s_waitcnt lgkmcnt(0)
	s_barrier
	s_waitcnt lgkmcnt(0)
	s_setprio 0
	v_mfma_f32_16x16x32_bf16 v[124:127], v[128:131], v[172:175], v[124:127]
	v_mfma_f32_16x16x32_bf16 v[124:127], v[132:135], v[176:179], v[124:127]
	v_mfma_f32_16x16x32_bf16 v[120:123], v[140:143], v[176:179], v[120:123]
	v_mfma_f32_16x16x32_bf16 v[120:123], v[136:139], v[172:175], v[120:123]
	v_mfma_f32_16x16x32_bf16 v[116:119], v[144:147], v[172:175], v[116:119]
	v_mfma_f32_16x16x32_bf16 v[116:119], v[160:163], v[176:179], v[116:119]
	v_mfma_f32_16x16x32_bf16 v[112:115], v[168:171], v[176:179], v[112:115]
	v_mfma_f32_16x16x32_bf16 v[112:115], v[164:167], v[172:175], v[112:115]
	v_mfma_f32_16x16x32_bf16 v[96:99], v[164:167], v[180:183], v[96:99]
	v_mfma_f32_16x16x32_bf16 v[96:99], v[168:171], v[184:187], v[96:99]
	v_mfma_f32_16x16x32_bf16 v[100:103], v[160:163], v[184:187], v[100:103]
	v_mfma_f32_16x16x32_bf16 v[100:103], v[144:147], v[180:183], v[100:103]
	v_mfma_f32_16x16x32_bf16 v[104:107], v[136:139], v[180:183], v[104:107]
	v_mfma_f32_16x16x32_bf16 v[104:107], v[140:143], v[184:187], v[104:107]
	v_mfma_f32_16x16x32_bf16 v[108:111], v[132:135], v[184:187], v[108:111]
	v_mfma_f32_16x16x32_bf16 v[108:111], v[128:131], v[180:183], v[108:111]
	v_mfma_f32_16x16x32_bf16 v[92:95], v[128:131], v[188:191], v[92:95]
	v_mfma_f32_16x16x32_bf16 v[92:95], v[132:135], v[192:195], v[92:95]
	v_mfma_f32_16x16x32_bf16 v[88:91], v[140:143], v[192:195], v[88:91]
	v_mfma_f32_16x16x32_bf16 v[88:91], v[136:139], v[188:191], v[88:91]
	v_mfma_f32_16x16x32_bf16 v[84:87], v[144:147], v[188:191], v[84:87]
	v_mfma_f32_16x16x32_bf16 v[84:87], v[160:163], v[192:195], v[84:87]
	v_mfma_f32_16x16x32_bf16 v[80:83], v[168:171], v[192:195], v[80:83]
	v_mfma_f32_16x16x32_bf16 v[80:83], v[164:167], v[188:191], v[80:83]
	v_mfma_f32_16x16x32_bf16 v[64:67], v[164:167], v[196:199], v[64:67]
	v_mfma_f32_16x16x32_bf16 v[64:67], v[168:171], v[212:215], v[64:67]
	v_mfma_f32_16x16x32_bf16 v[68:71], v[160:163], v[212:215], v[68:71]
	v_mfma_f32_16x16x32_bf16 v[68:71], v[144:147], v[196:199], v[68:71]
	v_mfma_f32_16x16x32_bf16 v[72:75], v[136:139], v[196:199], v[72:75]
	v_mfma_f32_16x16x32_bf16 v[72:75], v[140:143], v[212:215], v[72:75]
	v_mfma_f32_16x16x32_bf16 v[76:79], v[132:135], v[212:215], v[76:79]
	v_mfma_f32_16x16x32_bf16 v[76:79], v[128:131], v[196:199], v[76:79]
	s_setprio 1
	s_barrier
	s_add_i32 s6, s68, s46
	v_lshl_add_u64 v[200:201], v[200:201], 0, s[20:21]
	s_mov_b32 m0, s6
	ds_read_b128 v[172:175], v207 offset:49152
	ds_read_b128 v[176:179], v207 offset:50176
	ds_read_b128 v[180:183], v207 offset:51200
	ds_read_b128 v[184:187], v207 offset:52224
	ds_read_b128 v[188:191], v207 offset:53248
	ds_read_b128 v[192:195], v207 offset:54272
	ds_read_b128 v[196:199], v207 offset:55296
	ds_read_b128 v[212:215], v207 offset:56320
	global_load_lds_dwordx4 v[200:201], off
	v_lshl_add_u64 v[200:201], v[216:217], 0, s[20:21]
	s_add_i32 m0, s6, 0x2000
	s_add_i32 s6, s69, s46
	global_load_lds_dwordx4 v[200:201], off
	v_lshl_add_u64 v[200:201], v[218:219], 0, s[20:21]
	s_mov_b32 m0, s6
	s_nop 0
	global_load_lds_dwordx4 v[200:201], off
	v_lshl_add_u64 v[200:201], v[220:221], 0, s[20:21]
	s_add_i32 m0, s6, 0x2000
	s_nop 0
	global_load_lds_dwordx4 v[200:201], off
	v_lshl_add_u64 v[200:201], v[222:223], 0, s[20:21]
	s_mov_b32 m0, s54
	s_nop 0
	global_load_lds_dwordx4 v[200:201], off
	v_lshl_add_u64 v[200:201], v[224:225], 0, s[20:21]
	s_mov_b32 m0, s55
	s_nop 0
	global_load_lds_dwordx4 v[200:201], off
	s_waitcnt vmcnt(8)
	s_waitcnt lgkmcnt(0)
	s_barrier
	s_waitcnt lgkmcnt(0)
	s_setprio 0
	v_mfma_f32_16x16x32_bf16 v[60:63], v[128:131], v[172:175], v[60:63]
	v_mfma_f32_16x16x32_bf16 v[60:63], v[132:135], v[176:179], v[60:63]
	v_mfma_f32_16x16x32_bf16 v[56:59], v[140:143], v[176:179], v[56:59]
	v_mfma_f32_16x16x32_bf16 v[56:59], v[136:139], v[172:175], v[56:59]
	v_mfma_f32_16x16x32_bf16 v[52:55], v[144:147], v[172:175], v[52:55]
	v_mfma_f32_16x16x32_bf16 v[52:55], v[160:163], v[176:179], v[52:55]
	v_mfma_f32_16x16x32_bf16 v[48:51], v[168:171], v[176:179], v[48:51]
	v_mfma_f32_16x16x32_bf16 v[48:51], v[164:167], v[172:175], v[48:51]
	v_mfma_f32_16x16x32_bf16 v[32:35], v[164:167], v[180:183], v[32:35]
	v_mfma_f32_16x16x32_bf16 v[32:35], v[168:171], v[184:187], v[32:35]
	v_mfma_f32_16x16x32_bf16 v[36:39], v[160:163], v[184:187], v[36:39]
	v_mfma_f32_16x16x32_bf16 v[36:39], v[144:147], v[180:183], v[36:39]
	v_mfma_f32_16x16x32_bf16 v[40:43], v[136:139], v[180:183], v[40:43]
	v_mfma_f32_16x16x32_bf16 v[40:43], v[140:143], v[184:187], v[40:43]
	v_mfma_f32_16x16x32_bf16 v[44:47], v[132:135], v[184:187], v[44:47]
	v_mfma_f32_16x16x32_bf16 v[44:47], v[128:131], v[180:183], v[44:47]
	v_mfma_f32_16x16x32_bf16 v[28:31], v[128:131], v[188:191], v[28:31]
	v_mfma_f32_16x16x32_bf16 v[28:31], v[132:135], v[192:195], v[28:31]
	v_mfma_f32_16x16x32_bf16 v[24:27], v[140:143], v[192:195], v[24:27]
	v_mfma_f32_16x16x32_bf16 v[24:27], v[136:139], v[188:191], v[24:27]
	v_mfma_f32_16x16x32_bf16 v[20:23], v[144:147], v[188:191], v[20:23]
	v_mfma_f32_16x16x32_bf16 v[20:23], v[160:163], v[192:195], v[20:23]
	v_mfma_f32_16x16x32_bf16 v[16:19], v[168:171], v[192:195], v[16:19]
	v_mfma_f32_16x16x32_bf16 v[16:19], v[164:167], v[188:191], v[16:19]
	v_mfma_f32_16x16x32_bf16 v[0:3], v[164:167], v[196:199], v[0:3]
	v_mfma_f32_16x16x32_bf16 v[0:3], v[168:171], v[212:215], v[0:3]
	v_mfma_f32_16x16x32_bf16 v[4:7], v[160:163], v[212:215], v[4:7]
	v_mfma_f32_16x16x32_bf16 v[4:7], v[144:147], v[196:199], v[4:7]
	v_mfma_f32_16x16x32_bf16 v[8:11], v[136:139], v[196:199], v[8:11]
	v_mfma_f32_16x16x32_bf16 v[8:11], v[140:143], v[212:215], v[8:11]
	v_mfma_f32_16x16x32_bf16 v[12:15], v[132:135], v[212:215], v[12:15]
	v_mfma_f32_16x16x32_bf16 v[12:15], v[128:131], v[196:199], v[12:15]
	s_setprio 1
	s_barrier
	s_add_u32 s0, s0, 0x100
	s_addc_u32 s1, s1, 0
	s_add_u32 s38, s38, 0x100
	s_addc_u32 s39, s39, 0
	s_cmp_ge_i32 s41, s56
	s_mov_b32 s6, s41
	s_cbranch_scc0 .LBB0_1159
